# opt20: first two counted waits of a tile's first K iteration no longer wait for the previous epilogue's stores (vmcnt 8+E from the second tile on)
# speedup vs baseline: 1.0018x; 1.0018x over previous
.Lmy_nobar2_2:
	ds_read_b128 v[152:155], v157
	ds_read_b128 v[160:163], v157 offset:1024
	ds_read_b128 v[164:167], v157 offset:2048
	ds_read_b128 v[168:171], v157 offset:3072
	ds_read_b128 v[172:175], v158
	ds_read_b128 v[176:179], v158 offset:1024
	ds_read_b128 v[180:183], v158 offset:2048
	ds_read_b128 v[184:187], v158 offset:3072
	s_add_u32 s34, s50, 0xfffc0080
	s_addc_u32 s35, s51, -1
	s_cmp_eq_u32 s86, 12
	s_cselect_b32 s55, s7, s35
	s_cselect_b32 s54, s8, s34
	s_cselect_b32 s53, s12, s41
	s_cselect_b32 s52, s13, s29
	v_lshl_add_u64 v[220:221], s[50:51], 0, v[144:145]
	s_add_i32 m0, s63, 0xc000
	ds_read_b128 v[188:191], v159
	ds_read_b128 v[192:195], v159 offset:1024
	ds_read_b128 v[196:199], v159 offset:2048
	ds_read_b128 v[200:203], v159 offset:3072
	ds_read_b128 v[204:207], v159 offset:4096
	ds_read_b128 v[208:211], v159 offset:5120
	ds_read_b128 v[212:215], v159 offset:6144
	ds_read_b128 v[216:219], v159 offset:7168
	global_load_lds_dwordx4 v[220:221], off
	v_lshl_add_u64 v[220:221], s[50:51], 0, v[146:147]
	s_add_i32 m0, s63, 0xe000
	s_nop 0
	global_load_lds_dwordx4 v[220:221], off
	s_cmp_eq_u32 s84, 1
	s_cbranch_scc1 .Lmy_sw_2_0a
	s_waitcnt vmcnt(16)
	s_branch .Lmy_sw_2_0b

.Lmy_sw_2_0b:
	s_waitcnt lgkmcnt(0)
	s_barrier
	s_setprio 1
	s_waitcnt lgkmcnt(0)
	v_mfma_f32_16x16x32_bf16 v[124:127], v[152:155], v[188:191], 0
	v_mfma_f32_16x16x32_bf16 v[120:123], v[164:167], v[188:191], 0
	v_mfma_f32_16x16x32_bf16 v[108:111], v[152:155], v[196:199], 0
	v_mfma_f32_16x16x32_bf16 v[104:107], v[164:167], v[196:199], 0
	v_mfma_f32_16x16x32_bf16 v[92:95], v[152:155], v[204:207], 0
	v_mfma_f32_16x16x32_bf16 v[88:91], v[164:167], v[204:207], 0
	v_mfma_f32_16x16x32_bf16 v[76:79], v[152:155], v[212:215], 0
	v_mfma_f32_16x16x32_bf16 v[72:75], v[164:167], v[212:215], 0
	v_mfma_f32_16x16x32_bf16 v[124:127], v[160:163], v[192:195], v[124:127]
	v_mfma_f32_16x16x32_bf16 v[120:123], v[168:171], v[192:195], v[120:123]
	v_mfma_f32_16x16x32_bf16 v[108:111], v[160:163], v[200:203], v[108:111]
	v_mfma_f32_16x16x32_bf16 v[104:107], v[168:171], v[200:203], v[104:107]
	v_mfma_f32_16x16x32_bf16 v[92:95], v[160:163], v[208:211], v[92:95]
	v_mfma_f32_16x16x32_bf16 v[88:91], v[168:171], v[208:211], v[88:91]
	v_mfma_f32_16x16x32_bf16 v[76:79], v[160:163], v[216:219], v[76:79]
	v_mfma_f32_16x16x32_bf16 v[72:75], v[168:171], v[216:219], v[72:75]
	s_setprio 0
	s_setprio 1
	v_mfma_f32_16x16x32_bf16 v[116:119], v[172:175], v[188:191], 0
	v_mfma_f32_16x16x32_bf16 v[112:115], v[180:183], v[188:191], 0
	v_mfma_f32_16x16x32_bf16 v[100:103], v[172:175], v[196:199], 0
	v_mfma_f32_16x16x32_bf16 v[96:99], v[180:183], v[196:199], 0
	v_mfma_f32_16x16x32_bf16 v[84:87], v[172:175], v[204:207], 0
	v_mfma_f32_16x16x32_bf16 v[80:83], v[180:183], v[204:207], 0
	v_mfma_f32_16x16x32_bf16 v[68:71], v[172:175], v[212:215], 0
	v_mfma_f32_16x16x32_bf16 v[64:67], v[180:183], v[212:215], 0
	v_mfma_f32_16x16x32_bf16 v[116:119], v[176:179], v[192:195], v[116:119]
	v_mfma_f32_16x16x32_bf16 v[112:115], v[184:187], v[192:195], v[112:115]
	v_mfma_f32_16x16x32_bf16 v[100:103], v[176:179], v[200:203], v[100:103]
	v_mfma_f32_16x16x32_bf16 v[96:99], v[184:187], v[200:203], v[96:99]
	v_mfma_f32_16x16x32_bf16 v[84:87], v[176:179], v[208:211], v[84:87]
	v_mfma_f32_16x16x32_bf16 v[80:83], v[184:187], v[208:211], v[80:83]
	v_mfma_f32_16x16x32_bf16 v[68:71], v[176:179], v[216:219], v[68:71]
	v_mfma_f32_16x16x32_bf16 v[64:67], v[184:187], v[216:219], v[64:67]
	s_setprio 0
	s_barrier
	s_add_i32 s34, s82, s58
	v_lshl_add_u64 v[220:221], s[52:53], 0, v[136:137]
	s_mov_b32 m0, s34
	ds_read_b128 v[188:191], v159 offset:16384
	ds_read_b128 v[192:195], v159 offset:17408
	ds_read_b128 v[196:199], v159 offset:18432
	ds_read_b128 v[200:203], v159 offset:19456
	ds_read_b128 v[204:207], v159 offset:20480
	ds_read_b128 v[208:211], v159 offset:21504
	ds_read_b128 v[212:215], v159 offset:22528
	ds_read_b128 v[216:219], v159 offset:23552
	global_load_lds_dwordx4 v[220:221], off
	s_add_i32 m0, s34, 0x2000
	s_add_u32 s34, s52, 0x40000
	v_lshl_add_u64 v[222:223], s[52:53], 0, v[140:141]
	s_addc_u32 s35, s53, 0
	s_add_i32 s87, s83, s58
	global_load_lds_dwordx4 v[222:223], off
	v_lshl_add_u64 v[224:225], s[34:35], 0, v[136:137]
	s_mov_b32 m0, s87
	v_lshl_add_u64 v[226:227], s[54:55], 0, v[138:139]
	global_load_lds_dwordx4 v[224:225], off
	v_lshl_add_u64 v[224:225], s[34:35], 0, v[140:141]
	s_add_i32 m0, s87, 0x2000
	s_nop 0
	global_load_lds_dwordx4 v[224:225], off
	v_lshl_add_u64 v[224:225], s[54:55], 0, v[134:135]
	s_mov_b32 m0, s63
	s_nop 0
	global_load_lds_dwordx4 v[224:225], off
	s_mov_b32 m0, s64
	s_nop 0
	global_load_lds_dwordx4 v[226:227], off
	s_cmp_eq_u32 s84, 1
	s_cbranch_scc1 .Lmy_sw_2_1a
	s_waitcnt vmcnt(16)
	s_branch .Lmy_sw_2_1b

.Lmy_sw_2_1b:
	s_waitcnt lgkmcnt(0)
	s_barrier
	s_setprio 1
	s_waitcnt lgkmcnt(0)
	v_mfma_f32_16x16x32_bf16 v[60:63], v[152:155], v[188:191], 0
	v_mfma_f32_16x16x32_bf16 v[56:59], v[164:167], v[188:191], 0
	v_mfma_f32_16x16x32_bf16 v[44:47], v[152:155], v[196:199], 0
	v_mfma_f32_16x16x32_bf16 v[40:43], v[164:167], v[196:199], 0
	v_mfma_f32_16x16x32_bf16 v[28:31], v[152:155], v[204:207], 0
	v_mfma_f32_16x16x32_bf16 v[24:27], v[164:167], v[204:207], 0
	v_mfma_f32_16x16x32_bf16 v[12:15], v[152:155], v[212:215], 0
	v_mfma_f32_16x16x32_bf16 v[8:11], v[164:167], v[212:215], 0
	v_mfma_f32_16x16x32_bf16 v[60:63], v[160:163], v[192:195], v[60:63]
	v_mfma_f32_16x16x32_bf16 v[56:59], v[168:171], v[192:195], v[56:59]
	v_mfma_f32_16x16x32_bf16 v[44:47], v[160:163], v[200:203], v[44:47]
	v_mfma_f32_16x16x32_bf16 v[40:43], v[168:171], v[200:203], v[40:43]
	v_mfma_f32_16x16x32_bf16 v[28:31], v[160:163], v[208:211], v[28:31]
	v_mfma_f32_16x16x32_bf16 v[24:27], v[168:171], v[208:211], v[24:27]
	v_mfma_f32_16x16x32_bf16 v[12:15], v[160:163], v[216:219], v[12:15]
	v_mfma_f32_16x16x32_bf16 v[8:11], v[168:171], v[216:219], v[8:11]
	s_setprio 0
	s_setprio 1
	v_mfma_f32_16x16x32_bf16 v[52:55], v[172:175], v[188:191], 0
	v_mfma_f32_16x16x32_bf16 v[48:51], v[180:183], v[188:191], 0
	v_mfma_f32_16x16x32_bf16 v[36:39], v[172:175], v[196:199], 0
	v_mfma_f32_16x16x32_bf16 v[32:35], v[180:183], v[196:199], 0
	v_mfma_f32_16x16x32_bf16 v[20:23], v[172:175], v[204:207], 0
	v_mfma_f32_16x16x32_bf16 v[16:19], v[180:183], v[204:207], 0
	v_mfma_f32_16x16x32_bf16 v[4:7], v[172:175], v[212:215], 0
	v_mfma_f32_16x16x32_bf16 v[0:3], v[180:183], v[212:215], 0
	v_mfma_f32_16x16x32_bf16 v[52:55], v[176:179], v[192:195], v[52:55]
	v_mfma_f32_16x16x32_bf16 v[48:51], v[184:187], v[192:195], v[48:51]
	v_mfma_f32_16x16x32_bf16 v[36:39], v[176:179], v[200:203], v[36:39]
	v_mfma_f32_16x16x32_bf16 v[32:35], v[184:187], v[200:203], v[32:35]
	v_mfma_f32_16x16x32_bf16 v[20:23], v[176:179], v[208:211], v[20:23]
	v_mfma_f32_16x16x32_bf16 v[16:19], v[184:187], v[208:211], v[16:19]
	v_mfma_f32_16x16x32_bf16 v[4:7], v[176:179], v[216:219], v[4:7]
	v_mfma_f32_16x16x32_bf16 v[0:3], v[184:187], v[216:219], v[0:3]
	s_setprio 0
	s_barrier
	s_add_i32 s87, 0, 0x18000
	v_add_u32_e32 v142, s87, v133
	s_add_i32 s88, 0, 0x1c000
	ds_read_b128 v[152:155], v142
	ds_read_b128 v[160:163], v142 offset:1024
	ds_read_b128 v[164:167], v142 offset:2048
	ds_read_b128 v[168:171], v142 offset:3072
	v_add_u32_e32 v142, s88, v133
	ds_read_b128 v[172:175], v142
	ds_read_b128 v[176:179], v142 offset:1024
	ds_read_b128 v[180:183], v142 offset:2048
	ds_read_b128 v[184:187], v142 offset:3072
	s_add_u32 s34, s54, 0x40000
	s_addc_u32 s35, s55, 0
	s_mov_b32 m0, s65
	v_lshl_add_u64 v[228:229], s[34:35], 0, v[134:135]
	ds_read_b128 v[188:191], v159 offset:32768
	ds_read_b128 v[192:195], v159 offset:33792
	ds_read_b128 v[196:199], v159 offset:34816
	ds_read_b128 v[200:203], v159 offset:35840
	ds_read_b128 v[204:207], v159 offset:36864
	ds_read_b128 v[208:211], v159 offset:37888
	ds_read_b128 v[212:215], v159 offset:38912
	ds_read_b128 v[216:219], v159 offset:39936
	global_load_lds_dwordx4 v[228:229], off
	v_lshl_add_u64 v[228:229], s[34:35], 0, v[138:139]
	s_mov_b32 m0, s66
	s_nop 0
	global_load_lds_dwordx4 v[228:229], off
	s_waitcnt vmcnt(8)
	s_waitcnt lgkmcnt(0)
	s_barrier
	s_setprio 1
	s_waitcnt lgkmcnt(0)
	v_mfma_f32_16x16x32_bf16 v[124:127], v[152:155], v[188:191], v[124:127]
	v_mfma_f32_16x16x32_bf16 v[120:123], v[164:167], v[188:191], v[120:123]
	v_mfma_f32_16x16x32_bf16 v[108:111], v[152:155], v[196:199], v[108:111]
	v_mfma_f32_16x16x32_bf16 v[104:107], v[164:167], v[196:199], v[104:107]
	v_mfma_f32_16x16x32_bf16 v[92:95], v[152:155], v[204:207], v[92:95]
	v_mfma_f32_16x16x32_bf16 v[88:91], v[164:167], v[204:207], v[88:91]
	v_mfma_f32_16x16x32_bf16 v[76:79], v[152:155], v[212:215], v[76:79]
	v_mfma_f32_16x16x32_bf16 v[72:75], v[164:167], v[212:215], v[72:75]
	v_mfma_f32_16x16x32_bf16 v[124:127], v[160:163], v[192:195], v[124:127]
	v_mfma_f32_16x16x32_bf16 v[120:123], v[168:171], v[192:195], v[120:123]
	v_mfma_f32_16x16x32_bf16 v[108:111], v[160:163], v[200:203], v[108:111]
	v_mfma_f32_16x16x32_bf16 v[104:107], v[168:171], v[200:203], v[104:107]
	v_mfma_f32_16x16x32_bf16 v[92:95], v[160:163], v[208:211], v[92:95]
	v_mfma_f32_16x16x32_bf16 v[88:91], v[168:171], v[208:211], v[88:91]
	v_mfma_f32_16x16x32_bf16 v[76:79], v[160:163], v[216:219], v[76:79]
	v_mfma_f32_16x16x32_bf16 v[72:75], v[168:171], v[216:219], v[72:75]
	s_setprio 0
	s_setprio 1
	v_mfma_f32_16x16x32_bf16 v[116:119], v[172:175], v[188:191], v[116:119]
	v_mfma_f32_16x16x32_bf16 v[112:115], v[180:183], v[188:191], v[112:115]
	v_mfma_f32_16x16x32_bf16 v[100:103], v[172:175], v[196:199], v[100:103]
	v_mfma_f32_16x16x32_bf16 v[96:99], v[180:183], v[196:199], v[96:99]
	v_mfma_f32_16x16x32_bf16 v[84:87], v[172:175], v[204:207], v[84:87]
	v_mfma_f32_16x16x32_bf16 v[80:83], v[180:183], v[204:207], v[80:83]
	v_mfma_f32_16x16x32_bf16 v[68:71], v[172:175], v[212:215], v[68:71]
	v_mfma_f32_16x16x32_bf16 v[64:67], v[180:183], v[212:215], v[64:67]
	v_mfma_f32_16x16x32_bf16 v[116:119], v[176:179], v[192:195], v[116:119]
	v_mfma_f32_16x16x32_bf16 v[112:115], v[184:187], v[192:195], v[112:115]
	v_mfma_f32_16x16x32_bf16 v[100:103], v[176:179], v[200:203], v[100:103]
	v_mfma_f32_16x16x32_bf16 v[96:99], v[184:187], v[200:203], v[96:99]
	v_mfma_f32_16x16x32_bf16 v[84:87], v[176:179], v[208:211], v[84:87]
	v_mfma_f32_16x16x32_bf16 v[80:83], v[184:187], v[208:211], v[80:83]
	v_mfma_f32_16x16x32_bf16 v[68:71], v[176:179], v[216:219], v[68:71]
	v_mfma_f32_16x16x32_bf16 v[64:67], v[184:187], v[216:219], v[64:67]
	s_setprio 0
	s_barrier
	s_add_i32 s34, s87, s58
	v_lshl_add_u64 v[220:221], v[220:221], 0, s[22:23]
	s_mov_b32 m0, s34
	ds_read_b128 v[188:191], v159 offset:49152
	ds_read_b128 v[192:195], v159 offset:50176
	ds_read_b128 v[196:199], v159 offset:51200
	ds_read_b128 v[200:203], v159 offset:52224
	ds_read_b128 v[204:207], v159 offset:53248
	ds_read_b128 v[208:211], v159 offset:54272
	ds_read_b128 v[212:215], v159 offset:55296
	ds_read_b128 v[216:219], v159 offset:56320
	global_load_lds_dwordx4 v[220:221], off
	s_add_i32 m0, s34, 0x2000
	s_add_u32 s34, s52, 0x40080
	v_lshl_add_u64 v[220:221], v[222:223], 0, s[22:23]
	s_addc_u32 s35, s53, 0
	s_add_i32 s52, s88, s58
	global_load_lds_dwordx4 v[220:221], off
	v_lshl_add_u64 v[220:221], s[34:35], 0, v[136:137]
	s_mov_b32 m0, s52
	s_nop 0
	global_load_lds_dwordx4 v[220:221], off
	v_lshl_add_u64 v[220:221], s[34:35], 0, v[140:141]
	s_add_i32 m0, s52, 0x2000
	s_nop 0
	global_load_lds_dwordx4 v[220:221], off
	v_lshl_add_u64 v[220:221], v[224:225], 0, s[22:23]
	s_mov_b32 m0, s79
	s_nop 0
	global_load_lds_dwordx4 v[220:221], off
	v_lshl_add_u64 v[220:221], v[226:227], 0, s[22:23]
	s_mov_b32 m0, s81
	s_nop 0
	global_load_lds_dwordx4 v[220:221], off
	s_waitcnt vmcnt(8)
	s_waitcnt lgkmcnt(0)
	s_barrier
	s_setprio 1
	s_waitcnt lgkmcnt(0)
	v_mfma_f32_16x16x32_bf16 v[60:63], v[152:155], v[188:191], v[60:63]
	v_mfma_f32_16x16x32_bf16 v[56:59], v[164:167], v[188:191], v[56:59]
	v_mfma_f32_16x16x32_bf16 v[44:47], v[152:155], v[196:199], v[44:47]
	v_mfma_f32_16x16x32_bf16 v[40:43], v[164:167], v[196:199], v[40:43]
	v_mfma_f32_16x16x32_bf16 v[28:31], v[152:155], v[204:207], v[28:31]
	v_mfma_f32_16x16x32_bf16 v[24:27], v[164:167], v[204:207], v[24:27]
	v_mfma_f32_16x16x32_bf16 v[12:15], v[152:155], v[212:215], v[12:15]
	v_mfma_f32_16x16x32_bf16 v[8:11], v[164:167], v[212:215], v[8:11]
	v_mfma_f32_16x16x32_bf16 v[60:63], v[160:163], v[192:195], v[60:63]
	v_mfma_f32_16x16x32_bf16 v[56:59], v[168:171], v[192:195], v[56:59]
	v_mfma_f32_16x16x32_bf16 v[44:47], v[160:163], v[200:203], v[44:47]
	v_mfma_f32_16x16x32_bf16 v[40:43], v[168:171], v[200:203], v[40:43]
	v_mfma_f32_16x16x32_bf16 v[28:31], v[160:163], v[208:211], v[28:31]
	v_mfma_f32_16x16x32_bf16 v[24:27], v[168:171], v[208:211], v[24:27]
	v_mfma_f32_16x16x32_bf16 v[12:15], v[160:163], v[216:219], v[12:15]
	v_mfma_f32_16x16x32_bf16 v[8:11], v[168:171], v[216:219], v[8:11]
	s_setprio 0
	s_setprio 1
	v_mfma_f32_16x16x32_bf16 v[52:55], v[172:175], v[188:191], v[52:55]
	v_mfma_f32_16x16x32_bf16 v[48:51], v[180:183], v[188:191], v[48:51]
	v_mfma_f32_16x16x32_bf16 v[36:39], v[172:175], v[196:199], v[36:39]
	v_mfma_f32_16x16x32_bf16 v[32:35], v[180:183], v[196:199], v[32:35]
	v_mfma_f32_16x16x32_bf16 v[20:23], v[172:175], v[204:207], v[20:23]
	v_mfma_f32_16x16x32_bf16 v[16:19], v[180:183], v[204:207], v[16:19]
	v_mfma_f32_16x16x32_bf16 v[4:7], v[172:175], v[212:215], v[4:7]
	v_mfma_f32_16x16x32_bf16 v[0:3], v[180:183], v[212:215], v[0:3]
	v_mfma_f32_16x16x32_bf16 v[52:55], v[176:179], v[192:195], v[52:55]
	v_mfma_f32_16x16x32_bf16 v[48:51], v[184:187], v[192:195], v[48:51]
	v_mfma_f32_16x16x32_bf16 v[36:39], v[176:179], v[200:203], v[36:39]
	v_mfma_f32_16x16x32_bf16 v[32:35], v[184:187], v[200:203], v[32:35]
	v_mfma_f32_16x16x32_bf16 v[20:23], v[176:179], v[208:211], v[20:23]
	v_mfma_f32_16x16x32_bf16 v[16:19], v[184:187], v[208:211], v[16:19]
	v_mfma_f32_16x16x32_bf16 v[4:7], v[176:179], v[216:219], v[4:7]
	v_mfma_f32_16x16x32_bf16 v[0:3], v[184:187], v[216:219], v[0:3]
	s_setprio 0
	s_barrier
	s_add_i32 s86, s86, 2
	s_add_u32 s50, s50, 0x100
	s_addc_u32 s51, s51, 0
	s_add_u32 s29, s29, 0x100
	s_addc_u32 s41, s41, 0

.Lmy_nobar2_4:
	ds_read_b128 v[148:151], v154
	ds_read_b128 v[160:163], v154 offset:1024
	ds_read_b128 v[164:167], v154 offset:2048
	ds_read_b128 v[168:171], v154 offset:3072
	ds_read_b128 v[172:175], v155
	ds_read_b128 v[176:179], v155 offset:1024
	ds_read_b128 v[180:183], v155 offset:2048
	ds_read_b128 v[184:187], v155 offset:3072
	s_add_u32 s34, s50, 0xfffc0080
	s_addc_u32 s35, s51, -1
	s_cmp_eq_u32 s85, 12
	s_cselect_b32 s55, s12, s35
	s_cselect_b32 s54, s13, s34
	s_cselect_b32 s53, s27, s77
	s_cselect_b32 s52, s29, s49
	v_lshl_add_u64 v[220:221], s[50:51], 0, v[140:141]
	s_add_i32 m0, s58, 0xc000
	ds_read_b128 v[188:191], v157
	ds_read_b128 v[192:195], v157 offset:1024
	ds_read_b128 v[196:199], v157 offset:2048
	ds_read_b128 v[200:203], v157 offset:3072
	ds_read_b128 v[204:207], v157 offset:4096
	ds_read_b128 v[208:211], v157 offset:5120
	ds_read_b128 v[212:215], v157 offset:6144
	ds_read_b128 v[216:219], v157 offset:7168
	global_load_lds_dwordx4 v[220:221], off
	v_lshl_add_u64 v[220:221], s[50:51], 0, v[142:143]
	s_add_i32 m0, s58, 0xe000
	s_nop 0
	global_load_lds_dwordx4 v[220:221], off
	s_cmp_eq_u32 s84, 1
	s_cbranch_scc1 .Lmy_sw_4_0a
	s_waitcnt vmcnt(40)
	s_branch .Lmy_sw_4_0b

.Lmy_sw_4_0b:
	s_waitcnt lgkmcnt(0)
	s_barrier
	s_setprio 1
	s_waitcnt lgkmcnt(0)
	v_mfma_f32_16x16x32_bf16 v[124:127], v[148:151], v[188:191], 0
	v_mfma_f32_16x16x32_bf16 v[120:123], v[164:167], v[188:191], 0
	v_mfma_f32_16x16x32_bf16 v[108:111], v[148:151], v[196:199], 0
	v_mfma_f32_16x16x32_bf16 v[104:107], v[164:167], v[196:199], 0
	v_mfma_f32_16x16x32_bf16 v[92:95], v[148:151], v[204:207], 0
	v_mfma_f32_16x16x32_bf16 v[88:91], v[164:167], v[204:207], 0
	v_mfma_f32_16x16x32_bf16 v[76:79], v[148:151], v[212:215], 0
	v_mfma_f32_16x16x32_bf16 v[72:75], v[164:167], v[212:215], 0
	v_mfma_f32_16x16x32_bf16 v[124:127], v[160:163], v[192:195], v[124:127]
	v_mfma_f32_16x16x32_bf16 v[120:123], v[168:171], v[192:195], v[120:123]
	v_mfma_f32_16x16x32_bf16 v[108:111], v[160:163], v[200:203], v[108:111]
	v_mfma_f32_16x16x32_bf16 v[104:107], v[168:171], v[200:203], v[104:107]
	v_mfma_f32_16x16x32_bf16 v[92:95], v[160:163], v[208:211], v[92:95]
	v_mfma_f32_16x16x32_bf16 v[88:91], v[168:171], v[208:211], v[88:91]
	v_mfma_f32_16x16x32_bf16 v[76:79], v[160:163], v[216:219], v[76:79]
	v_mfma_f32_16x16x32_bf16 v[72:75], v[168:171], v[216:219], v[72:75]
	s_setprio 0
	s_setprio 1
	v_mfma_f32_16x16x32_bf16 v[116:119], v[172:175], v[188:191], 0
	v_mfma_f32_16x16x32_bf16 v[112:115], v[180:183], v[188:191], 0
	v_mfma_f32_16x16x32_bf16 v[100:103], v[172:175], v[196:199], 0
	v_mfma_f32_16x16x32_bf16 v[96:99], v[180:183], v[196:199], 0
	v_mfma_f32_16x16x32_bf16 v[84:87], v[172:175], v[204:207], 0
	v_mfma_f32_16x16x32_bf16 v[80:83], v[180:183], v[204:207], 0
	v_mfma_f32_16x16x32_bf16 v[68:71], v[172:175], v[212:215], 0
	v_mfma_f32_16x16x32_bf16 v[64:67], v[180:183], v[212:215], 0
	v_mfma_f32_16x16x32_bf16 v[116:119], v[176:179], v[192:195], v[116:119]
	v_mfma_f32_16x16x32_bf16 v[112:115], v[184:187], v[192:195], v[112:115]
	v_mfma_f32_16x16x32_bf16 v[100:103], v[176:179], v[200:203], v[100:103]
	v_mfma_f32_16x16x32_bf16 v[96:99], v[184:187], v[200:203], v[96:99]
	v_mfma_f32_16x16x32_bf16 v[84:87], v[176:179], v[208:211], v[84:87]
	v_mfma_f32_16x16x32_bf16 v[80:83], v[184:187], v[208:211], v[80:83]
	v_mfma_f32_16x16x32_bf16 v[68:71], v[176:179], v[216:219], v[68:71]
	v_mfma_f32_16x16x32_bf16 v[64:67], v[184:187], v[216:219], v[64:67]
	s_setprio 0
	s_barrier
	s_add_i32 s34, s82, s57
	v_lshl_add_u64 v[220:221], s[52:53], 0, v[134:135]
	s_mov_b32 m0, s34
	ds_read_b128 v[188:191], v157 offset:16384
	ds_read_b128 v[192:195], v157 offset:17408
	ds_read_b128 v[196:199], v157 offset:18432
	ds_read_b128 v[200:203], v157 offset:19456
	ds_read_b128 v[204:207], v157 offset:20480
	ds_read_b128 v[208:211], v157 offset:21504
	ds_read_b128 v[212:215], v157 offset:22528
	ds_read_b128 v[216:219], v157 offset:23552
	global_load_lds_dwordx4 v[220:221], off
	s_add_i32 m0, s34, 0x2000
	s_add_u32 s34, s52, 0x40000
	v_lshl_add_u64 v[222:223], s[52:53], 0, v[138:139]
	s_addc_u32 s35, s53, 0
	s_add_i32 s86, s83, s57
	global_load_lds_dwordx4 v[222:223], off
	v_lshl_add_u64 v[224:225], s[34:35], 0, v[134:135]
	s_mov_b32 m0, s86
	v_lshl_add_u64 v[226:227], s[54:55], 0, v[136:137]
	global_load_lds_dwordx4 v[224:225], off
	v_lshl_add_u64 v[224:225], s[34:35], 0, v[138:139]
	s_add_i32 m0, s86, 0x2000
	s_nop 0
	global_load_lds_dwordx4 v[224:225], off
	v_lshl_add_u64 v[224:225], s[54:55], 0, v[132:133]
	s_mov_b32 m0, s58
	s_nop 0
	global_load_lds_dwordx4 v[224:225], off
	s_mov_b32 m0, s59
	s_nop 0
	global_load_lds_dwordx4 v[226:227], off
	s_cmp_eq_u32 s84, 1
	s_cbranch_scc1 .Lmy_sw_4_1a
	s_waitcnt vmcnt(40)
	s_branch .Lmy_sw_4_1b

.Lmy_sw_4_1b:
	s_waitcnt lgkmcnt(0)
	s_barrier
	s_setprio 1
	s_waitcnt lgkmcnt(0)
	v_mfma_f32_16x16x32_bf16 v[60:63], v[148:151], v[188:191], 0
	v_mfma_f32_16x16x32_bf16 v[56:59], v[164:167], v[188:191], 0
	v_mfma_f32_16x16x32_bf16 v[44:47], v[148:151], v[196:199], 0
	v_mfma_f32_16x16x32_bf16 v[40:43], v[164:167], v[196:199], 0
	v_mfma_f32_16x16x32_bf16 v[28:31], v[148:151], v[204:207], 0
	v_mfma_f32_16x16x32_bf16 v[24:27], v[164:167], v[204:207], 0
	v_mfma_f32_16x16x32_bf16 v[12:15], v[148:151], v[212:215], 0
	v_mfma_f32_16x16x32_bf16 v[8:11], v[164:167], v[212:215], 0
	v_mfma_f32_16x16x32_bf16 v[60:63], v[160:163], v[192:195], v[60:63]
	v_mfma_f32_16x16x32_bf16 v[56:59], v[168:171], v[192:195], v[56:59]
	v_mfma_f32_16x16x32_bf16 v[44:47], v[160:163], v[200:203], v[44:47]
	v_mfma_f32_16x16x32_bf16 v[40:43], v[168:171], v[200:203], v[40:43]
	v_mfma_f32_16x16x32_bf16 v[28:31], v[160:163], v[208:211], v[28:31]
	v_mfma_f32_16x16x32_bf16 v[24:27], v[168:171], v[208:211], v[24:27]
	v_mfma_f32_16x16x32_bf16 v[12:15], v[160:163], v[216:219], v[12:15]
	v_mfma_f32_16x16x32_bf16 v[8:11], v[168:171], v[216:219], v[8:11]
	s_setprio 0
	s_setprio 1
	v_mfma_f32_16x16x32_bf16 v[52:55], v[172:175], v[188:191], 0
	v_mfma_f32_16x16x32_bf16 v[48:51], v[180:183], v[188:191], 0
	v_mfma_f32_16x16x32_bf16 v[36:39], v[172:175], v[196:199], 0
	v_mfma_f32_16x16x32_bf16 v[32:35], v[180:183], v[196:199], 0
	v_mfma_f32_16x16x32_bf16 v[20:23], v[172:175], v[204:207], 0
	v_mfma_f32_16x16x32_bf16 v[16:19], v[180:183], v[204:207], 0
	v_mfma_f32_16x16x32_bf16 v[4:7], v[172:175], v[212:215], 0
	v_mfma_f32_16x16x32_bf16 v[0:3], v[180:183], v[212:215], 0
	v_mfma_f32_16x16x32_bf16 v[52:55], v[176:179], v[192:195], v[52:55]
	v_mfma_f32_16x16x32_bf16 v[48:51], v[184:187], v[192:195], v[48:51]
	v_mfma_f32_16x16x32_bf16 v[36:39], v[176:179], v[200:203], v[36:39]
	v_mfma_f32_16x16x32_bf16 v[32:35], v[184:187], v[200:203], v[32:35]
	v_mfma_f32_16x16x32_bf16 v[20:23], v[176:179], v[208:211], v[20:23]
	v_mfma_f32_16x16x32_bf16 v[16:19], v[184:187], v[208:211], v[16:19]
	v_mfma_f32_16x16x32_bf16 v[4:7], v[176:179], v[216:219], v[4:7]
	v_mfma_f32_16x16x32_bf16 v[0:3], v[184:187], v[216:219], v[0:3]
	s_setprio 0
	s_barrier
	s_add_i32 s86, 0, 0x18000
	v_add_u32_e32 v159, s86, v152
	s_add_i32 s87, 0, 0x1c000
	ds_read_b128 v[148:151], v159
	ds_read_b128 v[160:163], v159 offset:1024
	ds_read_b128 v[164:167], v159 offset:2048
	ds_read_b128 v[168:171], v159 offset:3072
	v_add_u32_e32 v159, s87, v152
	ds_read_b128 v[172:175], v159
	ds_read_b128 v[176:179], v159 offset:1024
	ds_read_b128 v[180:183], v159 offset:2048
	ds_read_b128 v[184:187], v159 offset:3072
	s_add_u32 s34, s54, 0x40000
	s_addc_u32 s35, s55, 0
	s_mov_b32 m0, s62
	v_lshl_add_u64 v[228:229], s[34:35], 0, v[132:133]
	ds_read_b128 v[188:191], v157 offset:32768
	ds_read_b128 v[192:195], v157 offset:33792
	ds_read_b128 v[196:199], v157 offset:34816
	ds_read_b128 v[200:203], v157 offset:35840
	ds_read_b128 v[204:207], v157 offset:36864
	ds_read_b128 v[208:211], v157 offset:37888
	ds_read_b128 v[212:215], v157 offset:38912
	ds_read_b128 v[216:219], v157 offset:39936
	global_load_lds_dwordx4 v[228:229], off
	v_lshl_add_u64 v[228:229], s[34:35], 0, v[136:137]
	s_mov_b32 m0, s63
	s_nop 0
	global_load_lds_dwordx4 v[228:229], off
	s_waitcnt vmcnt(8)
	s_waitcnt lgkmcnt(0)
	s_barrier
	s_setprio 1
	s_waitcnt lgkmcnt(0)
	v_mfma_f32_16x16x32_bf16 v[124:127], v[148:151], v[188:191], v[124:127]
	v_mfma_f32_16x16x32_bf16 v[120:123], v[164:167], v[188:191], v[120:123]
	v_mfma_f32_16x16x32_bf16 v[108:111], v[148:151], v[196:199], v[108:111]
	v_mfma_f32_16x16x32_bf16 v[104:107], v[164:167], v[196:199], v[104:107]
	v_mfma_f32_16x16x32_bf16 v[92:95], v[148:151], v[204:207], v[92:95]
	v_mfma_f32_16x16x32_bf16 v[88:91], v[164:167], v[204:207], v[88:91]
	v_mfma_f32_16x16x32_bf16 v[76:79], v[148:151], v[212:215], v[76:79]
	v_mfma_f32_16x16x32_bf16 v[72:75], v[164:167], v[212:215], v[72:75]
	v_mfma_f32_16x16x32_bf16 v[124:127], v[160:163], v[192:195], v[124:127]
	v_mfma_f32_16x16x32_bf16 v[120:123], v[168:171], v[192:195], v[120:123]
	v_mfma_f32_16x16x32_bf16 v[108:111], v[160:163], v[200:203], v[108:111]
	v_mfma_f32_16x16x32_bf16 v[104:107], v[168:171], v[200:203], v[104:107]
	v_mfma_f32_16x16x32_bf16 v[92:95], v[160:163], v[208:211], v[92:95]
	v_mfma_f32_16x16x32_bf16 v[88:91], v[168:171], v[208:211], v[88:91]
	v_mfma_f32_16x16x32_bf16 v[76:79], v[160:163], v[216:219], v[76:79]
	v_mfma_f32_16x16x32_bf16 v[72:75], v[168:171], v[216:219], v[72:75]
	s_setprio 0
	s_setprio 1
	v_mfma_f32_16x16x32_bf16 v[116:119], v[172:175], v[188:191], v[116:119]
	v_mfma_f32_16x16x32_bf16 v[112:115], v[180:183], v[188:191], v[112:115]
	v_mfma_f32_16x16x32_bf16 v[100:103], v[172:175], v[196:199], v[100:103]
	v_mfma_f32_16x16x32_bf16 v[96:99], v[180:183], v[196:199], v[96:99]
	v_mfma_f32_16x16x32_bf16 v[84:87], v[172:175], v[204:207], v[84:87]
	v_mfma_f32_16x16x32_bf16 v[80:83], v[180:183], v[204:207], v[80:83]
	v_mfma_f32_16x16x32_bf16 v[68:71], v[172:175], v[212:215], v[68:71]
	v_mfma_f32_16x16x32_bf16 v[64:67], v[180:183], v[212:215], v[64:67]
	v_mfma_f32_16x16x32_bf16 v[116:119], v[176:179], v[192:195], v[116:119]
	v_mfma_f32_16x16x32_bf16 v[112:115], v[184:187], v[192:195], v[112:115]
	v_mfma_f32_16x16x32_bf16 v[100:103], v[176:179], v[200:203], v[100:103]
	v_mfma_f32_16x16x32_bf16 v[96:99], v[184:187], v[200:203], v[96:99]
	v_mfma_f32_16x16x32_bf16 v[84:87], v[176:179], v[208:211], v[84:87]
	v_mfma_f32_16x16x32_bf16 v[80:83], v[184:187], v[208:211], v[80:83]
	v_mfma_f32_16x16x32_bf16 v[68:71], v[176:179], v[216:219], v[68:71]
	v_mfma_f32_16x16x32_bf16 v[64:67], v[184:187], v[216:219], v[64:67]
	s_setprio 0
	s_barrier
	s_add_i32 s34, s86, s57
	v_lshl_add_u64 v[220:221], v[220:221], 0, s[10:11]
	s_mov_b32 m0, s34
	ds_read_b128 v[188:191], v157 offset:49152
	ds_read_b128 v[192:195], v157 offset:50176
	ds_read_b128 v[196:199], v157 offset:51200
	ds_read_b128 v[200:203], v157 offset:52224
	ds_read_b128 v[204:207], v157 offset:53248
	ds_read_b128 v[208:211], v157 offset:54272
	ds_read_b128 v[212:215], v157 offset:55296
	ds_read_b128 v[216:219], v157 offset:56320
	global_load_lds_dwordx4 v[220:221], off
	s_add_i32 m0, s34, 0x2000
	s_add_u32 s34, s52, 0x40080
	v_lshl_add_u64 v[220:221], v[222:223], 0, s[10:11]
	s_addc_u32 s35, s53, 0
	s_add_i32 s52, s87, s57
	global_load_lds_dwordx4 v[220:221], off
	v_lshl_add_u64 v[220:221], s[34:35], 0, v[134:135]
	s_mov_b32 m0, s52
	s_nop 0
	global_load_lds_dwordx4 v[220:221], off
	v_lshl_add_u64 v[220:221], s[34:35], 0, v[138:139]
	s_add_i32 m0, s52, 0x2000
	s_nop 0
	global_load_lds_dwordx4 v[220:221], off
	v_lshl_add_u64 v[220:221], v[224:225], 0, s[10:11]
	s_mov_b32 m0, s65
	s_nop 0
	global_load_lds_dwordx4 v[220:221], off
	v_lshl_add_u64 v[220:221], v[226:227], 0, s[10:11]
	s_mov_b32 m0, s66
	s_nop 0
	global_load_lds_dwordx4 v[220:221], off
	s_waitcnt vmcnt(8)
	s_waitcnt lgkmcnt(0)
	s_barrier
	s_setprio 1
	s_waitcnt lgkmcnt(0)
	v_mfma_f32_16x16x32_bf16 v[60:63], v[148:151], v[188:191], v[60:63]
	v_mfma_f32_16x16x32_bf16 v[56:59], v[164:167], v[188:191], v[56:59]
	v_mfma_f32_16x16x32_bf16 v[44:47], v[148:151], v[196:199], v[44:47]
	v_mfma_f32_16x16x32_bf16 v[40:43], v[164:167], v[196:199], v[40:43]
	v_mfma_f32_16x16x32_bf16 v[28:31], v[148:151], v[204:207], v[28:31]
	v_mfma_f32_16x16x32_bf16 v[24:27], v[164:167], v[204:207], v[24:27]
	v_mfma_f32_16x16x32_bf16 v[12:15], v[148:151], v[212:215], v[12:15]
	v_mfma_f32_16x16x32_bf16 v[8:11], v[164:167], v[212:215], v[8:11]
	v_mfma_f32_16x16x32_bf16 v[60:63], v[160:163], v[192:195], v[60:63]
	v_mfma_f32_16x16x32_bf16 v[56:59], v[168:171], v[192:195], v[56:59]
	v_mfma_f32_16x16x32_bf16 v[44:47], v[160:163], v[200:203], v[44:47]
	v_mfma_f32_16x16x32_bf16 v[40:43], v[168:171], v[200:203], v[40:43]
	v_mfma_f32_16x16x32_bf16 v[28:31], v[160:163], v[208:211], v[28:31]
	v_mfma_f32_16x16x32_bf16 v[24:27], v[168:171], v[208:211], v[24:27]
	v_mfma_f32_16x16x32_bf16 v[12:15], v[160:163], v[216:219], v[12:15]
	v_mfma_f32_16x16x32_bf16 v[8:11], v[168:171], v[216:219], v[8:11]
	s_setprio 0
	s_setprio 1
	v_mfma_f32_16x16x32_bf16 v[52:55], v[172:175], v[188:191], v[52:55]
	v_mfma_f32_16x16x32_bf16 v[48:51], v[180:183], v[188:191], v[48:51]
	v_mfma_f32_16x16x32_bf16 v[36:39], v[172:175], v[196:199], v[36:39]
	v_mfma_f32_16x16x32_bf16 v[32:35], v[180:183], v[196:199], v[32:35]
	v_mfma_f32_16x16x32_bf16 v[20:23], v[172:175], v[204:207], v[20:23]
	v_mfma_f32_16x16x32_bf16 v[16:19], v[180:183], v[204:207], v[16:19]
	v_mfma_f32_16x16x32_bf16 v[4:7], v[172:175], v[212:215], v[4:7]
	v_mfma_f32_16x16x32_bf16 v[0:3], v[180:183], v[212:215], v[0:3]
	v_mfma_f32_16x16x32_bf16 v[52:55], v[176:179], v[192:195], v[52:55]
	v_mfma_f32_16x16x32_bf16 v[48:51], v[184:187], v[192:195], v[48:51]
	v_mfma_f32_16x16x32_bf16 v[36:39], v[176:179], v[200:203], v[36:39]
	v_mfma_f32_16x16x32_bf16 v[32:35], v[184:187], v[200:203], v[32:35]
	v_mfma_f32_16x16x32_bf16 v[20:23], v[176:179], v[208:211], v[20:23]
	v_mfma_f32_16x16x32_bf16 v[16:19], v[184:187], v[208:211], v[16:19]
	v_mfma_f32_16x16x32_bf16 v[4:7], v[176:179], v[216:219], v[4:7]
	v_mfma_f32_16x16x32_bf16 v[0:3], v[184:187], v[216:219], v[0:3]
	s_setprio 0
	s_barrier
	s_add_i32 s85, s85, 2
	s_add_u32 s50, s50, 0x100
	s_addc_u32 s51, s51, 0
	s_add_u32 s49, s49, 0x100
	s_addc_u32 s77, s77, 0

.Lmy_nobar2_5:
	ds_read_b128 v[148:151], v155
	ds_read_b128 v[160:163], v155 offset:1024
	ds_read_b128 v[164:167], v155 offset:2048
	ds_read_b128 v[168:171], v155 offset:3072
	ds_read_b128 v[172:175], v157
	ds_read_b128 v[176:179], v157 offset:1024
	ds_read_b128 v[180:183], v157 offset:2048
	ds_read_b128 v[184:187], v157 offset:3072
	s_add_u32 s34, s42, 0xfffc0080
	s_addc_u32 s35, s43, -1
	s_cmp_eq_u32 s85, 12
	s_cselect_b32 s51, s23, s35
	s_cselect_b32 s50, s81, s34
	s_cselect_b32 s49, s11, s84
	s_cselect_b32 s48, s82, s83
	v_lshl_add_u64 v[220:221], s[42:43], 0, v[140:141]
	s_add_i32 m0, s41, 0xc000
	ds_read_b128 v[188:191], v158
	ds_read_b128 v[192:195], v158 offset:1024
	ds_read_b128 v[196:199], v158 offset:2048
	ds_read_b128 v[200:203], v158 offset:3072
	ds_read_b128 v[204:207], v158 offset:4096
	ds_read_b128 v[208:211], v158 offset:5120
	ds_read_b128 v[212:215], v158 offset:6144
	ds_read_b128 v[216:219], v158 offset:7168
	global_load_lds_dwordx4 v[220:221], off
	v_lshl_add_u64 v[220:221], s[42:43], 0, v[142:143]
	s_add_i32 m0, s41, 0xe000
	s_nop 0
	global_load_lds_dwordx4 v[220:221], off
	s_cmp_eq_u32 s77, 1
	s_cbranch_scc1 .Lmy_sw_5_0a
	s_waitcnt vmcnt(16)
	s_branch .Lmy_sw_5_0b

.Lmy_sw_5_0b:
	s_waitcnt lgkmcnt(0)
	s_barrier
	s_setprio 1
	s_waitcnt lgkmcnt(0)
	v_mfma_f32_16x16x32_bf16 v[124:127], v[148:151], v[188:191], 0
	v_mfma_f32_16x16x32_bf16 v[120:123], v[164:167], v[188:191], 0
	v_mfma_f32_16x16x32_bf16 v[108:111], v[148:151], v[196:199], 0
	v_mfma_f32_16x16x32_bf16 v[104:107], v[164:167], v[196:199], 0
	v_mfma_f32_16x16x32_bf16 v[92:95], v[148:151], v[204:207], 0
	v_mfma_f32_16x16x32_bf16 v[88:91], v[164:167], v[204:207], 0
	v_mfma_f32_16x16x32_bf16 v[76:79], v[148:151], v[212:215], 0
	v_mfma_f32_16x16x32_bf16 v[72:75], v[164:167], v[212:215], 0
	v_mfma_f32_16x16x32_bf16 v[124:127], v[160:163], v[192:195], v[124:127]
	v_mfma_f32_16x16x32_bf16 v[120:123], v[168:171], v[192:195], v[120:123]
	v_mfma_f32_16x16x32_bf16 v[108:111], v[160:163], v[200:203], v[108:111]
	v_mfma_f32_16x16x32_bf16 v[104:107], v[168:171], v[200:203], v[104:107]
	v_mfma_f32_16x16x32_bf16 v[92:95], v[160:163], v[208:211], v[92:95]
	v_mfma_f32_16x16x32_bf16 v[88:91], v[168:171], v[208:211], v[88:91]
	v_mfma_f32_16x16x32_bf16 v[76:79], v[160:163], v[216:219], v[76:79]
	v_mfma_f32_16x16x32_bf16 v[72:75], v[168:171], v[216:219], v[72:75]
	s_setprio 0
	s_setprio 1
	v_mfma_f32_16x16x32_bf16 v[116:119], v[172:175], v[188:191], 0
	v_mfma_f32_16x16x32_bf16 v[112:115], v[180:183], v[188:191], 0
	v_mfma_f32_16x16x32_bf16 v[100:103], v[172:175], v[196:199], 0
	v_mfma_f32_16x16x32_bf16 v[96:99], v[180:183], v[196:199], 0
	v_mfma_f32_16x16x32_bf16 v[84:87], v[172:175], v[204:207], 0
	v_mfma_f32_16x16x32_bf16 v[80:83], v[180:183], v[204:207], 0
	v_mfma_f32_16x16x32_bf16 v[68:71], v[172:175], v[212:215], 0
	v_mfma_f32_16x16x32_bf16 v[64:67], v[180:183], v[212:215], 0
	v_mfma_f32_16x16x32_bf16 v[116:119], v[176:179], v[192:195], v[116:119]
	v_mfma_f32_16x16x32_bf16 v[112:115], v[184:187], v[192:195], v[112:115]
	v_mfma_f32_16x16x32_bf16 v[100:103], v[176:179], v[200:203], v[100:103]
	v_mfma_f32_16x16x32_bf16 v[96:99], v[184:187], v[200:203], v[96:99]
	v_mfma_f32_16x16x32_bf16 v[84:87], v[176:179], v[208:211], v[84:87]
	v_mfma_f32_16x16x32_bf16 v[80:83], v[184:187], v[208:211], v[80:83]
	v_mfma_f32_16x16x32_bf16 v[68:71], v[176:179], v[216:219], v[68:71]
	v_mfma_f32_16x16x32_bf16 v[64:67], v[184:187], v[216:219], v[64:67]
	s_setprio 0
	s_barrier
	s_add_i32 s34, s65, s54
	v_lshl_add_u64 v[220:221], s[48:49], 0, v[136:137]
	s_mov_b32 m0, s34
	ds_read_b128 v[188:191], v158 offset:16384
	ds_read_b128 v[192:195], v158 offset:17408
	ds_read_b128 v[196:199], v158 offset:18432
	ds_read_b128 v[200:203], v158 offset:19456
	ds_read_b128 v[204:207], v158 offset:20480
	ds_read_b128 v[208:211], v158 offset:21504
	ds_read_b128 v[212:215], v158 offset:22528
	ds_read_b128 v[216:219], v158 offset:23552
	global_load_lds_dwordx4 v[220:221], off
	s_add_i32 m0, s34, 0x2000
	s_add_u32 s34, s48, 0x40000
	v_lshl_add_u64 v[222:223], s[48:49], 0, v[132:133]
	s_addc_u32 s35, s49, 0
	s_add_i32 s86, s66, s54
	global_load_lds_dwordx4 v[222:223], off
	v_lshl_add_u64 v[224:225], s[34:35], 0, v[136:137]
	s_mov_b32 m0, s86
	v_lshl_add_u64 v[226:227], s[50:51], 0, v[134:135]
	global_load_lds_dwordx4 v[224:225], off
	v_lshl_add_u64 v[224:225], s[34:35], 0, v[132:133]
	s_add_i32 m0, s86, 0x2000
	s_nop 0
	global_load_lds_dwordx4 v[224:225], off
	v_lshl_add_u64 v[224:225], s[50:51], 0, v[138:139]
	s_mov_b32 m0, s41
	s_nop 0
	global_load_lds_dwordx4 v[224:225], off
	s_mov_b32 m0, s58
	s_nop 0
	global_load_lds_dwordx4 v[226:227], off
	s_cmp_eq_u32 s77, 1
	s_cbranch_scc1 .Lmy_sw_5_1a
	s_waitcnt vmcnt(16)
	s_branch .Lmy_sw_5_1b

.Lmy_sw_5_1b:
	s_waitcnt lgkmcnt(0)
	s_barrier
	s_setprio 1
	s_waitcnt lgkmcnt(0)
	v_mfma_f32_16x16x32_bf16 v[60:63], v[148:151], v[188:191], 0
	v_mfma_f32_16x16x32_bf16 v[56:59], v[164:167], v[188:191], 0
	v_mfma_f32_16x16x32_bf16 v[44:47], v[148:151], v[196:199], 0
	v_mfma_f32_16x16x32_bf16 v[40:43], v[164:167], v[196:199], 0
	v_mfma_f32_16x16x32_bf16 v[28:31], v[148:151], v[204:207], 0
	v_mfma_f32_16x16x32_bf16 v[24:27], v[164:167], v[204:207], 0
	v_mfma_f32_16x16x32_bf16 v[12:15], v[148:151], v[212:215], 0
	v_mfma_f32_16x16x32_bf16 v[8:11], v[164:167], v[212:215], 0
	v_mfma_f32_16x16x32_bf16 v[60:63], v[160:163], v[192:195], v[60:63]
	v_mfma_f32_16x16x32_bf16 v[56:59], v[168:171], v[192:195], v[56:59]
	v_mfma_f32_16x16x32_bf16 v[44:47], v[160:163], v[200:203], v[44:47]
	v_mfma_f32_16x16x32_bf16 v[40:43], v[168:171], v[200:203], v[40:43]
	v_mfma_f32_16x16x32_bf16 v[28:31], v[160:163], v[208:211], v[28:31]
	v_mfma_f32_16x16x32_bf16 v[24:27], v[168:171], v[208:211], v[24:27]
	v_mfma_f32_16x16x32_bf16 v[12:15], v[160:163], v[216:219], v[12:15]
	v_mfma_f32_16x16x32_bf16 v[8:11], v[168:171], v[216:219], v[8:11]
	s_setprio 0
	s_setprio 1
	v_mfma_f32_16x16x32_bf16 v[52:55], v[172:175], v[188:191], 0
	v_mfma_f32_16x16x32_bf16 v[48:51], v[180:183], v[188:191], 0
	v_mfma_f32_16x16x32_bf16 v[36:39], v[172:175], v[196:199], 0
	v_mfma_f32_16x16x32_bf16 v[32:35], v[180:183], v[196:199], 0
	v_mfma_f32_16x16x32_bf16 v[20:23], v[172:175], v[204:207], 0
	v_mfma_f32_16x16x32_bf16 v[16:19], v[180:183], v[204:207], 0
	v_mfma_f32_16x16x32_bf16 v[4:7], v[172:175], v[212:215], 0
	v_mfma_f32_16x16x32_bf16 v[0:3], v[180:183], v[212:215], 0
	v_mfma_f32_16x16x32_bf16 v[52:55], v[176:179], v[192:195], v[52:55]
	v_mfma_f32_16x16x32_bf16 v[48:51], v[184:187], v[192:195], v[48:51]
	v_mfma_f32_16x16x32_bf16 v[36:39], v[176:179], v[200:203], v[36:39]
	v_mfma_f32_16x16x32_bf16 v[32:35], v[184:187], v[200:203], v[32:35]
	v_mfma_f32_16x16x32_bf16 v[20:23], v[176:179], v[208:211], v[20:23]
	v_mfma_f32_16x16x32_bf16 v[16:19], v[184:187], v[208:211], v[16:19]
	v_mfma_f32_16x16x32_bf16 v[4:7], v[176:179], v[216:219], v[4:7]
	v_mfma_f32_16x16x32_bf16 v[0:3], v[184:187], v[216:219], v[0:3]
	s_setprio 0
	s_barrier
	s_add_i32 s86, 0, 0x18000
	v_add_u32_e32 v159, s86, v152
	s_add_i32 s87, 0, 0x1c000
	ds_read_b128 v[148:151], v159
	ds_read_b128 v[160:163], v159 offset:1024
	ds_read_b128 v[164:167], v159 offset:2048
	ds_read_b128 v[168:171], v159 offset:3072
	v_add_u32_e32 v159, s87, v152
	ds_read_b128 v[172:175], v159
	ds_read_b128 v[176:179], v159 offset:1024
	ds_read_b128 v[180:183], v159 offset:2048
	ds_read_b128 v[184:187], v159 offset:3072
	s_add_u32 s34, s50, 0x40000
	s_addc_u32 s35, s51, 0
	s_mov_b32 m0, s59
	v_lshl_add_u64 v[228:229], s[34:35], 0, v[138:139]
	ds_read_b128 v[188:191], v158 offset:32768
	ds_read_b128 v[192:195], v158 offset:33792
	ds_read_b128 v[196:199], v158 offset:34816
	ds_read_b128 v[200:203], v158 offset:35840
	ds_read_b128 v[204:207], v158 offset:36864
	ds_read_b128 v[208:211], v158 offset:37888
	ds_read_b128 v[212:215], v158 offset:38912
	ds_read_b128 v[216:219], v158 offset:39936
	global_load_lds_dwordx4 v[228:229], off
	v_lshl_add_u64 v[228:229], s[34:35], 0, v[134:135]
	s_mov_b32 m0, s62
	s_nop 0
	global_load_lds_dwordx4 v[228:229], off
	s_waitcnt vmcnt(8)
	s_waitcnt lgkmcnt(0)
	s_barrier
	s_setprio 1
	s_waitcnt lgkmcnt(0)
	v_mfma_f32_16x16x32_bf16 v[124:127], v[148:151], v[188:191], v[124:127]
	v_mfma_f32_16x16x32_bf16 v[120:123], v[164:167], v[188:191], v[120:123]
	v_mfma_f32_16x16x32_bf16 v[108:111], v[148:151], v[196:199], v[108:111]
	v_mfma_f32_16x16x32_bf16 v[104:107], v[164:167], v[196:199], v[104:107]
	v_mfma_f32_16x16x32_bf16 v[92:95], v[148:151], v[204:207], v[92:95]
	v_mfma_f32_16x16x32_bf16 v[88:91], v[164:167], v[204:207], v[88:91]
	v_mfma_f32_16x16x32_bf16 v[76:79], v[148:151], v[212:215], v[76:79]
	v_mfma_f32_16x16x32_bf16 v[72:75], v[164:167], v[212:215], v[72:75]
	v_mfma_f32_16x16x32_bf16 v[124:127], v[160:163], v[192:195], v[124:127]
	v_mfma_f32_16x16x32_bf16 v[120:123], v[168:171], v[192:195], v[120:123]
	v_mfma_f32_16x16x32_bf16 v[108:111], v[160:163], v[200:203], v[108:111]
	v_mfma_f32_16x16x32_bf16 v[104:107], v[168:171], v[200:203], v[104:107]
	v_mfma_f32_16x16x32_bf16 v[92:95], v[160:163], v[208:211], v[92:95]
	v_mfma_f32_16x16x32_bf16 v[88:91], v[168:171], v[208:211], v[88:91]
	v_mfma_f32_16x16x32_bf16 v[76:79], v[160:163], v[216:219], v[76:79]
	v_mfma_f32_16x16x32_bf16 v[72:75], v[168:171], v[216:219], v[72:75]
	s_setprio 0
	s_setprio 1
	v_mfma_f32_16x16x32_bf16 v[116:119], v[172:175], v[188:191], v[116:119]
	v_mfma_f32_16x16x32_bf16 v[112:115], v[180:183], v[188:191], v[112:115]
	v_mfma_f32_16x16x32_bf16 v[100:103], v[172:175], v[196:199], v[100:103]
	v_mfma_f32_16x16x32_bf16 v[96:99], v[180:183], v[196:199], v[96:99]
	v_mfma_f32_16x16x32_bf16 v[84:87], v[172:175], v[204:207], v[84:87]
	v_mfma_f32_16x16x32_bf16 v[80:83], v[180:183], v[204:207], v[80:83]
	v_mfma_f32_16x16x32_bf16 v[68:71], v[172:175], v[212:215], v[68:71]
	v_mfma_f32_16x16x32_bf16 v[64:67], v[180:183], v[212:215], v[64:67]
	v_mfma_f32_16x16x32_bf16 v[116:119], v[176:179], v[192:195], v[116:119]
	v_mfma_f32_16x16x32_bf16 v[112:115], v[184:187], v[192:195], v[112:115]
	v_mfma_f32_16x16x32_bf16 v[100:103], v[176:179], v[200:203], v[100:103]
	v_mfma_f32_16x16x32_bf16 v[96:99], v[184:187], v[200:203], v[96:99]
	v_mfma_f32_16x16x32_bf16 v[84:87], v[176:179], v[208:211], v[84:87]
	v_mfma_f32_16x16x32_bf16 v[80:83], v[184:187], v[208:211], v[80:83]
	v_mfma_f32_16x16x32_bf16 v[68:71], v[176:179], v[216:219], v[68:71]
	v_mfma_f32_16x16x32_bf16 v[64:67], v[184:187], v[216:219], v[64:67]
	s_setprio 0
	s_barrier
	s_add_i32 s34, s86, s54
	v_lshl_add_u64 v[220:221], v[220:221], 0, s[6:7]
	s_mov_b32 m0, s34
	ds_read_b128 v[188:191], v158 offset:49152
	ds_read_b128 v[192:195], v158 offset:50176
	ds_read_b128 v[196:199], v158 offset:51200
	ds_read_b128 v[200:203], v158 offset:52224
	ds_read_b128 v[204:207], v158 offset:53248
	ds_read_b128 v[208:211], v158 offset:54272
	ds_read_b128 v[212:215], v158 offset:55296
	ds_read_b128 v[216:219], v158 offset:56320
	global_load_lds_dwordx4 v[220:221], off
	s_add_i32 m0, s34, 0x2000
	s_add_u32 s34, s48, 0x40080
	v_lshl_add_u64 v[220:221], v[222:223], 0, s[6:7]
	s_addc_u32 s35, s49, 0
	s_add_i32 s48, s87, s54
	global_load_lds_dwordx4 v[220:221], off
	v_lshl_add_u64 v[220:221], s[34:35], 0, v[136:137]
	s_mov_b32 m0, s48
	s_nop 0
	global_load_lds_dwordx4 v[220:221], off
	v_lshl_add_u64 v[220:221], s[34:35], 0, v[132:133]
	s_add_i32 m0, s48, 0x2000
	s_nop 0
	global_load_lds_dwordx4 v[220:221], off
	v_lshl_add_u64 v[220:221], v[224:225], 0, s[6:7]
	s_mov_b32 m0, s63
	s_nop 0
	global_load_lds_dwordx4 v[220:221], off
	v_lshl_add_u64 v[220:221], v[226:227], 0, s[6:7]
	s_mov_b32 m0, s64
	s_nop 0
	global_load_lds_dwordx4 v[220:221], off
	s_waitcnt vmcnt(8)
	s_waitcnt lgkmcnt(0)
	s_barrier
	s_setprio 1
	s_waitcnt lgkmcnt(0)
	v_mfma_f32_16x16x32_bf16 v[60:63], v[148:151], v[188:191], v[60:63]
	v_mfma_f32_16x16x32_bf16 v[56:59], v[164:167], v[188:191], v[56:59]
	v_mfma_f32_16x16x32_bf16 v[44:47], v[148:151], v[196:199], v[44:47]
	v_mfma_f32_16x16x32_bf16 v[40:43], v[164:167], v[196:199], v[40:43]
	v_mfma_f32_16x16x32_bf16 v[28:31], v[148:151], v[204:207], v[28:31]
	v_mfma_f32_16x16x32_bf16 v[24:27], v[164:167], v[204:207], v[24:27]
	v_mfma_f32_16x16x32_bf16 v[12:15], v[148:151], v[212:215], v[12:15]
	v_mfma_f32_16x16x32_bf16 v[8:11], v[164:167], v[212:215], v[8:11]
	v_mfma_f32_16x16x32_bf16 v[60:63], v[160:163], v[192:195], v[60:63]
	v_mfma_f32_16x16x32_bf16 v[56:59], v[168:171], v[192:195], v[56:59]
	v_mfma_f32_16x16x32_bf16 v[44:47], v[160:163], v[200:203], v[44:47]
	v_mfma_f32_16x16x32_bf16 v[40:43], v[168:171], v[200:203], v[40:43]
	v_mfma_f32_16x16x32_bf16 v[28:31], v[160:163], v[208:211], v[28:31]
	v_mfma_f32_16x16x32_bf16 v[24:27], v[168:171], v[208:211], v[24:27]
	v_mfma_f32_16x16x32_bf16 v[12:15], v[160:163], v[216:219], v[12:15]
	v_mfma_f32_16x16x32_bf16 v[8:11], v[168:171], v[216:219], v[8:11]
	s_setprio 0
	s_setprio 1
	v_mfma_f32_16x16x32_bf16 v[52:55], v[172:175], v[188:191], v[52:55]
	v_mfma_f32_16x16x32_bf16 v[48:51], v[180:183], v[188:191], v[48:51]
	v_mfma_f32_16x16x32_bf16 v[36:39], v[172:175], v[196:199], v[36:39]
	v_mfma_f32_16x16x32_bf16 v[32:35], v[180:183], v[196:199], v[32:35]
	v_mfma_f32_16x16x32_bf16 v[20:23], v[172:175], v[204:207], v[20:23]
	v_mfma_f32_16x16x32_bf16 v[16:19], v[180:183], v[204:207], v[16:19]
	v_mfma_f32_16x16x32_bf16 v[4:7], v[172:175], v[212:215], v[4:7]
	v_mfma_f32_16x16x32_bf16 v[0:3], v[180:183], v[212:215], v[0:3]
	v_mfma_f32_16x16x32_bf16 v[52:55], v[176:179], v[192:195], v[52:55]
	v_mfma_f32_16x16x32_bf16 v[48:51], v[184:187], v[192:195], v[48:51]
	v_mfma_f32_16x16x32_bf16 v[36:39], v[176:179], v[200:203], v[36:39]
	v_mfma_f32_16x16x32_bf16 v[32:35], v[184:187], v[200:203], v[32:35]
	v_mfma_f32_16x16x32_bf16 v[20:23], v[176:179], v[208:211], v[20:23]
	v_mfma_f32_16x16x32_bf16 v[16:19], v[184:187], v[208:211], v[16:19]
	v_mfma_f32_16x16x32_bf16 v[4:7], v[176:179], v[216:219], v[4:7]
	v_mfma_f32_16x16x32_bf16 v[0:3], v[184:187], v[216:219], v[0:3]
	s_setprio 0
	s_barrier
	s_add_i32 s85, s85, 2
	s_add_u32 s42, s42, 0x100
	s_addc_u32 s43, s43, 0
	s_add_u32 s83, s83, 0x100
	s_addc_u32 s84, s84, 0

.Lmy_nobar2_6:
	ds_read_b128 v[148:151], v154
	ds_read_b128 v[160:163], v154 offset:1024
	ds_read_b128 v[164:167], v154 offset:2048
	ds_read_b128 v[168:171], v154 offset:3072
	ds_read_b128 v[172:175], v155
	ds_read_b128 v[176:179], v155 offset:1024
	ds_read_b128 v[180:183], v155 offset:2048
	ds_read_b128 v[184:187], v155 offset:3072
	s_add_u32 s34, s40, 0xfff50080
	s_addc_u32 s35, s41, -1
	s_cmp_eq_u32 s81, 40
	s_cselect_b32 s49, s1, s35
	s_cselect_b32 s48, s0, s34
	s_cselect_b32 s43, s29, s77
	s_cselect_b32 s42, s28, s13
	v_lshl_add_u64 v[220:221], s[40:41], 0, v[140:141]
	s_add_i32 m0, s52, 0xc000
	ds_read_b128 v[188:191], v157
	ds_read_b128 v[192:195], v157 offset:1024
	ds_read_b128 v[196:199], v157 offset:2048
	ds_read_b128 v[200:203], v157 offset:3072
	ds_read_b128 v[204:207], v157 offset:4096
	ds_read_b128 v[208:211], v157 offset:5120
	ds_read_b128 v[212:215], v157 offset:6144
	ds_read_b128 v[216:219], v157 offset:7168
	global_load_lds_dwordx4 v[220:221], off
	v_lshl_add_u64 v[220:221], s[40:41], 0, v[142:143]
	s_add_i32 m0, s52, 0xe000
	s_nop 0
	global_load_lds_dwordx4 v[220:221], off
	s_cmp_eq_u32 s66, 1
	s_cbranch_scc1 .Lmy_sw_6_0a
	s_waitcnt vmcnt(40)
	s_branch .Lmy_sw_6_0b

.Lmy_sw_6_0b:
	s_waitcnt lgkmcnt(0)
	s_barrier
	s_setprio 1
	s_waitcnt lgkmcnt(0)
	v_mfma_f32_16x16x32_bf16 v[124:127], v[148:151], v[188:191], 0
	v_mfma_f32_16x16x32_bf16 v[120:123], v[164:167], v[188:191], 0
	v_mfma_f32_16x16x32_bf16 v[108:111], v[148:151], v[196:199], 0
	v_mfma_f32_16x16x32_bf16 v[104:107], v[164:167], v[196:199], 0
	v_mfma_f32_16x16x32_bf16 v[92:95], v[148:151], v[204:207], 0
	v_mfma_f32_16x16x32_bf16 v[88:91], v[164:167], v[204:207], 0
	v_mfma_f32_16x16x32_bf16 v[76:79], v[148:151], v[212:215], 0
	v_mfma_f32_16x16x32_bf16 v[72:75], v[164:167], v[212:215], 0
	v_mfma_f32_16x16x32_bf16 v[124:127], v[160:163], v[192:195], v[124:127]
	v_mfma_f32_16x16x32_bf16 v[120:123], v[168:171], v[192:195], v[120:123]
	v_mfma_f32_16x16x32_bf16 v[108:111], v[160:163], v[200:203], v[108:111]
	v_mfma_f32_16x16x32_bf16 v[104:107], v[168:171], v[200:203], v[104:107]
	v_mfma_f32_16x16x32_bf16 v[92:95], v[160:163], v[208:211], v[92:95]
	v_mfma_f32_16x16x32_bf16 v[88:91], v[168:171], v[208:211], v[88:91]
	v_mfma_f32_16x16x32_bf16 v[76:79], v[160:163], v[216:219], v[76:79]
	v_mfma_f32_16x16x32_bf16 v[72:75], v[168:171], v[216:219], v[72:75]
	s_setprio 0
	s_setprio 1
	v_mfma_f32_16x16x32_bf16 v[116:119], v[172:175], v[188:191], 0
	v_mfma_f32_16x16x32_bf16 v[112:115], v[180:183], v[188:191], 0
	v_mfma_f32_16x16x32_bf16 v[100:103], v[172:175], v[196:199], 0
	v_mfma_f32_16x16x32_bf16 v[96:99], v[180:183], v[196:199], 0
	v_mfma_f32_16x16x32_bf16 v[84:87], v[172:175], v[204:207], 0
	v_mfma_f32_16x16x32_bf16 v[80:83], v[180:183], v[204:207], 0
	v_mfma_f32_16x16x32_bf16 v[68:71], v[172:175], v[212:215], 0
	v_mfma_f32_16x16x32_bf16 v[64:67], v[180:183], v[212:215], 0
	v_mfma_f32_16x16x32_bf16 v[116:119], v[176:179], v[192:195], v[116:119]
	v_mfma_f32_16x16x32_bf16 v[112:115], v[184:187], v[192:195], v[112:115]
	v_mfma_f32_16x16x32_bf16 v[100:103], v[176:179], v[200:203], v[100:103]
	v_mfma_f32_16x16x32_bf16 v[96:99], v[184:187], v[200:203], v[96:99]
	v_mfma_f32_16x16x32_bf16 v[84:87], v[176:179], v[208:211], v[84:87]
	v_mfma_f32_16x16x32_bf16 v[80:83], v[184:187], v[208:211], v[80:83]
	v_mfma_f32_16x16x32_bf16 v[68:71], v[176:179], v[216:219], v[68:71]
	v_mfma_f32_16x16x32_bf16 v[64:67], v[184:187], v[216:219], v[64:67]
	s_setprio 0
	s_barrier
	s_add_i32 s34, s64, s51
	v_lshl_add_u64 v[220:221], s[42:43], 0, v[134:135]
	s_mov_b32 m0, s34
	ds_read_b128 v[188:191], v157 offset:16384
	ds_read_b128 v[192:195], v157 offset:17408
	ds_read_b128 v[196:199], v157 offset:18432
	ds_read_b128 v[200:203], v157 offset:19456
	ds_read_b128 v[204:207], v157 offset:20480
	ds_read_b128 v[208:211], v157 offset:21504
	ds_read_b128 v[212:215], v157 offset:22528
	ds_read_b128 v[216:219], v157 offset:23552
	global_load_lds_dwordx4 v[220:221], off
	s_add_i32 m0, s34, 0x2000
	s_add_u32 s34, s42, 0xb0000
	v_lshl_add_u64 v[222:223], s[42:43], 0, v[138:139]
	s_addc_u32 s35, s43, 0
	s_add_i32 s82, s65, s51
	global_load_lds_dwordx4 v[222:223], off
	v_lshl_add_u64 v[224:225], s[34:35], 0, v[134:135]
	s_mov_b32 m0, s82
	v_lshl_add_u64 v[226:227], s[48:49], 0, v[136:137]
	global_load_lds_dwordx4 v[224:225], off
	v_lshl_add_u64 v[224:225], s[34:35], 0, v[138:139]
	s_add_i32 m0, s82, 0x2000
	s_nop 0
	global_load_lds_dwordx4 v[224:225], off
	v_lshl_add_u64 v[224:225], s[48:49], 0, v[132:133]
	s_mov_b32 m0, s52
	s_nop 0
	global_load_lds_dwordx4 v[224:225], off
	s_mov_b32 m0, s53
	s_nop 0
	global_load_lds_dwordx4 v[226:227], off
	s_cmp_eq_u32 s66, 1
	s_cbranch_scc1 .Lmy_sw_6_1a
	s_waitcnt vmcnt(40)
	s_branch .Lmy_sw_6_1b

.Lmy_sw_6_1b:
	s_waitcnt lgkmcnt(0)
	s_barrier
	s_setprio 1
	s_waitcnt lgkmcnt(0)
	v_mfma_f32_16x16x32_bf16 v[60:63], v[148:151], v[188:191], 0
	v_mfma_f32_16x16x32_bf16 v[56:59], v[164:167], v[188:191], 0
	v_mfma_f32_16x16x32_bf16 v[44:47], v[148:151], v[196:199], 0
	v_mfma_f32_16x16x32_bf16 v[40:43], v[164:167], v[196:199], 0
	v_mfma_f32_16x16x32_bf16 v[28:31], v[148:151], v[204:207], 0
	v_mfma_f32_16x16x32_bf16 v[24:27], v[164:167], v[204:207], 0
	v_mfma_f32_16x16x32_bf16 v[12:15], v[148:151], v[212:215], 0
	v_mfma_f32_16x16x32_bf16 v[8:11], v[164:167], v[212:215], 0
	v_mfma_f32_16x16x32_bf16 v[60:63], v[160:163], v[192:195], v[60:63]
	v_mfma_f32_16x16x32_bf16 v[56:59], v[168:171], v[192:195], v[56:59]
	v_mfma_f32_16x16x32_bf16 v[44:47], v[160:163], v[200:203], v[44:47]
	v_mfma_f32_16x16x32_bf16 v[40:43], v[168:171], v[200:203], v[40:43]
	v_mfma_f32_16x16x32_bf16 v[28:31], v[160:163], v[208:211], v[28:31]
	v_mfma_f32_16x16x32_bf16 v[24:27], v[168:171], v[208:211], v[24:27]
	v_mfma_f32_16x16x32_bf16 v[12:15], v[160:163], v[216:219], v[12:15]
	v_mfma_f32_16x16x32_bf16 v[8:11], v[168:171], v[216:219], v[8:11]
	s_setprio 0
	s_setprio 1
	v_mfma_f32_16x16x32_bf16 v[52:55], v[172:175], v[188:191], 0
	v_mfma_f32_16x16x32_bf16 v[48:51], v[180:183], v[188:191], 0
	v_mfma_f32_16x16x32_bf16 v[36:39], v[172:175], v[196:199], 0
	v_mfma_f32_16x16x32_bf16 v[32:35], v[180:183], v[196:199], 0
	v_mfma_f32_16x16x32_bf16 v[20:23], v[172:175], v[204:207], 0
	v_mfma_f32_16x16x32_bf16 v[16:19], v[180:183], v[204:207], 0
	v_mfma_f32_16x16x32_bf16 v[4:7], v[172:175], v[212:215], 0
	v_mfma_f32_16x16x32_bf16 v[0:3], v[180:183], v[212:215], 0
	v_mfma_f32_16x16x32_bf16 v[52:55], v[176:179], v[192:195], v[52:55]
	v_mfma_f32_16x16x32_bf16 v[48:51], v[184:187], v[192:195], v[48:51]
	v_mfma_f32_16x16x32_bf16 v[36:39], v[176:179], v[200:203], v[36:39]
	v_mfma_f32_16x16x32_bf16 v[32:35], v[184:187], v[200:203], v[32:35]
	v_mfma_f32_16x16x32_bf16 v[20:23], v[176:179], v[208:211], v[20:23]
	v_mfma_f32_16x16x32_bf16 v[16:19], v[184:187], v[208:211], v[16:19]
	v_mfma_f32_16x16x32_bf16 v[4:7], v[176:179], v[216:219], v[4:7]
	v_mfma_f32_16x16x32_bf16 v[0:3], v[184:187], v[216:219], v[0:3]
	s_setprio 0
	s_barrier
	s_add_i32 s82, 0, 0x18000
	v_add_u32_e32 v159, s82, v152
	s_add_i32 s83, 0, 0x1c000
	ds_read_b128 v[148:151], v159
	ds_read_b128 v[160:163], v159 offset:1024
	ds_read_b128 v[164:167], v159 offset:2048
	ds_read_b128 v[168:171], v159 offset:3072
	v_add_u32_e32 v159, s83, v152
	ds_read_b128 v[172:175], v159
	ds_read_b128 v[176:179], v159 offset:1024
	ds_read_b128 v[180:183], v159 offset:2048
	ds_read_b128 v[184:187], v159 offset:3072
	s_add_u32 s34, s48, 0xb0000
	s_addc_u32 s35, s49, 0
	s_mov_b32 m0, s54
	v_lshl_add_u64 v[228:229], s[34:35], 0, v[132:133]
	ds_read_b128 v[188:191], v157 offset:32768
	ds_read_b128 v[192:195], v157 offset:33792
	ds_read_b128 v[196:199], v157 offset:34816
	ds_read_b128 v[200:203], v157 offset:35840
	ds_read_b128 v[204:207], v157 offset:36864
	ds_read_b128 v[208:211], v157 offset:37888
	ds_read_b128 v[212:215], v157 offset:38912
	ds_read_b128 v[216:219], v157 offset:39936
	global_load_lds_dwordx4 v[228:229], off
	v_lshl_add_u64 v[228:229], s[34:35], 0, v[136:137]
	s_mov_b32 m0, s55
	s_nop 0
	global_load_lds_dwordx4 v[228:229], off
	s_waitcnt vmcnt(8)
	s_waitcnt lgkmcnt(0)
	s_barrier
	s_setprio 1
	s_waitcnt lgkmcnt(0)
	v_mfma_f32_16x16x32_bf16 v[124:127], v[148:151], v[188:191], v[124:127]
	v_mfma_f32_16x16x32_bf16 v[120:123], v[164:167], v[188:191], v[120:123]
	v_mfma_f32_16x16x32_bf16 v[108:111], v[148:151], v[196:199], v[108:111]
	v_mfma_f32_16x16x32_bf16 v[104:107], v[164:167], v[196:199], v[104:107]
	v_mfma_f32_16x16x32_bf16 v[92:95], v[148:151], v[204:207], v[92:95]
	v_mfma_f32_16x16x32_bf16 v[88:91], v[164:167], v[204:207], v[88:91]
	v_mfma_f32_16x16x32_bf16 v[76:79], v[148:151], v[212:215], v[76:79]
	v_mfma_f32_16x16x32_bf16 v[72:75], v[164:167], v[212:215], v[72:75]
	v_mfma_f32_16x16x32_bf16 v[124:127], v[160:163], v[192:195], v[124:127]
	v_mfma_f32_16x16x32_bf16 v[120:123], v[168:171], v[192:195], v[120:123]
	v_mfma_f32_16x16x32_bf16 v[108:111], v[160:163], v[200:203], v[108:111]
	v_mfma_f32_16x16x32_bf16 v[104:107], v[168:171], v[200:203], v[104:107]
	v_mfma_f32_16x16x32_bf16 v[92:95], v[160:163], v[208:211], v[92:95]
	v_mfma_f32_16x16x32_bf16 v[88:91], v[168:171], v[208:211], v[88:91]
	v_mfma_f32_16x16x32_bf16 v[76:79], v[160:163], v[216:219], v[76:79]
	v_mfma_f32_16x16x32_bf16 v[72:75], v[168:171], v[216:219], v[72:75]
	s_setprio 0
	s_setprio 1
	v_mfma_f32_16x16x32_bf16 v[116:119], v[172:175], v[188:191], v[116:119]
	v_mfma_f32_16x16x32_bf16 v[112:115], v[180:183], v[188:191], v[112:115]
	v_mfma_f32_16x16x32_bf16 v[100:103], v[172:175], v[196:199], v[100:103]
	v_mfma_f32_16x16x32_bf16 v[96:99], v[180:183], v[196:199], v[96:99]
	v_mfma_f32_16x16x32_bf16 v[84:87], v[172:175], v[204:207], v[84:87]
	v_mfma_f32_16x16x32_bf16 v[80:83], v[180:183], v[204:207], v[80:83]
	v_mfma_f32_16x16x32_bf16 v[68:71], v[172:175], v[212:215], v[68:71]
	v_mfma_f32_16x16x32_bf16 v[64:67], v[180:183], v[212:215], v[64:67]
	v_mfma_f32_16x16x32_bf16 v[116:119], v[176:179], v[192:195], v[116:119]
	v_mfma_f32_16x16x32_bf16 v[112:115], v[184:187], v[192:195], v[112:115]
	v_mfma_f32_16x16x32_bf16 v[100:103], v[176:179], v[200:203], v[100:103]
	v_mfma_f32_16x16x32_bf16 v[96:99], v[184:187], v[200:203], v[96:99]
	v_mfma_f32_16x16x32_bf16 v[84:87], v[176:179], v[208:211], v[84:87]
	v_mfma_f32_16x16x32_bf16 v[80:83], v[184:187], v[208:211], v[80:83]
	v_mfma_f32_16x16x32_bf16 v[68:71], v[176:179], v[216:219], v[68:71]
	v_mfma_f32_16x16x32_bf16 v[64:67], v[184:187], v[216:219], v[64:67]
	s_setprio 0
	s_barrier
	s_add_i32 s34, s82, s51
	v_lshl_add_u64 v[220:221], v[220:221], 0, s[22:23]
	s_mov_b32 m0, s34
	ds_read_b128 v[188:191], v157 offset:49152
	ds_read_b128 v[192:195], v157 offset:50176
	ds_read_b128 v[196:199], v157 offset:51200
	ds_read_b128 v[200:203], v157 offset:52224
	ds_read_b128 v[204:207], v157 offset:53248
	ds_read_b128 v[208:211], v157 offset:54272
	ds_read_b128 v[212:215], v157 offset:55296
	ds_read_b128 v[216:219], v157 offset:56320
	global_load_lds_dwordx4 v[220:221], off
	s_add_i32 m0, s34, 0x2000
	s_add_u32 s34, s42, 0xb0080
	v_lshl_add_u64 v[220:221], v[222:223], 0, s[22:23]
	s_addc_u32 s35, s43, 0
	s_add_i32 s42, s83, s51
	global_load_lds_dwordx4 v[220:221], off
	v_lshl_add_u64 v[220:221], s[34:35], 0, v[134:135]
	s_mov_b32 m0, s42
	s_nop 0
	global_load_lds_dwordx4 v[220:221], off
	v_lshl_add_u64 v[220:221], s[34:35], 0, v[138:139]
	s_add_i32 m0, s42, 0x2000
	s_nop 0
	global_load_lds_dwordx4 v[220:221], off
	v_lshl_add_u64 v[220:221], v[224:225], 0, s[22:23]
	s_mov_b32 m0, s57
	s_nop 0
	global_load_lds_dwordx4 v[220:221], off
	v_lshl_add_u64 v[220:221], v[226:227], 0, s[22:23]
	s_mov_b32 m0, s58
	s_nop 0
	global_load_lds_dwordx4 v[220:221], off
	s_waitcnt vmcnt(8)
	s_waitcnt lgkmcnt(0)
	s_barrier
	s_setprio 1
	s_waitcnt lgkmcnt(0)
	v_mfma_f32_16x16x32_bf16 v[60:63], v[148:151], v[188:191], v[60:63]
	v_mfma_f32_16x16x32_bf16 v[56:59], v[164:167], v[188:191], v[56:59]
	v_mfma_f32_16x16x32_bf16 v[44:47], v[148:151], v[196:199], v[44:47]
	v_mfma_f32_16x16x32_bf16 v[40:43], v[164:167], v[196:199], v[40:43]
	v_mfma_f32_16x16x32_bf16 v[28:31], v[148:151], v[204:207], v[28:31]
	v_mfma_f32_16x16x32_bf16 v[24:27], v[164:167], v[204:207], v[24:27]
	v_mfma_f32_16x16x32_bf16 v[12:15], v[148:151], v[212:215], v[12:15]
	v_mfma_f32_16x16x32_bf16 v[8:11], v[164:167], v[212:215], v[8:11]
	v_mfma_f32_16x16x32_bf16 v[60:63], v[160:163], v[192:195], v[60:63]
	v_mfma_f32_16x16x32_bf16 v[56:59], v[168:171], v[192:195], v[56:59]
	v_mfma_f32_16x16x32_bf16 v[44:47], v[160:163], v[200:203], v[44:47]
	v_mfma_f32_16x16x32_bf16 v[40:43], v[168:171], v[200:203], v[40:43]
	v_mfma_f32_16x16x32_bf16 v[28:31], v[160:163], v[208:211], v[28:31]
	v_mfma_f32_16x16x32_bf16 v[24:27], v[168:171], v[208:211], v[24:27]
	v_mfma_f32_16x16x32_bf16 v[12:15], v[160:163], v[216:219], v[12:15]
	v_mfma_f32_16x16x32_bf16 v[8:11], v[168:171], v[216:219], v[8:11]
	s_setprio 0
	s_setprio 1
	v_mfma_f32_16x16x32_bf16 v[52:55], v[172:175], v[188:191], v[52:55]
	v_mfma_f32_16x16x32_bf16 v[48:51], v[180:183], v[188:191], v[48:51]
	v_mfma_f32_16x16x32_bf16 v[36:39], v[172:175], v[196:199], v[36:39]
	v_mfma_f32_16x16x32_bf16 v[32:35], v[180:183], v[196:199], v[32:35]
	v_mfma_f32_16x16x32_bf16 v[20:23], v[172:175], v[204:207], v[20:23]
	v_mfma_f32_16x16x32_bf16 v[16:19], v[180:183], v[204:207], v[16:19]
	v_mfma_f32_16x16x32_bf16 v[4:7], v[172:175], v[212:215], v[4:7]
	v_mfma_f32_16x16x32_bf16 v[0:3], v[180:183], v[212:215], v[0:3]
	v_mfma_f32_16x16x32_bf16 v[52:55], v[176:179], v[192:195], v[52:55]
	v_mfma_f32_16x16x32_bf16 v[48:51], v[184:187], v[192:195], v[48:51]
	v_mfma_f32_16x16x32_bf16 v[36:39], v[176:179], v[200:203], v[36:39]
	v_mfma_f32_16x16x32_bf16 v[32:35], v[184:187], v[200:203], v[32:35]
	v_mfma_f32_16x16x32_bf16 v[20:23], v[176:179], v[208:211], v[20:23]
	v_mfma_f32_16x16x32_bf16 v[16:19], v[184:187], v[208:211], v[16:19]
	v_mfma_f32_16x16x32_bf16 v[4:7], v[176:179], v[216:219], v[4:7]
	v_mfma_f32_16x16x32_bf16 v[0:3], v[184:187], v[216:219], v[0:3]
	s_setprio 0
	s_barrier
	s_add_i32 s81, s81, 2
	s_add_u32 s40, s40, 0x100
	s_addc_u32 s41, s41, 0
	s_add_u32 s13, s13, 0x100
	s_addc_u32 s77, s77, 0

.Lmy_nobar2_7:
	ds_read_b128 v[148:151], v160
	ds_read_b128 v[152:155], v160 offset:1024
	ds_read_b128 v[164:167], v160 offset:2048
	ds_read_b128 v[168:171], v160 offset:3072
	ds_read_b128 v[172:175], v161
	ds_read_b128 v[176:179], v161 offset:1024
	ds_read_b128 v[180:183], v161 offset:2048
	ds_read_b128 v[184:187], v161 offset:3072
	s_add_u32 s34, s52, 0xfffc0080
	s_addc_u32 s35, s53, -1
	s_cmp_eq_u32 s77, 12
	s_cselect_b32 s57, s9, s35
	s_cselect_b32 s56, s10, s34
	s_cselect_b32 s55, s12, s43
	s_cselect_b32 s54, s13, s41
	v_lshl_add_u64 v[220:221], s[52:53], 0, v[140:141]
	s_add_i32 m0, s65, 0xc000
	ds_read_b128 v[188:191], v162
	ds_read_b128 v[192:195], v162 offset:1024
	ds_read_b128 v[196:199], v162 offset:2048
	ds_read_b128 v[200:203], v162 offset:3072
	ds_read_b128 v[204:207], v162 offset:4096
	ds_read_b128 v[208:211], v162 offset:5120
	ds_read_b128 v[212:215], v162 offset:6144
	ds_read_b128 v[216:219], v162 offset:7168
	global_load_lds_dwordx4 v[220:221], off
	v_lshl_add_u64 v[220:221], s[52:53], 0, v[142:143]
	s_add_i32 m0, s65, 0xe000
	s_nop 0
	global_load_lds_dwordx4 v[220:221], off
	s_cmp_eq_u32 s93, 1
	s_cbranch_scc1 .Lmy_sw_7_0a
	s_waitcnt vmcnt(24)
	s_branch .Lmy_sw_7_0b

.Lmy_sw_7_0b:
	s_waitcnt lgkmcnt(0)
	s_barrier
	s_setprio 1
	s_waitcnt lgkmcnt(0)
	v_mfma_f32_16x16x32_bf16 v[124:127], v[148:151], v[188:191], 0
	v_mfma_f32_16x16x32_bf16 v[120:123], v[164:167], v[188:191], 0
	v_mfma_f32_16x16x32_bf16 v[108:111], v[148:151], v[196:199], 0
	v_mfma_f32_16x16x32_bf16 v[104:107], v[164:167], v[196:199], 0
	v_mfma_f32_16x16x32_bf16 v[92:95], v[148:151], v[204:207], 0
	v_mfma_f32_16x16x32_bf16 v[88:91], v[164:167], v[204:207], 0
	v_mfma_f32_16x16x32_bf16 v[76:79], v[148:151], v[212:215], 0
	v_mfma_f32_16x16x32_bf16 v[72:75], v[164:167], v[212:215], 0
	v_mfma_f32_16x16x32_bf16 v[124:127], v[152:155], v[192:195], v[124:127]
	v_mfma_f32_16x16x32_bf16 v[120:123], v[168:171], v[192:195], v[120:123]
	v_mfma_f32_16x16x32_bf16 v[108:111], v[152:155], v[200:203], v[108:111]
	v_mfma_f32_16x16x32_bf16 v[104:107], v[168:171], v[200:203], v[104:107]
	v_mfma_f32_16x16x32_bf16 v[92:95], v[152:155], v[208:211], v[92:95]
	v_mfma_f32_16x16x32_bf16 v[88:91], v[168:171], v[208:211], v[88:91]
	v_mfma_f32_16x16x32_bf16 v[76:79], v[152:155], v[216:219], v[76:79]
	v_mfma_f32_16x16x32_bf16 v[72:75], v[168:171], v[216:219], v[72:75]
	s_setprio 0
	s_setprio 1
	v_mfma_f32_16x16x32_bf16 v[116:119], v[172:175], v[188:191], 0
	v_mfma_f32_16x16x32_bf16 v[112:115], v[180:183], v[188:191], 0
	v_mfma_f32_16x16x32_bf16 v[100:103], v[172:175], v[196:199], 0
	v_mfma_f32_16x16x32_bf16 v[96:99], v[180:183], v[196:199], 0
	v_mfma_f32_16x16x32_bf16 v[84:87], v[172:175], v[204:207], 0
	v_mfma_f32_16x16x32_bf16 v[80:83], v[180:183], v[204:207], 0
	v_mfma_f32_16x16x32_bf16 v[68:71], v[172:175], v[212:215], 0
	v_mfma_f32_16x16x32_bf16 v[64:67], v[180:183], v[212:215], 0
	v_mfma_f32_16x16x32_bf16 v[116:119], v[176:179], v[192:195], v[116:119]
	v_mfma_f32_16x16x32_bf16 v[112:115], v[184:187], v[192:195], v[112:115]
	v_mfma_f32_16x16x32_bf16 v[100:103], v[176:179], v[200:203], v[100:103]
	v_mfma_f32_16x16x32_bf16 v[96:99], v[184:187], v[200:203], v[96:99]
	v_mfma_f32_16x16x32_bf16 v[84:87], v[176:179], v[208:211], v[84:87]
	v_mfma_f32_16x16x32_bf16 v[80:83], v[184:187], v[208:211], v[80:83]
	v_mfma_f32_16x16x32_bf16 v[68:71], v[176:179], v[216:219], v[68:71]
	v_mfma_f32_16x16x32_bf16 v[64:67], v[184:187], v[216:219], v[64:67]
	s_setprio 0
	s_barrier
	s_add_i32 s34, s88, s62
	v_lshl_add_u64 v[220:221], s[54:55], 0, v[134:135]
	s_mov_b32 m0, s34
	ds_read_b128 v[188:191], v162 offset:16384
	ds_read_b128 v[192:195], v162 offset:17408
	ds_read_b128 v[196:199], v162 offset:18432
	ds_read_b128 v[200:203], v162 offset:19456
	ds_read_b128 v[204:207], v162 offset:20480
	ds_read_b128 v[208:211], v162 offset:21504
	ds_read_b128 v[212:215], v162 offset:22528
	ds_read_b128 v[216:219], v162 offset:23552
	global_load_lds_dwordx4 v[220:221], off
	s_add_i32 m0, s34, 0x2000
	s_add_u32 s34, s54, 0x40000
	v_lshl_add_u64 v[222:223], s[54:55], 0, v[138:139]
	s_addc_u32 s35, s55, 0
	s_add_i32 s90, s89, s62
	global_load_lds_dwordx4 v[222:223], off
	v_lshl_add_u64 v[224:225], s[34:35], 0, v[134:135]
	s_mov_b32 m0, s90
	v_lshl_add_u64 v[226:227], s[56:57], 0, v[136:137]
	global_load_lds_dwordx4 v[224:225], off
	v_lshl_add_u64 v[224:225], s[34:35], 0, v[138:139]
	s_add_i32 m0, s90, 0x2000
	s_nop 0
	global_load_lds_dwordx4 v[224:225], off
	v_lshl_add_u64 v[224:225], s[56:57], 0, v[132:133]
	s_mov_b32 m0, s65
	s_nop 0
	global_load_lds_dwordx4 v[224:225], off
	s_mov_b32 m0, s66
	s_nop 0
	global_load_lds_dwordx4 v[226:227], off
	s_cmp_eq_u32 s93, 1
	s_cbranch_scc1 .Lmy_sw_7_1a
	s_waitcnt vmcnt(24)
	s_branch .Lmy_sw_7_1b

.Lmy_sw_7_1b:
	s_waitcnt lgkmcnt(0)
	s_barrier
	s_setprio 1
	s_waitcnt lgkmcnt(0)
	v_mfma_f32_16x16x32_bf16 v[60:63], v[148:151], v[188:191], 0
	v_mfma_f32_16x16x32_bf16 v[56:59], v[164:167], v[188:191], 0
	v_mfma_f32_16x16x32_bf16 v[44:47], v[148:151], v[196:199], 0
	v_mfma_f32_16x16x32_bf16 v[40:43], v[164:167], v[196:199], 0
	v_mfma_f32_16x16x32_bf16 v[28:31], v[148:151], v[204:207], 0
	v_mfma_f32_16x16x32_bf16 v[24:27], v[164:167], v[204:207], 0
	v_mfma_f32_16x16x32_bf16 v[12:15], v[148:151], v[212:215], 0
	v_mfma_f32_16x16x32_bf16 v[8:11], v[164:167], v[212:215], 0
	v_mfma_f32_16x16x32_bf16 v[60:63], v[152:155], v[192:195], v[60:63]
	v_mfma_f32_16x16x32_bf16 v[56:59], v[168:171], v[192:195], v[56:59]
	v_mfma_f32_16x16x32_bf16 v[44:47], v[152:155], v[200:203], v[44:47]
	v_mfma_f32_16x16x32_bf16 v[40:43], v[168:171], v[200:203], v[40:43]
	v_mfma_f32_16x16x32_bf16 v[28:31], v[152:155], v[208:211], v[28:31]
	v_mfma_f32_16x16x32_bf16 v[24:27], v[168:171], v[208:211], v[24:27]
	v_mfma_f32_16x16x32_bf16 v[12:15], v[152:155], v[216:219], v[12:15]
	v_mfma_f32_16x16x32_bf16 v[8:11], v[168:171], v[216:219], v[8:11]
	s_setprio 0
	s_setprio 1
	v_mfma_f32_16x16x32_bf16 v[52:55], v[172:175], v[188:191], 0
	v_mfma_f32_16x16x32_bf16 v[48:51], v[180:183], v[188:191], 0
	v_mfma_f32_16x16x32_bf16 v[36:39], v[172:175], v[196:199], 0
	v_mfma_f32_16x16x32_bf16 v[32:35], v[180:183], v[196:199], 0
	v_mfma_f32_16x16x32_bf16 v[20:23], v[172:175], v[204:207], 0
	v_mfma_f32_16x16x32_bf16 v[16:19], v[180:183], v[204:207], 0
	v_mfma_f32_16x16x32_bf16 v[4:7], v[172:175], v[212:215], 0
	v_mfma_f32_16x16x32_bf16 v[0:3], v[180:183], v[212:215], 0
	v_mfma_f32_16x16x32_bf16 v[52:55], v[176:179], v[192:195], v[52:55]
	v_mfma_f32_16x16x32_bf16 v[48:51], v[184:187], v[192:195], v[48:51]
	v_mfma_f32_16x16x32_bf16 v[36:39], v[176:179], v[200:203], v[36:39]
	v_mfma_f32_16x16x32_bf16 v[32:35], v[184:187], v[200:203], v[32:35]
	v_mfma_f32_16x16x32_bf16 v[20:23], v[176:179], v[208:211], v[20:23]
	v_mfma_f32_16x16x32_bf16 v[16:19], v[184:187], v[208:211], v[16:19]
	v_mfma_f32_16x16x32_bf16 v[4:7], v[176:179], v[216:219], v[4:7]
	v_mfma_f32_16x16x32_bf16 v[0:3], v[184:187], v[216:219], v[0:3]
	s_setprio 0
	s_barrier
	s_add_i32 s90, 0, 0x18000
	s_add_i32 s95, 0, 0x1c000
	v_add_u32_e32 v168, s90, v157
	v_add_u32_e32 v184, s95, v157
	ds_read_b128 v[148:151], v168
	ds_read_b128 v[152:155], v168 offset:1024
	ds_read_b128 v[164:167], v168 offset:2048
	ds_read_b128 v[168:171], v168 offset:3072
	ds_read_b128 v[172:175], v184
	ds_read_b128 v[176:179], v184 offset:1024
	ds_read_b128 v[180:183], v184 offset:2048
	ds_read_b128 v[184:187], v184 offset:3072
	s_add_u32 s34, s56, 0x40000
	s_addc_u32 s35, s57, 0
	s_mov_b32 m0, s67
	v_lshl_add_u64 v[228:229], s[34:35], 0, v[132:133]
	ds_read_b128 v[188:191], v162 offset:32768
	ds_read_b128 v[192:195], v162 offset:33792
	ds_read_b128 v[196:199], v162 offset:34816
	ds_read_b128 v[200:203], v162 offset:35840
	ds_read_b128 v[204:207], v162 offset:36864
	ds_read_b128 v[208:211], v162 offset:37888
	ds_read_b128 v[212:215], v162 offset:38912
	ds_read_b128 v[216:219], v162 offset:39936
	global_load_lds_dwordx4 v[228:229], off
	v_lshl_add_u64 v[228:229], s[34:35], 0, v[136:137]
	s_mov_b32 m0, s79
	s_nop 0
	global_load_lds_dwordx4 v[228:229], off
	s_waitcnt vmcnt(8)
	s_waitcnt lgkmcnt(0)
	s_barrier
	s_setprio 1
	s_waitcnt lgkmcnt(0)
	v_mfma_f32_16x16x32_bf16 v[124:127], v[148:151], v[188:191], v[124:127]
	v_mfma_f32_16x16x32_bf16 v[120:123], v[164:167], v[188:191], v[120:123]
	v_mfma_f32_16x16x32_bf16 v[108:111], v[148:151], v[196:199], v[108:111]
	v_mfma_f32_16x16x32_bf16 v[104:107], v[164:167], v[196:199], v[104:107]
	v_mfma_f32_16x16x32_bf16 v[92:95], v[148:151], v[204:207], v[92:95]
	v_mfma_f32_16x16x32_bf16 v[88:91], v[164:167], v[204:207], v[88:91]
	v_mfma_f32_16x16x32_bf16 v[76:79], v[148:151], v[212:215], v[76:79]
	v_mfma_f32_16x16x32_bf16 v[72:75], v[164:167], v[212:215], v[72:75]
	v_mfma_f32_16x16x32_bf16 v[124:127], v[152:155], v[192:195], v[124:127]
	v_mfma_f32_16x16x32_bf16 v[120:123], v[168:171], v[192:195], v[120:123]
	v_mfma_f32_16x16x32_bf16 v[108:111], v[152:155], v[200:203], v[108:111]
	v_mfma_f32_16x16x32_bf16 v[104:107], v[168:171], v[200:203], v[104:107]
	v_mfma_f32_16x16x32_bf16 v[92:95], v[152:155], v[208:211], v[92:95]
	v_mfma_f32_16x16x32_bf16 v[88:91], v[168:171], v[208:211], v[88:91]
	v_mfma_f32_16x16x32_bf16 v[76:79], v[152:155], v[216:219], v[76:79]
	v_mfma_f32_16x16x32_bf16 v[72:75], v[168:171], v[216:219], v[72:75]
	s_setprio 0
	s_setprio 1
	v_mfma_f32_16x16x32_bf16 v[116:119], v[172:175], v[188:191], v[116:119]
	v_mfma_f32_16x16x32_bf16 v[112:115], v[180:183], v[188:191], v[112:115]
	v_mfma_f32_16x16x32_bf16 v[100:103], v[172:175], v[196:199], v[100:103]
	v_mfma_f32_16x16x32_bf16 v[96:99], v[180:183], v[196:199], v[96:99]
	v_mfma_f32_16x16x32_bf16 v[84:87], v[172:175], v[204:207], v[84:87]
	v_mfma_f32_16x16x32_bf16 v[80:83], v[180:183], v[204:207], v[80:83]
	v_mfma_f32_16x16x32_bf16 v[68:71], v[172:175], v[212:215], v[68:71]
	v_mfma_f32_16x16x32_bf16 v[64:67], v[180:183], v[212:215], v[64:67]
	v_mfma_f32_16x16x32_bf16 v[116:119], v[176:179], v[192:195], v[116:119]
	v_mfma_f32_16x16x32_bf16 v[112:115], v[184:187], v[192:195], v[112:115]
	v_mfma_f32_16x16x32_bf16 v[100:103], v[176:179], v[200:203], v[100:103]
	v_mfma_f32_16x16x32_bf16 v[96:99], v[184:187], v[200:203], v[96:99]
	v_mfma_f32_16x16x32_bf16 v[84:87], v[176:179], v[208:211], v[84:87]
	v_mfma_f32_16x16x32_bf16 v[80:83], v[184:187], v[208:211], v[80:83]
	v_mfma_f32_16x16x32_bf16 v[68:71], v[176:179], v[216:219], v[68:71]
	v_mfma_f32_16x16x32_bf16 v[64:67], v[184:187], v[216:219], v[64:67]
	s_setprio 0
	s_barrier
	s_add_i32 s34, s90, s62
	v_lshl_add_u64 v[220:221], v[220:221], 0, s[26:27]
	s_mov_b32 m0, s34
	ds_read_b128 v[188:191], v162 offset:49152
	ds_read_b128 v[192:195], v162 offset:50176
	ds_read_b128 v[196:199], v162 offset:51200
	ds_read_b128 v[200:203], v162 offset:52224
	ds_read_b128 v[204:207], v162 offset:53248
	ds_read_b128 v[208:211], v162 offset:54272
	ds_read_b128 v[212:215], v162 offset:55296
	ds_read_b128 v[216:219], v162 offset:56320
	global_load_lds_dwordx4 v[220:221], off
	s_add_i32 m0, s34, 0x2000
	s_add_u32 s34, s54, 0x40080
	v_lshl_add_u64 v[220:221], v[222:223], 0, s[26:27]
	s_addc_u32 s35, s55, 0
	s_add_i32 s54, s95, s62
	global_load_lds_dwordx4 v[220:221], off
	v_lshl_add_u64 v[220:221], s[34:35], 0, v[134:135]
	s_mov_b32 m0, s54
	s_nop 0
	global_load_lds_dwordx4 v[220:221], off
	v_lshl_add_u64 v[220:221], s[34:35], 0, v[138:139]
	s_add_i32 m0, s54, 0x2000
	s_nop 0
	global_load_lds_dwordx4 v[220:221], off
	v_lshl_add_u64 v[220:221], v[224:225], 0, s[26:27]
	s_mov_b32 m0, s83
	s_nop 0
	global_load_lds_dwordx4 v[220:221], off
	v_lshl_add_u64 v[220:221], v[226:227], 0, s[26:27]
	s_mov_b32 m0, s84
	s_nop 0
	global_load_lds_dwordx4 v[220:221], off
	s_waitcnt vmcnt(8)
	s_waitcnt lgkmcnt(0)
	s_barrier
	s_setprio 1
	s_waitcnt lgkmcnt(0)
	v_mfma_f32_16x16x32_bf16 v[60:63], v[148:151], v[188:191], v[60:63]
	v_mfma_f32_16x16x32_bf16 v[56:59], v[164:167], v[188:191], v[56:59]
	v_mfma_f32_16x16x32_bf16 v[44:47], v[148:151], v[196:199], v[44:47]
	v_mfma_f32_16x16x32_bf16 v[40:43], v[164:167], v[196:199], v[40:43]
	v_mfma_f32_16x16x32_bf16 v[28:31], v[148:151], v[204:207], v[28:31]
	v_mfma_f32_16x16x32_bf16 v[24:27], v[164:167], v[204:207], v[24:27]
	v_mfma_f32_16x16x32_bf16 v[12:15], v[148:151], v[212:215], v[12:15]
	v_mfma_f32_16x16x32_bf16 v[8:11], v[164:167], v[212:215], v[8:11]
	v_mfma_f32_16x16x32_bf16 v[60:63], v[152:155], v[192:195], v[60:63]
	v_mfma_f32_16x16x32_bf16 v[56:59], v[168:171], v[192:195], v[56:59]
	v_mfma_f32_16x16x32_bf16 v[44:47], v[152:155], v[200:203], v[44:47]
	v_mfma_f32_16x16x32_bf16 v[40:43], v[168:171], v[200:203], v[40:43]
	v_mfma_f32_16x16x32_bf16 v[28:31], v[152:155], v[208:211], v[28:31]
	v_mfma_f32_16x16x32_bf16 v[24:27], v[168:171], v[208:211], v[24:27]
	v_mfma_f32_16x16x32_bf16 v[12:15], v[152:155], v[216:219], v[12:15]
	v_mfma_f32_16x16x32_bf16 v[8:11], v[168:171], v[216:219], v[8:11]
	s_setprio 0
	s_setprio 1
	v_mfma_f32_16x16x32_bf16 v[52:55], v[172:175], v[188:191], v[52:55]
	v_mfma_f32_16x16x32_bf16 v[48:51], v[180:183], v[188:191], v[48:51]
	v_mfma_f32_16x16x32_bf16 v[36:39], v[172:175], v[196:199], v[36:39]
	v_mfma_f32_16x16x32_bf16 v[32:35], v[180:183], v[196:199], v[32:35]
	v_mfma_f32_16x16x32_bf16 v[20:23], v[172:175], v[204:207], v[20:23]
	v_mfma_f32_16x16x32_bf16 v[16:19], v[180:183], v[204:207], v[16:19]
	v_mfma_f32_16x16x32_bf16 v[4:7], v[172:175], v[212:215], v[4:7]
	v_mfma_f32_16x16x32_bf16 v[0:3], v[180:183], v[212:215], v[0:3]
	v_mfma_f32_16x16x32_bf16 v[52:55], v[176:179], v[192:195], v[52:55]
	v_mfma_f32_16x16x32_bf16 v[48:51], v[184:187], v[192:195], v[48:51]
	v_mfma_f32_16x16x32_bf16 v[36:39], v[176:179], v[200:203], v[36:39]
	v_mfma_f32_16x16x32_bf16 v[32:35], v[184:187], v[200:203], v[32:35]
	v_mfma_f32_16x16x32_bf16 v[20:23], v[176:179], v[208:211], v[20:23]
	v_mfma_f32_16x16x32_bf16 v[16:19], v[184:187], v[208:211], v[16:19]
	v_mfma_f32_16x16x32_bf16 v[4:7], v[176:179], v[216:219], v[4:7]
	v_mfma_f32_16x16x32_bf16 v[0:3], v[184:187], v[216:219], v[0:3]
	s_setprio 0
	s_barrier
	s_add_i32 s77, s77, 2
	s_add_u32 s52, s52, 0x100
	s_addc_u32 s53, s53, 0
	s_add_u32 s41, s41, 0x100
	s_addc_u32 s43, s43, 0

.Lmy_nobar2_9:
	ds_read_b128 v[148:151], v154
	ds_read_b128 v[160:163], v154 offset:1024
	ds_read_b128 v[164:167], v154 offset:2048
	ds_read_b128 v[168:171], v154 offset:3072
	ds_read_b128 v[172:175], v155
	ds_read_b128 v[176:179], v155 offset:1024
	ds_read_b128 v[180:183], v155 offset:2048
	ds_read_b128 v[184:187], v155 offset:3072
	s_add_u32 s34, s40, 0xfffc0080
	s_addc_u32 s35, s41, -1
	s_cmp_eq_u32 s77, 12
	s_cselect_b32 s49, s12, s35
	s_cselect_b32 s48, s13, s34
	s_cselect_b32 s43, s27, s67
	s_cselect_b32 s42, s29, s39
	v_lshl_add_u64 v[220:221], s[40:41], 0, v[140:141]
	s_add_i32 m0, s52, 0xc000
	ds_read_b128 v[188:191], v157
	ds_read_b128 v[192:195], v157 offset:1024
	ds_read_b128 v[196:199], v157 offset:2048
	ds_read_b128 v[200:203], v157 offset:3072
	ds_read_b128 v[204:207], v157 offset:4096
	ds_read_b128 v[208:211], v157 offset:5120
	ds_read_b128 v[212:215], v157 offset:6144
	ds_read_b128 v[216:219], v157 offset:7168
	global_load_lds_dwordx4 v[220:221], off
	v_lshl_add_u64 v[220:221], s[40:41], 0, v[142:143]
	s_add_i32 m0, s52, 0xe000
	s_nop 0
	global_load_lds_dwordx4 v[220:221], off
	s_cmp_eq_u32 s66, 1
	s_cbranch_scc1 .Lmy_sw_9_0a
	s_waitcnt vmcnt(40)
	s_branch .Lmy_sw_9_0b

.Lmy_sw_9_0b:
	s_waitcnt lgkmcnt(0)
	s_barrier
	s_setprio 1
	s_waitcnt lgkmcnt(0)
	v_mfma_f32_16x16x32_bf16 v[124:127], v[148:151], v[188:191], 0
	v_mfma_f32_16x16x32_bf16 v[120:123], v[164:167], v[188:191], 0
	v_mfma_f32_16x16x32_bf16 v[108:111], v[148:151], v[196:199], 0
	v_mfma_f32_16x16x32_bf16 v[104:107], v[164:167], v[196:199], 0
	v_mfma_f32_16x16x32_bf16 v[92:95], v[148:151], v[204:207], 0
	v_mfma_f32_16x16x32_bf16 v[88:91], v[164:167], v[204:207], 0
	v_mfma_f32_16x16x32_bf16 v[76:79], v[148:151], v[212:215], 0
	v_mfma_f32_16x16x32_bf16 v[72:75], v[164:167], v[212:215], 0
	v_mfma_f32_16x16x32_bf16 v[124:127], v[160:163], v[192:195], v[124:127]
	v_mfma_f32_16x16x32_bf16 v[120:123], v[168:171], v[192:195], v[120:123]
	v_mfma_f32_16x16x32_bf16 v[108:111], v[160:163], v[200:203], v[108:111]
	v_mfma_f32_16x16x32_bf16 v[104:107], v[168:171], v[200:203], v[104:107]
	v_mfma_f32_16x16x32_bf16 v[92:95], v[160:163], v[208:211], v[92:95]
	v_mfma_f32_16x16x32_bf16 v[88:91], v[168:171], v[208:211], v[88:91]
	v_mfma_f32_16x16x32_bf16 v[76:79], v[160:163], v[216:219], v[76:79]
	v_mfma_f32_16x16x32_bf16 v[72:75], v[168:171], v[216:219], v[72:75]
	s_setprio 0
	s_setprio 1
	v_mfma_f32_16x16x32_bf16 v[116:119], v[172:175], v[188:191], 0
	v_mfma_f32_16x16x32_bf16 v[112:115], v[180:183], v[188:191], 0
	v_mfma_f32_16x16x32_bf16 v[100:103], v[172:175], v[196:199], 0
	v_mfma_f32_16x16x32_bf16 v[96:99], v[180:183], v[196:199], 0
	v_mfma_f32_16x16x32_bf16 v[84:87], v[172:175], v[204:207], 0
	v_mfma_f32_16x16x32_bf16 v[80:83], v[180:183], v[204:207], 0
	v_mfma_f32_16x16x32_bf16 v[68:71], v[172:175], v[212:215], 0
	v_mfma_f32_16x16x32_bf16 v[64:67], v[180:183], v[212:215], 0
	v_mfma_f32_16x16x32_bf16 v[116:119], v[176:179], v[192:195], v[116:119]
	v_mfma_f32_16x16x32_bf16 v[112:115], v[184:187], v[192:195], v[112:115]
	v_mfma_f32_16x16x32_bf16 v[100:103], v[176:179], v[200:203], v[100:103]
	v_mfma_f32_16x16x32_bf16 v[96:99], v[184:187], v[200:203], v[96:99]
	v_mfma_f32_16x16x32_bf16 v[84:87], v[176:179], v[208:211], v[84:87]
	v_mfma_f32_16x16x32_bf16 v[80:83], v[184:187], v[208:211], v[80:83]
	v_mfma_f32_16x16x32_bf16 v[68:71], v[176:179], v[216:219], v[68:71]
	v_mfma_f32_16x16x32_bf16 v[64:67], v[184:187], v[216:219], v[64:67]
	s_setprio 0
	s_barrier
	s_add_i32 s34, s64, s51
	v_lshl_add_u64 v[220:221], s[42:43], 0, v[134:135]
	s_mov_b32 m0, s34
	ds_read_b128 v[188:191], v157 offset:16384
	ds_read_b128 v[192:195], v157 offset:17408
	ds_read_b128 v[196:199], v157 offset:18432
	ds_read_b128 v[200:203], v157 offset:19456
	ds_read_b128 v[204:207], v157 offset:20480
	ds_read_b128 v[208:211], v157 offset:21504
	ds_read_b128 v[212:215], v157 offset:22528
	ds_read_b128 v[216:219], v157 offset:23552
	global_load_lds_dwordx4 v[220:221], off
	s_add_i32 m0, s34, 0x2000
	s_add_u32 s34, s42, 0x40000
	v_lshl_add_u64 v[222:223], s[42:43], 0, v[138:139]
	s_addc_u32 s35, s43, 0
	s_add_i32 s79, s65, s51
	global_load_lds_dwordx4 v[222:223], off
	v_lshl_add_u64 v[224:225], s[34:35], 0, v[134:135]
	s_mov_b32 m0, s79
	v_lshl_add_u64 v[226:227], s[48:49], 0, v[136:137]
	global_load_lds_dwordx4 v[224:225], off
	v_lshl_add_u64 v[224:225], s[34:35], 0, v[138:139]
	s_add_i32 m0, s79, 0x2000
	s_nop 0
	global_load_lds_dwordx4 v[224:225], off
	v_lshl_add_u64 v[224:225], s[48:49], 0, v[132:133]
	s_mov_b32 m0, s52
	s_nop 0
	global_load_lds_dwordx4 v[224:225], off
	s_mov_b32 m0, s53
	s_nop 0
	global_load_lds_dwordx4 v[226:227], off
	s_cmp_eq_u32 s66, 1
	s_cbranch_scc1 .Lmy_sw_9_1a
	s_waitcnt vmcnt(40)
	s_branch .Lmy_sw_9_1b

.Lmy_sw_9_1b:
	s_waitcnt lgkmcnt(0)
	s_barrier
	s_setprio 1
	s_waitcnt lgkmcnt(0)
	v_mfma_f32_16x16x32_bf16 v[60:63], v[148:151], v[188:191], 0
	v_mfma_f32_16x16x32_bf16 v[56:59], v[164:167], v[188:191], 0
	v_mfma_f32_16x16x32_bf16 v[44:47], v[148:151], v[196:199], 0
	v_mfma_f32_16x16x32_bf16 v[40:43], v[164:167], v[196:199], 0
	v_mfma_f32_16x16x32_bf16 v[28:31], v[148:151], v[204:207], 0
	v_mfma_f32_16x16x32_bf16 v[24:27], v[164:167], v[204:207], 0
	v_mfma_f32_16x16x32_bf16 v[12:15], v[148:151], v[212:215], 0
	v_mfma_f32_16x16x32_bf16 v[8:11], v[164:167], v[212:215], 0
	v_mfma_f32_16x16x32_bf16 v[60:63], v[160:163], v[192:195], v[60:63]
	v_mfma_f32_16x16x32_bf16 v[56:59], v[168:171], v[192:195], v[56:59]
	v_mfma_f32_16x16x32_bf16 v[44:47], v[160:163], v[200:203], v[44:47]
	v_mfma_f32_16x16x32_bf16 v[40:43], v[168:171], v[200:203], v[40:43]
	v_mfma_f32_16x16x32_bf16 v[28:31], v[160:163], v[208:211], v[28:31]
	v_mfma_f32_16x16x32_bf16 v[24:27], v[168:171], v[208:211], v[24:27]
	v_mfma_f32_16x16x32_bf16 v[12:15], v[160:163], v[216:219], v[12:15]
	v_mfma_f32_16x16x32_bf16 v[8:11], v[168:171], v[216:219], v[8:11]
	s_setprio 0
	s_setprio 1
	v_mfma_f32_16x16x32_bf16 v[52:55], v[172:175], v[188:191], 0
	v_mfma_f32_16x16x32_bf16 v[48:51], v[180:183], v[188:191], 0
	v_mfma_f32_16x16x32_bf16 v[36:39], v[172:175], v[196:199], 0
	v_mfma_f32_16x16x32_bf16 v[32:35], v[180:183], v[196:199], 0
	v_mfma_f32_16x16x32_bf16 v[20:23], v[172:175], v[204:207], 0
	v_mfma_f32_16x16x32_bf16 v[16:19], v[180:183], v[204:207], 0
	v_mfma_f32_16x16x32_bf16 v[4:7], v[172:175], v[212:215], 0
	v_mfma_f32_16x16x32_bf16 v[0:3], v[180:183], v[212:215], 0
	v_mfma_f32_16x16x32_bf16 v[52:55], v[176:179], v[192:195], v[52:55]
	v_mfma_f32_16x16x32_bf16 v[48:51], v[184:187], v[192:195], v[48:51]
	v_mfma_f32_16x16x32_bf16 v[36:39], v[176:179], v[200:203], v[36:39]
	v_mfma_f32_16x16x32_bf16 v[32:35], v[184:187], v[200:203], v[32:35]
	v_mfma_f32_16x16x32_bf16 v[20:23], v[176:179], v[208:211], v[20:23]
	v_mfma_f32_16x16x32_bf16 v[16:19], v[184:187], v[208:211], v[16:19]
	v_mfma_f32_16x16x32_bf16 v[4:7], v[176:179], v[216:219], v[4:7]
	v_mfma_f32_16x16x32_bf16 v[0:3], v[184:187], v[216:219], v[0:3]
	s_setprio 0
	s_barrier
	s_add_i32 s79, 0, 0x18000
	v_add_u32_e32 v159, s79, v152
	s_add_i32 s81, 0, 0x1c000
	ds_read_b128 v[148:151], v159
	ds_read_b128 v[160:163], v159 offset:1024
	ds_read_b128 v[164:167], v159 offset:2048
	ds_read_b128 v[168:171], v159 offset:3072
	v_add_u32_e32 v159, s81, v152
	ds_read_b128 v[172:175], v159
	ds_read_b128 v[176:179], v159 offset:1024
	ds_read_b128 v[180:183], v159 offset:2048
	ds_read_b128 v[184:187], v159 offset:3072
	s_add_u32 s34, s48, 0x40000
	s_addc_u32 s35, s49, 0
	s_mov_b32 m0, s54
	v_lshl_add_u64 v[228:229], s[34:35], 0, v[132:133]
	ds_read_b128 v[188:191], v157 offset:32768
	ds_read_b128 v[192:195], v157 offset:33792
	ds_read_b128 v[196:199], v157 offset:34816
	ds_read_b128 v[200:203], v157 offset:35840
	ds_read_b128 v[204:207], v157 offset:36864
	ds_read_b128 v[208:211], v157 offset:37888
	ds_read_b128 v[212:215], v157 offset:38912
	ds_read_b128 v[216:219], v157 offset:39936
	global_load_lds_dwordx4 v[228:229], off
	v_lshl_add_u64 v[228:229], s[34:35], 0, v[136:137]
	s_mov_b32 m0, s55
	s_nop 0
	global_load_lds_dwordx4 v[228:229], off
	s_waitcnt vmcnt(8)
	s_waitcnt lgkmcnt(0)
	s_barrier
	s_setprio 1
	s_waitcnt lgkmcnt(0)
	v_mfma_f32_16x16x32_bf16 v[124:127], v[148:151], v[188:191], v[124:127]
	v_mfma_f32_16x16x32_bf16 v[120:123], v[164:167], v[188:191], v[120:123]
	v_mfma_f32_16x16x32_bf16 v[108:111], v[148:151], v[196:199], v[108:111]
	v_mfma_f32_16x16x32_bf16 v[104:107], v[164:167], v[196:199], v[104:107]
	v_mfma_f32_16x16x32_bf16 v[92:95], v[148:151], v[204:207], v[92:95]
	v_mfma_f32_16x16x32_bf16 v[88:91], v[164:167], v[204:207], v[88:91]
	v_mfma_f32_16x16x32_bf16 v[76:79], v[148:151], v[212:215], v[76:79]
	v_mfma_f32_16x16x32_bf16 v[72:75], v[164:167], v[212:215], v[72:75]
	v_mfma_f32_16x16x32_bf16 v[124:127], v[160:163], v[192:195], v[124:127]
	v_mfma_f32_16x16x32_bf16 v[120:123], v[168:171], v[192:195], v[120:123]
	v_mfma_f32_16x16x32_bf16 v[108:111], v[160:163], v[200:203], v[108:111]
	v_mfma_f32_16x16x32_bf16 v[104:107], v[168:171], v[200:203], v[104:107]
	v_mfma_f32_16x16x32_bf16 v[92:95], v[160:163], v[208:211], v[92:95]
	v_mfma_f32_16x16x32_bf16 v[88:91], v[168:171], v[208:211], v[88:91]
	v_mfma_f32_16x16x32_bf16 v[76:79], v[160:163], v[216:219], v[76:79]
	v_mfma_f32_16x16x32_bf16 v[72:75], v[168:171], v[216:219], v[72:75]
	s_setprio 0
	s_setprio 1
	v_mfma_f32_16x16x32_bf16 v[116:119], v[172:175], v[188:191], v[116:119]
	v_mfma_f32_16x16x32_bf16 v[112:115], v[180:183], v[188:191], v[112:115]
	v_mfma_f32_16x16x32_bf16 v[100:103], v[172:175], v[196:199], v[100:103]
	v_mfma_f32_16x16x32_bf16 v[96:99], v[180:183], v[196:199], v[96:99]
	v_mfma_f32_16x16x32_bf16 v[84:87], v[172:175], v[204:207], v[84:87]
	v_mfma_f32_16x16x32_bf16 v[80:83], v[180:183], v[204:207], v[80:83]
	v_mfma_f32_16x16x32_bf16 v[68:71], v[172:175], v[212:215], v[68:71]
	v_mfma_f32_16x16x32_bf16 v[64:67], v[180:183], v[212:215], v[64:67]
	v_mfma_f32_16x16x32_bf16 v[116:119], v[176:179], v[192:195], v[116:119]
	v_mfma_f32_16x16x32_bf16 v[112:115], v[184:187], v[192:195], v[112:115]
	v_mfma_f32_16x16x32_bf16 v[100:103], v[176:179], v[200:203], v[100:103]
	v_mfma_f32_16x16x32_bf16 v[96:99], v[184:187], v[200:203], v[96:99]
	v_mfma_f32_16x16x32_bf16 v[84:87], v[176:179], v[208:211], v[84:87]
	v_mfma_f32_16x16x32_bf16 v[80:83], v[184:187], v[208:211], v[80:83]
	v_mfma_f32_16x16x32_bf16 v[68:71], v[176:179], v[216:219], v[68:71]
	v_mfma_f32_16x16x32_bf16 v[64:67], v[184:187], v[216:219], v[64:67]
	s_setprio 0
	s_barrier
	s_add_i32 s34, s79, s51
	v_lshl_add_u64 v[220:221], v[220:221], 0, s[10:11]
	s_mov_b32 m0, s34
	ds_read_b128 v[188:191], v157 offset:49152
	ds_read_b128 v[192:195], v157 offset:50176
	ds_read_b128 v[196:199], v157 offset:51200
	ds_read_b128 v[200:203], v157 offset:52224
	ds_read_b128 v[204:207], v157 offset:53248
	ds_read_b128 v[208:211], v157 offset:54272
	ds_read_b128 v[212:215], v157 offset:55296
	ds_read_b128 v[216:219], v157 offset:56320
	global_load_lds_dwordx4 v[220:221], off
	s_add_i32 m0, s34, 0x2000
	s_add_u32 s34, s42, 0x40080
	v_lshl_add_u64 v[220:221], v[222:223], 0, s[10:11]
	s_addc_u32 s35, s43, 0
	s_add_i32 s42, s81, s51
	global_load_lds_dwordx4 v[220:221], off
	v_lshl_add_u64 v[220:221], s[34:35], 0, v[134:135]
	s_mov_b32 m0, s42
	s_nop 0
	global_load_lds_dwordx4 v[220:221], off
	v_lshl_add_u64 v[220:221], s[34:35], 0, v[138:139]
	s_add_i32 m0, s42, 0x2000
	s_nop 0
	global_load_lds_dwordx4 v[220:221], off
	v_lshl_add_u64 v[220:221], v[224:225], 0, s[10:11]
	s_mov_b32 m0, s57
	s_nop 0
	global_load_lds_dwordx4 v[220:221], off
	v_lshl_add_u64 v[220:221], v[226:227], 0, s[10:11]
	s_mov_b32 m0, s58
	s_nop 0
	global_load_lds_dwordx4 v[220:221], off
	s_waitcnt vmcnt(8)
	s_waitcnt lgkmcnt(0)
	s_barrier
	s_setprio 1
	s_waitcnt lgkmcnt(0)
	v_mfma_f32_16x16x32_bf16 v[60:63], v[148:151], v[188:191], v[60:63]
	v_mfma_f32_16x16x32_bf16 v[56:59], v[164:167], v[188:191], v[56:59]
	v_mfma_f32_16x16x32_bf16 v[44:47], v[148:151], v[196:199], v[44:47]
	v_mfma_f32_16x16x32_bf16 v[40:43], v[164:167], v[196:199], v[40:43]
	v_mfma_f32_16x16x32_bf16 v[28:31], v[148:151], v[204:207], v[28:31]
	v_mfma_f32_16x16x32_bf16 v[24:27], v[164:167], v[204:207], v[24:27]
	v_mfma_f32_16x16x32_bf16 v[12:15], v[148:151], v[212:215], v[12:15]
	v_mfma_f32_16x16x32_bf16 v[8:11], v[164:167], v[212:215], v[8:11]
	v_mfma_f32_16x16x32_bf16 v[60:63], v[160:163], v[192:195], v[60:63]
	v_mfma_f32_16x16x32_bf16 v[56:59], v[168:171], v[192:195], v[56:59]
	v_mfma_f32_16x16x32_bf16 v[44:47], v[160:163], v[200:203], v[44:47]
	v_mfma_f32_16x16x32_bf16 v[40:43], v[168:171], v[200:203], v[40:43]
	v_mfma_f32_16x16x32_bf16 v[28:31], v[160:163], v[208:211], v[28:31]
	v_mfma_f32_16x16x32_bf16 v[24:27], v[168:171], v[208:211], v[24:27]
	v_mfma_f32_16x16x32_bf16 v[12:15], v[160:163], v[216:219], v[12:15]
	v_mfma_f32_16x16x32_bf16 v[8:11], v[168:171], v[216:219], v[8:11]
	s_setprio 0
	s_setprio 1
	v_mfma_f32_16x16x32_bf16 v[52:55], v[172:175], v[188:191], v[52:55]
	v_mfma_f32_16x16x32_bf16 v[48:51], v[180:183], v[188:191], v[48:51]
	v_mfma_f32_16x16x32_bf16 v[36:39], v[172:175], v[196:199], v[36:39]
	v_mfma_f32_16x16x32_bf16 v[32:35], v[180:183], v[196:199], v[32:35]
	v_mfma_f32_16x16x32_bf16 v[20:23], v[172:175], v[204:207], v[20:23]
	v_mfma_f32_16x16x32_bf16 v[16:19], v[180:183], v[204:207], v[16:19]
	v_mfma_f32_16x16x32_bf16 v[4:7], v[172:175], v[212:215], v[4:7]
	v_mfma_f32_16x16x32_bf16 v[0:3], v[180:183], v[212:215], v[0:3]
	v_mfma_f32_16x16x32_bf16 v[52:55], v[176:179], v[192:195], v[52:55]
	v_mfma_f32_16x16x32_bf16 v[48:51], v[184:187], v[192:195], v[48:51]
	v_mfma_f32_16x16x32_bf16 v[36:39], v[176:179], v[200:203], v[36:39]
	v_mfma_f32_16x16x32_bf16 v[32:35], v[184:187], v[200:203], v[32:35]
	v_mfma_f32_16x16x32_bf16 v[20:23], v[176:179], v[208:211], v[20:23]
	v_mfma_f32_16x16x32_bf16 v[16:19], v[184:187], v[208:211], v[16:19]
	v_mfma_f32_16x16x32_bf16 v[4:7], v[176:179], v[216:219], v[4:7]
	v_mfma_f32_16x16x32_bf16 v[0:3], v[184:187], v[216:219], v[0:3]
	s_setprio 0
	s_barrier
	s_add_i32 s77, s77, 2
	s_add_u32 s40, s40, 0x100
	s_addc_u32 s41, s41, 0
	s_add_u32 s39, s39, 0x100
	s_addc_u32 s67, s67, 0

.Lmy_nobar2_10:
	ds_read_b128 v[148:151], v155
	ds_read_b128 v[160:163], v155 offset:1024
	ds_read_b128 v[164:167], v155 offset:2048
	ds_read_b128 v[168:171], v155 offset:3072
	ds_read_b128 v[172:175], v157
	ds_read_b128 v[176:179], v157 offset:1024
	ds_read_b128 v[180:183], v157 offset:2048
	ds_read_b128 v[184:187], v157 offset:3072
	s_add_u32 s34, s36, 0xfffc0080
	s_addc_u32 s35, s37, -1
	s_cmp_eq_u32 s77, 12
	s_cselect_b32 s41, s23, s35
	s_cselect_b32 s40, s64, s34
	s_cselect_b32 s39, s11, s67
	s_cselect_b32 s38, s65, s66
	v_lshl_add_u64 v[220:221], s[36:37], 0, v[140:141]
	s_add_i32 m0, s31, 0xc000
	ds_read_b128 v[188:191], v158
	ds_read_b128 v[192:195], v158 offset:1024
	ds_read_b128 v[196:199], v158 offset:2048
	ds_read_b128 v[200:203], v158 offset:3072
	ds_read_b128 v[204:207], v158 offset:4096
	ds_read_b128 v[208:211], v158 offset:5120
	ds_read_b128 v[212:215], v158 offset:6144
	ds_read_b128 v[216:219], v158 offset:7168
	global_load_lds_dwordx4 v[220:221], off
	v_lshl_add_u64 v[220:221], s[36:37], 0, v[142:143]
	s_add_i32 m0, s31, 0xe000
	s_nop 0
	global_load_lds_dwordx4 v[220:221], off
	s_cmp_eq_u32 s62, 1
	s_cbranch_scc1 .Lmy_sw_10_0a
	s_waitcnt vmcnt(16)
	s_branch .Lmy_sw_10_0b

.Lmy_sw_10_0b:
	s_waitcnt lgkmcnt(0)
	s_barrier
	s_setprio 1
	s_waitcnt lgkmcnt(0)
	v_mfma_f32_16x16x32_bf16 v[124:127], v[148:151], v[188:191], 0
	v_mfma_f32_16x16x32_bf16 v[120:123], v[164:167], v[188:191], 0
	v_mfma_f32_16x16x32_bf16 v[108:111], v[148:151], v[196:199], 0
	v_mfma_f32_16x16x32_bf16 v[104:107], v[164:167], v[196:199], 0
	v_mfma_f32_16x16x32_bf16 v[92:95], v[148:151], v[204:207], 0
	v_mfma_f32_16x16x32_bf16 v[88:91], v[164:167], v[204:207], 0
	v_mfma_f32_16x16x32_bf16 v[76:79], v[148:151], v[212:215], 0
	v_mfma_f32_16x16x32_bf16 v[72:75], v[164:167], v[212:215], 0
	v_mfma_f32_16x16x32_bf16 v[124:127], v[160:163], v[192:195], v[124:127]
	v_mfma_f32_16x16x32_bf16 v[120:123], v[168:171], v[192:195], v[120:123]
	v_mfma_f32_16x16x32_bf16 v[108:111], v[160:163], v[200:203], v[108:111]
	v_mfma_f32_16x16x32_bf16 v[104:107], v[168:171], v[200:203], v[104:107]
	v_mfma_f32_16x16x32_bf16 v[92:95], v[160:163], v[208:211], v[92:95]
	v_mfma_f32_16x16x32_bf16 v[88:91], v[168:171], v[208:211], v[88:91]
	v_mfma_f32_16x16x32_bf16 v[76:79], v[160:163], v[216:219], v[76:79]
	v_mfma_f32_16x16x32_bf16 v[72:75], v[168:171], v[216:219], v[72:75]
	s_setprio 0
	s_setprio 1
	v_mfma_f32_16x16x32_bf16 v[116:119], v[172:175], v[188:191], 0
	v_mfma_f32_16x16x32_bf16 v[112:115], v[180:183], v[188:191], 0
	v_mfma_f32_16x16x32_bf16 v[100:103], v[172:175], v[196:199], 0
	v_mfma_f32_16x16x32_bf16 v[96:99], v[180:183], v[196:199], 0
	v_mfma_f32_16x16x32_bf16 v[84:87], v[172:175], v[204:207], 0
	v_mfma_f32_16x16x32_bf16 v[80:83], v[180:183], v[204:207], 0
	v_mfma_f32_16x16x32_bf16 v[68:71], v[172:175], v[212:215], 0
	v_mfma_f32_16x16x32_bf16 v[64:67], v[180:183], v[212:215], 0
	v_mfma_f32_16x16x32_bf16 v[116:119], v[176:179], v[192:195], v[116:119]
	v_mfma_f32_16x16x32_bf16 v[112:115], v[184:187], v[192:195], v[112:115]
	v_mfma_f32_16x16x32_bf16 v[100:103], v[176:179], v[200:203], v[100:103]
	v_mfma_f32_16x16x32_bf16 v[96:99], v[184:187], v[200:203], v[96:99]
	v_mfma_f32_16x16x32_bf16 v[84:87], v[176:179], v[208:211], v[84:87]
	v_mfma_f32_16x16x32_bf16 v[80:83], v[184:187], v[208:211], v[80:83]
	v_mfma_f32_16x16x32_bf16 v[68:71], v[176:179], v[216:219], v[68:71]
	v_mfma_f32_16x16x32_bf16 v[64:67], v[184:187], v[216:219], v[64:67]
	s_setprio 0
	s_barrier
	s_add_i32 s34, s57, s48
	v_lshl_add_u64 v[220:221], s[38:39], 0, v[136:137]
	s_mov_b32 m0, s34
	ds_read_b128 v[188:191], v158 offset:16384
	ds_read_b128 v[192:195], v158 offset:17408
	ds_read_b128 v[196:199], v158 offset:18432
	ds_read_b128 v[200:203], v158 offset:19456
	ds_read_b128 v[204:207], v158 offset:20480
	ds_read_b128 v[208:211], v158 offset:21504
	ds_read_b128 v[212:215], v158 offset:22528
	ds_read_b128 v[216:219], v158 offset:23552
	global_load_lds_dwordx4 v[220:221], off
	s_add_i32 m0, s34, 0x2000
	s_add_u32 s34, s38, 0x40000
	v_lshl_add_u64 v[222:223], s[38:39], 0, v[132:133]
	s_addc_u32 s35, s39, 0
	s_add_i32 s79, s58, s48
	global_load_lds_dwordx4 v[222:223], off
	v_lshl_add_u64 v[224:225], s[34:35], 0, v[136:137]
	s_mov_b32 m0, s79
	v_lshl_add_u64 v[226:227], s[40:41], 0, v[134:135]
	global_load_lds_dwordx4 v[224:225], off
	v_lshl_add_u64 v[224:225], s[34:35], 0, v[132:133]
	s_add_i32 m0, s79, 0x2000
	s_nop 0
	global_load_lds_dwordx4 v[224:225], off
	v_lshl_add_u64 v[224:225], s[40:41], 0, v[138:139]
	s_mov_b32 m0, s31
	s_nop 0
	global_load_lds_dwordx4 v[224:225], off
	s_mov_b32 m0, s52
	s_nop 0
	global_load_lds_dwordx4 v[226:227], off
	s_cmp_eq_u32 s62, 1
	s_cbranch_scc1 .Lmy_sw_10_1a
	s_waitcnt vmcnt(16)
	s_branch .Lmy_sw_10_1b

.Lmy_sw_10_1b:
	s_waitcnt lgkmcnt(0)
	s_barrier
	s_setprio 1
	s_waitcnt lgkmcnt(0)
	v_mfma_f32_16x16x32_bf16 v[60:63], v[148:151], v[188:191], 0
	v_mfma_f32_16x16x32_bf16 v[56:59], v[164:167], v[188:191], 0
	v_mfma_f32_16x16x32_bf16 v[44:47], v[148:151], v[196:199], 0
	v_mfma_f32_16x16x32_bf16 v[40:43], v[164:167], v[196:199], 0
	v_mfma_f32_16x16x32_bf16 v[28:31], v[148:151], v[204:207], 0
	v_mfma_f32_16x16x32_bf16 v[24:27], v[164:167], v[204:207], 0
	v_mfma_f32_16x16x32_bf16 v[12:15], v[148:151], v[212:215], 0
	v_mfma_f32_16x16x32_bf16 v[8:11], v[164:167], v[212:215], 0
	v_mfma_f32_16x16x32_bf16 v[60:63], v[160:163], v[192:195], v[60:63]
	v_mfma_f32_16x16x32_bf16 v[56:59], v[168:171], v[192:195], v[56:59]
	v_mfma_f32_16x16x32_bf16 v[44:47], v[160:163], v[200:203], v[44:47]
	v_mfma_f32_16x16x32_bf16 v[40:43], v[168:171], v[200:203], v[40:43]
	v_mfma_f32_16x16x32_bf16 v[28:31], v[160:163], v[208:211], v[28:31]
	v_mfma_f32_16x16x32_bf16 v[24:27], v[168:171], v[208:211], v[24:27]
	v_mfma_f32_16x16x32_bf16 v[12:15], v[160:163], v[216:219], v[12:15]
	v_mfma_f32_16x16x32_bf16 v[8:11], v[168:171], v[216:219], v[8:11]
	s_setprio 0
	s_setprio 1
	v_mfma_f32_16x16x32_bf16 v[52:55], v[172:175], v[188:191], 0
	v_mfma_f32_16x16x32_bf16 v[48:51], v[180:183], v[188:191], 0
	v_mfma_f32_16x16x32_bf16 v[36:39], v[172:175], v[196:199], 0
	v_mfma_f32_16x16x32_bf16 v[32:35], v[180:183], v[196:199], 0
	v_mfma_f32_16x16x32_bf16 v[20:23], v[172:175], v[204:207], 0
	v_mfma_f32_16x16x32_bf16 v[16:19], v[180:183], v[204:207], 0
	v_mfma_f32_16x16x32_bf16 v[4:7], v[172:175], v[212:215], 0
	v_mfma_f32_16x16x32_bf16 v[0:3], v[180:183], v[212:215], 0
	v_mfma_f32_16x16x32_bf16 v[52:55], v[176:179], v[192:195], v[52:55]
	v_mfma_f32_16x16x32_bf16 v[48:51], v[184:187], v[192:195], v[48:51]
	v_mfma_f32_16x16x32_bf16 v[36:39], v[176:179], v[200:203], v[36:39]
	v_mfma_f32_16x16x32_bf16 v[32:35], v[184:187], v[200:203], v[32:35]
	v_mfma_f32_16x16x32_bf16 v[20:23], v[176:179], v[208:211], v[20:23]
	v_mfma_f32_16x16x32_bf16 v[16:19], v[184:187], v[208:211], v[16:19]
	v_mfma_f32_16x16x32_bf16 v[4:7], v[176:179], v[216:219], v[4:7]
	v_mfma_f32_16x16x32_bf16 v[0:3], v[184:187], v[216:219], v[0:3]
	s_setprio 0
	s_barrier
	s_add_i32 s79, 0, 0x18000
	v_add_u32_e32 v159, s79, v152
	s_add_i32 s81, 0, 0x1c000
	ds_read_b128 v[148:151], v159
	ds_read_b128 v[160:163], v159 offset:1024
	ds_read_b128 v[164:167], v159 offset:2048
	ds_read_b128 v[168:171], v159 offset:3072
	v_add_u32_e32 v159, s81, v152
	ds_read_b128 v[172:175], v159
	ds_read_b128 v[176:179], v159 offset:1024
	ds_read_b128 v[180:183], v159 offset:2048
	ds_read_b128 v[184:187], v159 offset:3072
	s_add_u32 s34, s40, 0x40000
	s_addc_u32 s35, s41, 0
	s_mov_b32 m0, s53
	v_lshl_add_u64 v[228:229], s[34:35], 0, v[138:139]
	ds_read_b128 v[188:191], v158 offset:32768
	ds_read_b128 v[192:195], v158 offset:33792
	ds_read_b128 v[196:199], v158 offset:34816
	ds_read_b128 v[200:203], v158 offset:35840
	ds_read_b128 v[204:207], v158 offset:36864
	ds_read_b128 v[208:211], v158 offset:37888
	ds_read_b128 v[212:215], v158 offset:38912
	ds_read_b128 v[216:219], v158 offset:39936
	global_load_lds_dwordx4 v[228:229], off
	v_lshl_add_u64 v[228:229], s[34:35], 0, v[134:135]
	s_mov_b32 m0, s54
	s_nop 0
	global_load_lds_dwordx4 v[228:229], off
	s_waitcnt vmcnt(8)
	s_waitcnt lgkmcnt(0)
	s_barrier
	s_setprio 1
	s_waitcnt lgkmcnt(0)
	v_mfma_f32_16x16x32_bf16 v[124:127], v[148:151], v[188:191], v[124:127]
	v_mfma_f32_16x16x32_bf16 v[120:123], v[164:167], v[188:191], v[120:123]
	v_mfma_f32_16x16x32_bf16 v[108:111], v[148:151], v[196:199], v[108:111]
	v_mfma_f32_16x16x32_bf16 v[104:107], v[164:167], v[196:199], v[104:107]
	v_mfma_f32_16x16x32_bf16 v[92:95], v[148:151], v[204:207], v[92:95]
	v_mfma_f32_16x16x32_bf16 v[88:91], v[164:167], v[204:207], v[88:91]
	v_mfma_f32_16x16x32_bf16 v[76:79], v[148:151], v[212:215], v[76:79]
	v_mfma_f32_16x16x32_bf16 v[72:75], v[164:167], v[212:215], v[72:75]
	v_mfma_f32_16x16x32_bf16 v[124:127], v[160:163], v[192:195], v[124:127]
	v_mfma_f32_16x16x32_bf16 v[120:123], v[168:171], v[192:195], v[120:123]
	v_mfma_f32_16x16x32_bf16 v[108:111], v[160:163], v[200:203], v[108:111]
	v_mfma_f32_16x16x32_bf16 v[104:107], v[168:171], v[200:203], v[104:107]
	v_mfma_f32_16x16x32_bf16 v[92:95], v[160:163], v[208:211], v[92:95]
	v_mfma_f32_16x16x32_bf16 v[88:91], v[168:171], v[208:211], v[88:91]
	v_mfma_f32_16x16x32_bf16 v[76:79], v[160:163], v[216:219], v[76:79]
	v_mfma_f32_16x16x32_bf16 v[72:75], v[168:171], v[216:219], v[72:75]
	s_setprio 0
	s_setprio 1
	v_mfma_f32_16x16x32_bf16 v[116:119], v[172:175], v[188:191], v[116:119]
	v_mfma_f32_16x16x32_bf16 v[112:115], v[180:183], v[188:191], v[112:115]
	v_mfma_f32_16x16x32_bf16 v[100:103], v[172:175], v[196:199], v[100:103]
	v_mfma_f32_16x16x32_bf16 v[96:99], v[180:183], v[196:199], v[96:99]
	v_mfma_f32_16x16x32_bf16 v[84:87], v[172:175], v[204:207], v[84:87]
	v_mfma_f32_16x16x32_bf16 v[80:83], v[180:183], v[204:207], v[80:83]
	v_mfma_f32_16x16x32_bf16 v[68:71], v[172:175], v[212:215], v[68:71]
	v_mfma_f32_16x16x32_bf16 v[64:67], v[180:183], v[212:215], v[64:67]
	v_mfma_f32_16x16x32_bf16 v[116:119], v[176:179], v[192:195], v[116:119]
	v_mfma_f32_16x16x32_bf16 v[112:115], v[184:187], v[192:195], v[112:115]
	v_mfma_f32_16x16x32_bf16 v[100:103], v[176:179], v[200:203], v[100:103]
	v_mfma_f32_16x16x32_bf16 v[96:99], v[184:187], v[200:203], v[96:99]
	v_mfma_f32_16x16x32_bf16 v[84:87], v[176:179], v[208:211], v[84:87]
	v_mfma_f32_16x16x32_bf16 v[80:83], v[184:187], v[208:211], v[80:83]
	v_mfma_f32_16x16x32_bf16 v[68:71], v[176:179], v[216:219], v[68:71]
	v_mfma_f32_16x16x32_bf16 v[64:67], v[184:187], v[216:219], v[64:67]
	s_setprio 0
	s_barrier
	s_add_i32 s34, s79, s48
	v_lshl_add_u64 v[220:221], v[220:221], 0, s[6:7]
	s_mov_b32 m0, s34
	ds_read_b128 v[188:191], v158 offset:49152
	ds_read_b128 v[192:195], v158 offset:50176
	ds_read_b128 v[196:199], v158 offset:51200
	ds_read_b128 v[200:203], v158 offset:52224
	ds_read_b128 v[204:207], v158 offset:53248
	ds_read_b128 v[208:211], v158 offset:54272
	ds_read_b128 v[212:215], v158 offset:55296
	ds_read_b128 v[216:219], v158 offset:56320
	global_load_lds_dwordx4 v[220:221], off
	s_add_i32 m0, s34, 0x2000
	s_add_u32 s34, s38, 0x40080
	v_lshl_add_u64 v[220:221], v[222:223], 0, s[6:7]
	s_addc_u32 s35, s39, 0
	s_add_i32 s38, s81, s48
	global_load_lds_dwordx4 v[220:221], off
	v_lshl_add_u64 v[220:221], s[34:35], 0, v[136:137]
	s_mov_b32 m0, s38
	s_nop 0
	global_load_lds_dwordx4 v[220:221], off
	v_lshl_add_u64 v[220:221], s[34:35], 0, v[132:133]
	s_add_i32 m0, s38, 0x2000
	s_nop 0
	global_load_lds_dwordx4 v[220:221], off
	v_lshl_add_u64 v[220:221], v[224:225], 0, s[6:7]
	s_mov_b32 m0, s55
	s_nop 0
	global_load_lds_dwordx4 v[220:221], off
	v_lshl_add_u64 v[220:221], v[226:227], 0, s[6:7]
	s_mov_b32 m0, s56
	s_nop 0
	global_load_lds_dwordx4 v[220:221], off
	s_waitcnt vmcnt(8)
	s_waitcnt lgkmcnt(0)
	s_barrier
	s_setprio 1
	s_waitcnt lgkmcnt(0)
	v_mfma_f32_16x16x32_bf16 v[60:63], v[148:151], v[188:191], v[60:63]
	v_mfma_f32_16x16x32_bf16 v[56:59], v[164:167], v[188:191], v[56:59]
	v_mfma_f32_16x16x32_bf16 v[44:47], v[148:151], v[196:199], v[44:47]
	v_mfma_f32_16x16x32_bf16 v[40:43], v[164:167], v[196:199], v[40:43]
	v_mfma_f32_16x16x32_bf16 v[28:31], v[148:151], v[204:207], v[28:31]
	v_mfma_f32_16x16x32_bf16 v[24:27], v[164:167], v[204:207], v[24:27]
	v_mfma_f32_16x16x32_bf16 v[12:15], v[148:151], v[212:215], v[12:15]
	v_mfma_f32_16x16x32_bf16 v[8:11], v[164:167], v[212:215], v[8:11]
	v_mfma_f32_16x16x32_bf16 v[60:63], v[160:163], v[192:195], v[60:63]
	v_mfma_f32_16x16x32_bf16 v[56:59], v[168:171], v[192:195], v[56:59]
	v_mfma_f32_16x16x32_bf16 v[44:47], v[160:163], v[200:203], v[44:47]
	v_mfma_f32_16x16x32_bf16 v[40:43], v[168:171], v[200:203], v[40:43]
	v_mfma_f32_16x16x32_bf16 v[28:31], v[160:163], v[208:211], v[28:31]
	v_mfma_f32_16x16x32_bf16 v[24:27], v[168:171], v[208:211], v[24:27]
	v_mfma_f32_16x16x32_bf16 v[12:15], v[160:163], v[216:219], v[12:15]
	v_mfma_f32_16x16x32_bf16 v[8:11], v[168:171], v[216:219], v[8:11]
	s_setprio 0
	s_setprio 1
	v_mfma_f32_16x16x32_bf16 v[52:55], v[172:175], v[188:191], v[52:55]
	v_mfma_f32_16x16x32_bf16 v[48:51], v[180:183], v[188:191], v[48:51]
	v_mfma_f32_16x16x32_bf16 v[36:39], v[172:175], v[196:199], v[36:39]
	v_mfma_f32_16x16x32_bf16 v[32:35], v[180:183], v[196:199], v[32:35]
	v_mfma_f32_16x16x32_bf16 v[20:23], v[172:175], v[204:207], v[20:23]
	v_mfma_f32_16x16x32_bf16 v[16:19], v[180:183], v[204:207], v[16:19]
	v_mfma_f32_16x16x32_bf16 v[4:7], v[172:175], v[212:215], v[4:7]
	v_mfma_f32_16x16x32_bf16 v[0:3], v[180:183], v[212:215], v[0:3]
	v_mfma_f32_16x16x32_bf16 v[52:55], v[176:179], v[192:195], v[52:55]
	v_mfma_f32_16x16x32_bf16 v[48:51], v[184:187], v[192:195], v[48:51]
	v_mfma_f32_16x16x32_bf16 v[36:39], v[176:179], v[200:203], v[36:39]
	v_mfma_f32_16x16x32_bf16 v[32:35], v[184:187], v[200:203], v[32:35]
	v_mfma_f32_16x16x32_bf16 v[20:23], v[176:179], v[208:211], v[20:23]
	v_mfma_f32_16x16x32_bf16 v[16:19], v[184:187], v[208:211], v[16:19]
	v_mfma_f32_16x16x32_bf16 v[4:7], v[176:179], v[216:219], v[4:7]
	v_mfma_f32_16x16x32_bf16 v[0:3], v[184:187], v[216:219], v[0:3]
	s_setprio 0
	s_barrier
	s_add_i32 s77, s77, 2
	s_add_u32 s36, s36, 0x100
	s_addc_u32 s37, s37, 0
	s_add_u32 s66, s66, 0x100
	s_addc_u32 s67, s67, 0

.Lmy_nobar2_11:
	ds_read_b128 v[148:151], v154
	ds_read_b128 v[160:163], v154 offset:1024
	ds_read_b128 v[164:167], v154 offset:2048
	ds_read_b128 v[168:171], v154 offset:3072
	ds_read_b128 v[172:175], v155
	ds_read_b128 v[176:179], v155 offset:1024
	ds_read_b128 v[180:183], v155 offset:2048
	ds_read_b128 v[184:187], v155 offset:3072
	s_add_u32 s34, s30, 0xfff50080
	s_addc_u32 s35, s31, -1
	s_cmp_eq_u32 s64, 40
	s_cselect_b32 s39, s1, s35
	s_cselect_b32 s38, s0, s34
	s_cselect_b32 s37, s29, s63
	s_cselect_b32 s36, s28, s13
	v_lshl_add_u64 v[220:221], s[30:31], 0, v[140:141]
	s_add_i32 m0, s42, 0xc000
	ds_read_b128 v[188:191], v157
	ds_read_b128 v[192:195], v157 offset:1024
	ds_read_b128 v[196:199], v157 offset:2048
	ds_read_b128 v[200:203], v157 offset:3072
	ds_read_b128 v[204:207], v157 offset:4096
	ds_read_b128 v[208:211], v157 offset:5120
	ds_read_b128 v[212:215], v157 offset:6144
	ds_read_b128 v[216:219], v157 offset:7168
	global_load_lds_dwordx4 v[220:221], off
	v_lshl_add_u64 v[220:221], s[30:31], 0, v[142:143]
	s_add_i32 m0, s42, 0xe000
	s_nop 0
	global_load_lds_dwordx4 v[220:221], off
	s_cmp_eq_u32 s58, 1
	s_cbranch_scc1 .Lmy_sw_11_0a
	s_waitcnt vmcnt(40)
	s_branch .Lmy_sw_11_0b

.Lmy_sw_11_0b:
	s_waitcnt lgkmcnt(0)
	s_barrier
	s_setprio 1
	s_waitcnt lgkmcnt(0)
	v_mfma_f32_16x16x32_bf16 v[124:127], v[148:151], v[188:191], 0
	v_mfma_f32_16x16x32_bf16 v[120:123], v[164:167], v[188:191], 0
	v_mfma_f32_16x16x32_bf16 v[108:111], v[148:151], v[196:199], 0
	v_mfma_f32_16x16x32_bf16 v[104:107], v[164:167], v[196:199], 0
	v_mfma_f32_16x16x32_bf16 v[92:95], v[148:151], v[204:207], 0
	v_mfma_f32_16x16x32_bf16 v[88:91], v[164:167], v[204:207], 0
	v_mfma_f32_16x16x32_bf16 v[76:79], v[148:151], v[212:215], 0
	v_mfma_f32_16x16x32_bf16 v[72:75], v[164:167], v[212:215], 0
	v_mfma_f32_16x16x32_bf16 v[124:127], v[160:163], v[192:195], v[124:127]
	v_mfma_f32_16x16x32_bf16 v[120:123], v[168:171], v[192:195], v[120:123]
	v_mfma_f32_16x16x32_bf16 v[108:111], v[160:163], v[200:203], v[108:111]
	v_mfma_f32_16x16x32_bf16 v[104:107], v[168:171], v[200:203], v[104:107]
	v_mfma_f32_16x16x32_bf16 v[92:95], v[160:163], v[208:211], v[92:95]
	v_mfma_f32_16x16x32_bf16 v[88:91], v[168:171], v[208:211], v[88:91]
	v_mfma_f32_16x16x32_bf16 v[76:79], v[160:163], v[216:219], v[76:79]
	v_mfma_f32_16x16x32_bf16 v[72:75], v[168:171], v[216:219], v[72:75]
	s_setprio 0
	s_setprio 1
	v_mfma_f32_16x16x32_bf16 v[116:119], v[172:175], v[188:191], 0
	v_mfma_f32_16x16x32_bf16 v[112:115], v[180:183], v[188:191], 0
	v_mfma_f32_16x16x32_bf16 v[100:103], v[172:175], v[196:199], 0
	v_mfma_f32_16x16x32_bf16 v[96:99], v[180:183], v[196:199], 0
	v_mfma_f32_16x16x32_bf16 v[84:87], v[172:175], v[204:207], 0
	v_mfma_f32_16x16x32_bf16 v[80:83], v[180:183], v[204:207], 0
	v_mfma_f32_16x16x32_bf16 v[68:71], v[172:175], v[212:215], 0
	v_mfma_f32_16x16x32_bf16 v[64:67], v[180:183], v[212:215], 0
	v_mfma_f32_16x16x32_bf16 v[116:119], v[176:179], v[192:195], v[116:119]
	v_mfma_f32_16x16x32_bf16 v[112:115], v[184:187], v[192:195], v[112:115]
	v_mfma_f32_16x16x32_bf16 v[100:103], v[176:179], v[200:203], v[100:103]
	v_mfma_f32_16x16x32_bf16 v[96:99], v[184:187], v[200:203], v[96:99]
	v_mfma_f32_16x16x32_bf16 v[84:87], v[176:179], v[208:211], v[84:87]
	v_mfma_f32_16x16x32_bf16 v[80:83], v[184:187], v[208:211], v[80:83]
	v_mfma_f32_16x16x32_bf16 v[68:71], v[176:179], v[216:219], v[68:71]
	v_mfma_f32_16x16x32_bf16 v[64:67], v[184:187], v[216:219], v[64:67]
	s_setprio 0
	s_barrier
	s_add_i32 s34, s56, s41
	v_lshl_add_u64 v[220:221], s[36:37], 0, v[134:135]
	s_mov_b32 m0, s34
	ds_read_b128 v[188:191], v157 offset:16384
	ds_read_b128 v[192:195], v157 offset:17408
	ds_read_b128 v[196:199], v157 offset:18432
	ds_read_b128 v[200:203], v157 offset:19456
	ds_read_b128 v[204:207], v157 offset:20480
	ds_read_b128 v[208:211], v157 offset:21504
	ds_read_b128 v[212:215], v157 offset:22528
	ds_read_b128 v[216:219], v157 offset:23552
	global_load_lds_dwordx4 v[220:221], off
	s_add_i32 m0, s34, 0x2000
	s_add_u32 s34, s36, 0xb0000
	v_lshl_add_u64 v[222:223], s[36:37], 0, v[138:139]
	s_addc_u32 s35, s37, 0
	s_add_i32 s65, s57, s41
	global_load_lds_dwordx4 v[222:223], off
	v_lshl_add_u64 v[224:225], s[34:35], 0, v[134:135]
	s_mov_b32 m0, s65
	v_lshl_add_u64 v[226:227], s[38:39], 0, v[136:137]
	global_load_lds_dwordx4 v[224:225], off
	v_lshl_add_u64 v[224:225], s[34:35], 0, v[138:139]
	s_add_i32 m0, s65, 0x2000
	s_nop 0
	global_load_lds_dwordx4 v[224:225], off
	v_lshl_add_u64 v[224:225], s[38:39], 0, v[132:133]
	s_mov_b32 m0, s42
	s_nop 0
	global_load_lds_dwordx4 v[224:225], off
	s_mov_b32 m0, s43
	s_nop 0
	global_load_lds_dwordx4 v[226:227], off
	s_cmp_eq_u32 s58, 1
	s_cbranch_scc1 .Lmy_sw_11_1a
	s_waitcnt vmcnt(40)
	s_branch .Lmy_sw_11_1b

.Lmy_sw_11_1b:
	s_waitcnt lgkmcnt(0)
	s_barrier
	s_setprio 1
	s_waitcnt lgkmcnt(0)
	v_mfma_f32_16x16x32_bf16 v[60:63], v[148:151], v[188:191], 0
	v_mfma_f32_16x16x32_bf16 v[56:59], v[164:167], v[188:191], 0
	v_mfma_f32_16x16x32_bf16 v[44:47], v[148:151], v[196:199], 0
	v_mfma_f32_16x16x32_bf16 v[40:43], v[164:167], v[196:199], 0
	v_mfma_f32_16x16x32_bf16 v[28:31], v[148:151], v[204:207], 0
	v_mfma_f32_16x16x32_bf16 v[24:27], v[164:167], v[204:207], 0
	v_mfma_f32_16x16x32_bf16 v[12:15], v[148:151], v[212:215], 0
	v_mfma_f32_16x16x32_bf16 v[8:11], v[164:167], v[212:215], 0
	v_mfma_f32_16x16x32_bf16 v[60:63], v[160:163], v[192:195], v[60:63]
	v_mfma_f32_16x16x32_bf16 v[56:59], v[168:171], v[192:195], v[56:59]
	v_mfma_f32_16x16x32_bf16 v[44:47], v[160:163], v[200:203], v[44:47]
	v_mfma_f32_16x16x32_bf16 v[40:43], v[168:171], v[200:203], v[40:43]
	v_mfma_f32_16x16x32_bf16 v[28:31], v[160:163], v[208:211], v[28:31]
	v_mfma_f32_16x16x32_bf16 v[24:27], v[168:171], v[208:211], v[24:27]
	v_mfma_f32_16x16x32_bf16 v[12:15], v[160:163], v[216:219], v[12:15]
	v_mfma_f32_16x16x32_bf16 v[8:11], v[168:171], v[216:219], v[8:11]
	s_setprio 0
	s_setprio 1
	v_mfma_f32_16x16x32_bf16 v[52:55], v[172:175], v[188:191], 0
	v_mfma_f32_16x16x32_bf16 v[48:51], v[180:183], v[188:191], 0
	v_mfma_f32_16x16x32_bf16 v[36:39], v[172:175], v[196:199], 0
	v_mfma_f32_16x16x32_bf16 v[32:35], v[180:183], v[196:199], 0
	v_mfma_f32_16x16x32_bf16 v[20:23], v[172:175], v[204:207], 0
	v_mfma_f32_16x16x32_bf16 v[16:19], v[180:183], v[204:207], 0
	v_mfma_f32_16x16x32_bf16 v[4:7], v[172:175], v[212:215], 0
	v_mfma_f32_16x16x32_bf16 v[0:3], v[180:183], v[212:215], 0
	v_mfma_f32_16x16x32_bf16 v[52:55], v[176:179], v[192:195], v[52:55]
	v_mfma_f32_16x16x32_bf16 v[48:51], v[184:187], v[192:195], v[48:51]
	v_mfma_f32_16x16x32_bf16 v[36:39], v[176:179], v[200:203], v[36:39]
	v_mfma_f32_16x16x32_bf16 v[32:35], v[184:187], v[200:203], v[32:35]
	v_mfma_f32_16x16x32_bf16 v[20:23], v[176:179], v[208:211], v[20:23]
	v_mfma_f32_16x16x32_bf16 v[16:19], v[184:187], v[208:211], v[16:19]
	v_mfma_f32_16x16x32_bf16 v[4:7], v[176:179], v[216:219], v[4:7]
	v_mfma_f32_16x16x32_bf16 v[0:3], v[184:187], v[216:219], v[0:3]
	s_setprio 0
	s_barrier
	s_add_i32 s65, 0, 0x18000
	v_add_u32_e32 v159, s65, v152
	s_add_i32 s66, 0, 0x1c000
	ds_read_b128 v[148:151], v159
	ds_read_b128 v[160:163], v159 offset:1024
	ds_read_b128 v[164:167], v159 offset:2048
	ds_read_b128 v[168:171], v159 offset:3072
	v_add_u32_e32 v159, s66, v152
	ds_read_b128 v[172:175], v159
	ds_read_b128 v[176:179], v159 offset:1024
	ds_read_b128 v[180:183], v159 offset:2048
	ds_read_b128 v[184:187], v159 offset:3072
	s_add_u32 s34, s38, 0xb0000
	s_addc_u32 s35, s39, 0
	s_mov_b32 m0, s48
	v_lshl_add_u64 v[228:229], s[34:35], 0, v[132:133]
	ds_read_b128 v[188:191], v157 offset:32768
	ds_read_b128 v[192:195], v157 offset:33792
	ds_read_b128 v[196:199], v157 offset:34816
	ds_read_b128 v[200:203], v157 offset:35840
	ds_read_b128 v[204:207], v157 offset:36864
	ds_read_b128 v[208:211], v157 offset:37888
	ds_read_b128 v[212:215], v157 offset:38912
	ds_read_b128 v[216:219], v157 offset:39936
	global_load_lds_dwordx4 v[228:229], off
	v_lshl_add_u64 v[228:229], s[34:35], 0, v[136:137]
	s_mov_b32 m0, s49
	s_nop 0
	global_load_lds_dwordx4 v[228:229], off
	s_waitcnt vmcnt(8)
	s_waitcnt lgkmcnt(0)
	s_barrier
	s_setprio 1
	s_waitcnt lgkmcnt(0)
	v_mfma_f32_16x16x32_bf16 v[124:127], v[148:151], v[188:191], v[124:127]
	v_mfma_f32_16x16x32_bf16 v[120:123], v[164:167], v[188:191], v[120:123]
	v_mfma_f32_16x16x32_bf16 v[108:111], v[148:151], v[196:199], v[108:111]
	v_mfma_f32_16x16x32_bf16 v[104:107], v[164:167], v[196:199], v[104:107]
	v_mfma_f32_16x16x32_bf16 v[92:95], v[148:151], v[204:207], v[92:95]
	v_mfma_f32_16x16x32_bf16 v[88:91], v[164:167], v[204:207], v[88:91]
	v_mfma_f32_16x16x32_bf16 v[76:79], v[148:151], v[212:215], v[76:79]
	v_mfma_f32_16x16x32_bf16 v[72:75], v[164:167], v[212:215], v[72:75]
	v_mfma_f32_16x16x32_bf16 v[124:127], v[160:163], v[192:195], v[124:127]
	v_mfma_f32_16x16x32_bf16 v[120:123], v[168:171], v[192:195], v[120:123]
	v_mfma_f32_16x16x32_bf16 v[108:111], v[160:163], v[200:203], v[108:111]
	v_mfma_f32_16x16x32_bf16 v[104:107], v[168:171], v[200:203], v[104:107]
	v_mfma_f32_16x16x32_bf16 v[92:95], v[160:163], v[208:211], v[92:95]
	v_mfma_f32_16x16x32_bf16 v[88:91], v[168:171], v[208:211], v[88:91]
	v_mfma_f32_16x16x32_bf16 v[76:79], v[160:163], v[216:219], v[76:79]
	v_mfma_f32_16x16x32_bf16 v[72:75], v[168:171], v[216:219], v[72:75]
	s_setprio 0
	s_setprio 1
	v_mfma_f32_16x16x32_bf16 v[116:119], v[172:175], v[188:191], v[116:119]
	v_mfma_f32_16x16x32_bf16 v[112:115], v[180:183], v[188:191], v[112:115]
	v_mfma_f32_16x16x32_bf16 v[100:103], v[172:175], v[196:199], v[100:103]
	v_mfma_f32_16x16x32_bf16 v[96:99], v[180:183], v[196:199], v[96:99]
	v_mfma_f32_16x16x32_bf16 v[84:87], v[172:175], v[204:207], v[84:87]
	v_mfma_f32_16x16x32_bf16 v[80:83], v[180:183], v[204:207], v[80:83]
	v_mfma_f32_16x16x32_bf16 v[68:71], v[172:175], v[212:215], v[68:71]
	v_mfma_f32_16x16x32_bf16 v[64:67], v[180:183], v[212:215], v[64:67]
	v_mfma_f32_16x16x32_bf16 v[116:119], v[176:179], v[192:195], v[116:119]
	v_mfma_f32_16x16x32_bf16 v[112:115], v[184:187], v[192:195], v[112:115]
	v_mfma_f32_16x16x32_bf16 v[100:103], v[176:179], v[200:203], v[100:103]
	v_mfma_f32_16x16x32_bf16 v[96:99], v[184:187], v[200:203], v[96:99]
	v_mfma_f32_16x16x32_bf16 v[84:87], v[176:179], v[208:211], v[84:87]
	v_mfma_f32_16x16x32_bf16 v[80:83], v[184:187], v[208:211], v[80:83]
	v_mfma_f32_16x16x32_bf16 v[68:71], v[176:179], v[216:219], v[68:71]
	v_mfma_f32_16x16x32_bf16 v[64:67], v[184:187], v[216:219], v[64:67]
	s_setprio 0
	s_barrier
	s_add_i32 s34, s65, s41
	v_lshl_add_u64 v[220:221], v[220:221], 0, s[22:23]
	s_mov_b32 m0, s34
	ds_read_b128 v[188:191], v157 offset:49152
	ds_read_b128 v[192:195], v157 offset:50176
	ds_read_b128 v[196:199], v157 offset:51200
	ds_read_b128 v[200:203], v157 offset:52224
	ds_read_b128 v[204:207], v157 offset:53248
	ds_read_b128 v[208:211], v157 offset:54272
	ds_read_b128 v[212:215], v157 offset:55296
	ds_read_b128 v[216:219], v157 offset:56320
	global_load_lds_dwordx4 v[220:221], off
	s_add_i32 m0, s34, 0x2000
	s_add_u32 s34, s36, 0xb0080
	v_lshl_add_u64 v[220:221], v[222:223], 0, s[22:23]
	s_addc_u32 s35, s37, 0
	s_add_i32 s36, s66, s41
	global_load_lds_dwordx4 v[220:221], off
	v_lshl_add_u64 v[220:221], s[34:35], 0, v[134:135]
	s_mov_b32 m0, s36
	s_nop 0
	global_load_lds_dwordx4 v[220:221], off
	v_lshl_add_u64 v[220:221], s[34:35], 0, v[138:139]
	s_add_i32 m0, s36, 0x2000
	s_nop 0
	global_load_lds_dwordx4 v[220:221], off
	v_lshl_add_u64 v[220:221], v[224:225], 0, s[22:23]
	s_mov_b32 m0, s51
	s_nop 0
	global_load_lds_dwordx4 v[220:221], off
	v_lshl_add_u64 v[220:221], v[226:227], 0, s[22:23]
	s_mov_b32 m0, s52
	s_nop 0
	global_load_lds_dwordx4 v[220:221], off
	s_waitcnt vmcnt(8)
	s_waitcnt lgkmcnt(0)
	s_barrier
	s_setprio 1
	s_waitcnt lgkmcnt(0)
	v_mfma_f32_16x16x32_bf16 v[60:63], v[148:151], v[188:191], v[60:63]
	v_mfma_f32_16x16x32_bf16 v[56:59], v[164:167], v[188:191], v[56:59]
	v_mfma_f32_16x16x32_bf16 v[44:47], v[148:151], v[196:199], v[44:47]
	v_mfma_f32_16x16x32_bf16 v[40:43], v[164:167], v[196:199], v[40:43]
	v_mfma_f32_16x16x32_bf16 v[28:31], v[148:151], v[204:207], v[28:31]
	v_mfma_f32_16x16x32_bf16 v[24:27], v[164:167], v[204:207], v[24:27]
	v_mfma_f32_16x16x32_bf16 v[12:15], v[148:151], v[212:215], v[12:15]
	v_mfma_f32_16x16x32_bf16 v[8:11], v[164:167], v[212:215], v[8:11]
	v_mfma_f32_16x16x32_bf16 v[60:63], v[160:163], v[192:195], v[60:63]
	v_mfma_f32_16x16x32_bf16 v[56:59], v[168:171], v[192:195], v[56:59]
	v_mfma_f32_16x16x32_bf16 v[44:47], v[160:163], v[200:203], v[44:47]
	v_mfma_f32_16x16x32_bf16 v[40:43], v[168:171], v[200:203], v[40:43]
	v_mfma_f32_16x16x32_bf16 v[28:31], v[160:163], v[208:211], v[28:31]
	v_mfma_f32_16x16x32_bf16 v[24:27], v[168:171], v[208:211], v[24:27]
	v_mfma_f32_16x16x32_bf16 v[12:15], v[160:163], v[216:219], v[12:15]
	v_mfma_f32_16x16x32_bf16 v[8:11], v[168:171], v[216:219], v[8:11]
	s_setprio 0
	s_setprio 1
	v_mfma_f32_16x16x32_bf16 v[52:55], v[172:175], v[188:191], v[52:55]
	v_mfma_f32_16x16x32_bf16 v[48:51], v[180:183], v[188:191], v[48:51]
	v_mfma_f32_16x16x32_bf16 v[36:39], v[172:175], v[196:199], v[36:39]
	v_mfma_f32_16x16x32_bf16 v[32:35], v[180:183], v[196:199], v[32:35]
	v_mfma_f32_16x16x32_bf16 v[20:23], v[172:175], v[204:207], v[20:23]
	v_mfma_f32_16x16x32_bf16 v[16:19], v[180:183], v[204:207], v[16:19]
	v_mfma_f32_16x16x32_bf16 v[4:7], v[172:175], v[212:215], v[4:7]
	v_mfma_f32_16x16x32_bf16 v[0:3], v[180:183], v[212:215], v[0:3]
	v_mfma_f32_16x16x32_bf16 v[52:55], v[176:179], v[192:195], v[52:55]
	v_mfma_f32_16x16x32_bf16 v[48:51], v[184:187], v[192:195], v[48:51]
	v_mfma_f32_16x16x32_bf16 v[36:39], v[176:179], v[200:203], v[36:39]
	v_mfma_f32_16x16x32_bf16 v[32:35], v[184:187], v[200:203], v[32:35]
	v_mfma_f32_16x16x32_bf16 v[20:23], v[176:179], v[208:211], v[20:23]
	v_mfma_f32_16x16x32_bf16 v[16:19], v[184:187], v[208:211], v[16:19]
	v_mfma_f32_16x16x32_bf16 v[4:7], v[176:179], v[216:219], v[4:7]
	v_mfma_f32_16x16x32_bf16 v[0:3], v[184:187], v[216:219], v[0:3]
	s_setprio 0
	s_barrier
	s_add_i32 s64, s64, 2
	s_add_u32 s30, s30, 0x100
	s_addc_u32 s31, s31, 0
	s_add_u32 s13, s13, 0x100
	s_addc_u32 s63, s63, 0

.Lmy_nobar2_12:
	ds_read_b128 v[148:151], v155
	ds_read_b128 v[160:163], v155 offset:1024
	ds_read_b128 v[164:167], v155 offset:2048
	ds_read_b128 v[168:171], v155 offset:3072
	ds_read_b128 v[172:175], v157
	ds_read_b128 v[176:179], v157 offset:1024
	ds_read_b128 v[180:183], v157 offset:2048
	ds_read_b128 v[184:187], v157 offset:3072
	s_add_u32 s34, s36, 0xfffc0080
	s_addc_u32 s35, s37, -1
	s_cmp_eq_u32 s77, 12
	s_cselect_b32 s41, s23, s35
	s_cselect_b32 s40, s64, s34
	s_cselect_b32 s39, s11, s67
	s_cselect_b32 s38, s65, s66
	v_lshl_add_u64 v[220:221], s[36:37], 0, v[140:141]
	s_add_i32 m0, s31, 0xc000
	ds_read_b128 v[188:191], v158
	ds_read_b128 v[192:195], v158 offset:1024
	ds_read_b128 v[196:199], v158 offset:2048
	ds_read_b128 v[200:203], v158 offset:3072
	ds_read_b128 v[204:207], v158 offset:4096
	ds_read_b128 v[208:211], v158 offset:5120
	ds_read_b128 v[212:215], v158 offset:6144
	ds_read_b128 v[216:219], v158 offset:7168
	global_load_lds_dwordx4 v[220:221], off
	v_lshl_add_u64 v[220:221], s[36:37], 0, v[142:143]
	s_add_i32 m0, s31, 0xe000
	s_nop 0
	global_load_lds_dwordx4 v[220:221], off
	s_cmp_eq_u32 s58, 1
	s_cbranch_scc1 .Lmy_sw_12_0a
	s_waitcnt vmcnt(24)
	s_branch .Lmy_sw_12_0b

.Lmy_sw_12_0b:
	s_waitcnt lgkmcnt(0)
	s_barrier
	s_setprio 1
	s_waitcnt lgkmcnt(0)
	v_mfma_f32_16x16x32_bf16 v[124:127], v[148:151], v[188:191], 0
	v_mfma_f32_16x16x32_bf16 v[120:123], v[164:167], v[188:191], 0
	v_mfma_f32_16x16x32_bf16 v[108:111], v[148:151], v[196:199], 0
	v_mfma_f32_16x16x32_bf16 v[104:107], v[164:167], v[196:199], 0
	v_mfma_f32_16x16x32_bf16 v[92:95], v[148:151], v[204:207], 0
	v_mfma_f32_16x16x32_bf16 v[88:91], v[164:167], v[204:207], 0
	v_mfma_f32_16x16x32_bf16 v[76:79], v[148:151], v[212:215], 0
	v_mfma_f32_16x16x32_bf16 v[72:75], v[164:167], v[212:215], 0
	v_mfma_f32_16x16x32_bf16 v[124:127], v[160:163], v[192:195], v[124:127]
	v_mfma_f32_16x16x32_bf16 v[120:123], v[168:171], v[192:195], v[120:123]
	v_mfma_f32_16x16x32_bf16 v[108:111], v[160:163], v[200:203], v[108:111]
	v_mfma_f32_16x16x32_bf16 v[104:107], v[168:171], v[200:203], v[104:107]
	v_mfma_f32_16x16x32_bf16 v[92:95], v[160:163], v[208:211], v[92:95]
	v_mfma_f32_16x16x32_bf16 v[88:91], v[168:171], v[208:211], v[88:91]
	v_mfma_f32_16x16x32_bf16 v[76:79], v[160:163], v[216:219], v[76:79]
	v_mfma_f32_16x16x32_bf16 v[72:75], v[168:171], v[216:219], v[72:75]
	s_setprio 0
	s_setprio 1
	v_mfma_f32_16x16x32_bf16 v[116:119], v[172:175], v[188:191], 0
	v_mfma_f32_16x16x32_bf16 v[112:115], v[180:183], v[188:191], 0
	v_mfma_f32_16x16x32_bf16 v[100:103], v[172:175], v[196:199], 0
	v_mfma_f32_16x16x32_bf16 v[96:99], v[180:183], v[196:199], 0
	v_mfma_f32_16x16x32_bf16 v[84:87], v[172:175], v[204:207], 0
	v_mfma_f32_16x16x32_bf16 v[80:83], v[180:183], v[204:207], 0
	v_mfma_f32_16x16x32_bf16 v[68:71], v[172:175], v[212:215], 0
	v_mfma_f32_16x16x32_bf16 v[64:67], v[180:183], v[212:215], 0
	v_mfma_f32_16x16x32_bf16 v[116:119], v[176:179], v[192:195], v[116:119]
	v_mfma_f32_16x16x32_bf16 v[112:115], v[184:187], v[192:195], v[112:115]
	v_mfma_f32_16x16x32_bf16 v[100:103], v[176:179], v[200:203], v[100:103]
	v_mfma_f32_16x16x32_bf16 v[96:99], v[184:187], v[200:203], v[96:99]
	v_mfma_f32_16x16x32_bf16 v[84:87], v[176:179], v[208:211], v[84:87]
	v_mfma_f32_16x16x32_bf16 v[80:83], v[184:187], v[208:211], v[80:83]
	v_mfma_f32_16x16x32_bf16 v[68:71], v[176:179], v[216:219], v[68:71]
	v_mfma_f32_16x16x32_bf16 v[64:67], v[184:187], v[216:219], v[64:67]
	s_setprio 0
	s_barrier
	s_add_i32 s34, s55, s48
	v_lshl_add_u64 v[220:221], s[38:39], 0, v[136:137]
	s_mov_b32 m0, s34
	ds_read_b128 v[188:191], v158 offset:16384
	ds_read_b128 v[192:195], v158 offset:17408
	ds_read_b128 v[196:199], v158 offset:18432
	ds_read_b128 v[200:203], v158 offset:19456
	ds_read_b128 v[204:207], v158 offset:20480
	ds_read_b128 v[208:211], v158 offset:21504
	ds_read_b128 v[212:215], v158 offset:22528
	ds_read_b128 v[216:219], v158 offset:23552
	global_load_lds_dwordx4 v[220:221], off
	s_add_i32 m0, s34, 0x2000
	s_add_u32 s34, s38, 0x40000
	v_lshl_add_u64 v[222:223], s[38:39], 0, v[132:133]
	s_addc_u32 s35, s39, 0
	s_add_i32 s79, s56, s48
	global_load_lds_dwordx4 v[222:223], off
	v_lshl_add_u64 v[224:225], s[34:35], 0, v[136:137]
	s_mov_b32 m0, s79
	v_lshl_add_u64 v[226:227], s[40:41], 0, v[134:135]
	global_load_lds_dwordx4 v[224:225], off
	v_lshl_add_u64 v[224:225], s[34:35], 0, v[132:133]
	s_add_i32 m0, s79, 0x2000
	s_nop 0
	global_load_lds_dwordx4 v[224:225], off
	v_lshl_add_u64 v[224:225], s[40:41], 0, v[138:139]
	s_mov_b32 m0, s31
	s_nop 0
	global_load_lds_dwordx4 v[224:225], off
	s_mov_b32 m0, s52
	s_nop 0
	global_load_lds_dwordx4 v[226:227], off
	s_cmp_eq_u32 s58, 1
	s_cbranch_scc1 .Lmy_sw_12_1a
	s_waitcnt vmcnt(24)
	s_branch .Lmy_sw_12_1b

.Lmy_sw_12_1b:
	s_waitcnt lgkmcnt(0)
	s_barrier
	s_setprio 1
	s_waitcnt lgkmcnt(0)
	v_mfma_f32_16x16x32_bf16 v[60:63], v[148:151], v[188:191], 0
	v_mfma_f32_16x16x32_bf16 v[56:59], v[164:167], v[188:191], 0
	v_mfma_f32_16x16x32_bf16 v[44:47], v[148:151], v[196:199], 0
	v_mfma_f32_16x16x32_bf16 v[40:43], v[164:167], v[196:199], 0
	v_mfma_f32_16x16x32_bf16 v[28:31], v[148:151], v[204:207], 0
	v_mfma_f32_16x16x32_bf16 v[24:27], v[164:167], v[204:207], 0
	v_mfma_f32_16x16x32_bf16 v[12:15], v[148:151], v[212:215], 0
	v_mfma_f32_16x16x32_bf16 v[8:11], v[164:167], v[212:215], 0
	v_mfma_f32_16x16x32_bf16 v[60:63], v[160:163], v[192:195], v[60:63]
	v_mfma_f32_16x16x32_bf16 v[56:59], v[168:171], v[192:195], v[56:59]
	v_mfma_f32_16x16x32_bf16 v[44:47], v[160:163], v[200:203], v[44:47]
	v_mfma_f32_16x16x32_bf16 v[40:43], v[168:171], v[200:203], v[40:43]
	v_mfma_f32_16x16x32_bf16 v[28:31], v[160:163], v[208:211], v[28:31]
	v_mfma_f32_16x16x32_bf16 v[24:27], v[168:171], v[208:211], v[24:27]
	v_mfma_f32_16x16x32_bf16 v[12:15], v[160:163], v[216:219], v[12:15]
	v_mfma_f32_16x16x32_bf16 v[8:11], v[168:171], v[216:219], v[8:11]
	s_setprio 0
	s_setprio 1
	v_mfma_f32_16x16x32_bf16 v[52:55], v[172:175], v[188:191], 0
	v_mfma_f32_16x16x32_bf16 v[48:51], v[180:183], v[188:191], 0
	v_mfma_f32_16x16x32_bf16 v[36:39], v[172:175], v[196:199], 0
	v_mfma_f32_16x16x32_bf16 v[32:35], v[180:183], v[196:199], 0
	v_mfma_f32_16x16x32_bf16 v[20:23], v[172:175], v[204:207], 0
	v_mfma_f32_16x16x32_bf16 v[16:19], v[180:183], v[204:207], 0
	v_mfma_f32_16x16x32_bf16 v[4:7], v[172:175], v[212:215], 0
	v_mfma_f32_16x16x32_bf16 v[0:3], v[180:183], v[212:215], 0
	v_mfma_f32_16x16x32_bf16 v[52:55], v[176:179], v[192:195], v[52:55]
	v_mfma_f32_16x16x32_bf16 v[48:51], v[184:187], v[192:195], v[48:51]
	v_mfma_f32_16x16x32_bf16 v[36:39], v[176:179], v[200:203], v[36:39]
	v_mfma_f32_16x16x32_bf16 v[32:35], v[184:187], v[200:203], v[32:35]
	v_mfma_f32_16x16x32_bf16 v[20:23], v[176:179], v[208:211], v[20:23]
	v_mfma_f32_16x16x32_bf16 v[16:19], v[184:187], v[208:211], v[16:19]
	v_mfma_f32_16x16x32_bf16 v[4:7], v[176:179], v[216:219], v[4:7]
	v_mfma_f32_16x16x32_bf16 v[0:3], v[184:187], v[216:219], v[0:3]
	s_setprio 0
	s_barrier
	s_add_i32 s79, 0, 0x18000
	v_add_u32_e32 v159, s79, v152
	s_add_i32 s81, 0, 0x1c000
	ds_read_b128 v[148:151], v159
	ds_read_b128 v[160:163], v159 offset:1024
	ds_read_b128 v[164:167], v159 offset:2048
	ds_read_b128 v[168:171], v159 offset:3072
	v_add_u32_e32 v159, s81, v152
	ds_read_b128 v[172:175], v159
	ds_read_b128 v[176:179], v159 offset:1024
	ds_read_b128 v[180:183], v159 offset:2048
	ds_read_b128 v[184:187], v159 offset:3072
	s_add_u32 s34, s40, 0x40000
	s_addc_u32 s35, s41, 0
	s_mov_b32 m0, s53
	v_lshl_add_u64 v[228:229], s[34:35], 0, v[138:139]
	ds_read_b128 v[188:191], v158 offset:32768
	ds_read_b128 v[192:195], v158 offset:33792
	ds_read_b128 v[196:199], v158 offset:34816
	ds_read_b128 v[200:203], v158 offset:35840
	ds_read_b128 v[204:207], v158 offset:36864
	ds_read_b128 v[208:211], v158 offset:37888
	ds_read_b128 v[212:215], v158 offset:38912
	ds_read_b128 v[216:219], v158 offset:39936
	global_load_lds_dwordx4 v[228:229], off
	v_lshl_add_u64 v[228:229], s[34:35], 0, v[134:135]
	s_mov_b32 m0, s54
	s_nop 0
	global_load_lds_dwordx4 v[228:229], off
	s_waitcnt vmcnt(8)
	s_waitcnt lgkmcnt(0)
	s_barrier
	s_setprio 1
	s_waitcnt lgkmcnt(0)
	v_mfma_f32_16x16x32_bf16 v[124:127], v[148:151], v[188:191], v[124:127]
	v_mfma_f32_16x16x32_bf16 v[120:123], v[164:167], v[188:191], v[120:123]
	v_mfma_f32_16x16x32_bf16 v[108:111], v[148:151], v[196:199], v[108:111]
	v_mfma_f32_16x16x32_bf16 v[104:107], v[164:167], v[196:199], v[104:107]
	v_mfma_f32_16x16x32_bf16 v[92:95], v[148:151], v[204:207], v[92:95]
	v_mfma_f32_16x16x32_bf16 v[88:91], v[164:167], v[204:207], v[88:91]
	v_mfma_f32_16x16x32_bf16 v[76:79], v[148:151], v[212:215], v[76:79]
	v_mfma_f32_16x16x32_bf16 v[72:75], v[164:167], v[212:215], v[72:75]
	v_mfma_f32_16x16x32_bf16 v[124:127], v[160:163], v[192:195], v[124:127]
	v_mfma_f32_16x16x32_bf16 v[120:123], v[168:171], v[192:195], v[120:123]
	v_mfma_f32_16x16x32_bf16 v[108:111], v[160:163], v[200:203], v[108:111]
	v_mfma_f32_16x16x32_bf16 v[104:107], v[168:171], v[200:203], v[104:107]
	v_mfma_f32_16x16x32_bf16 v[92:95], v[160:163], v[208:211], v[92:95]
	v_mfma_f32_16x16x32_bf16 v[88:91], v[168:171], v[208:211], v[88:91]
	v_mfma_f32_16x16x32_bf16 v[76:79], v[160:163], v[216:219], v[76:79]
	v_mfma_f32_16x16x32_bf16 v[72:75], v[168:171], v[216:219], v[72:75]
	s_setprio 0
	s_setprio 1
	v_mfma_f32_16x16x32_bf16 v[116:119], v[172:175], v[188:191], v[116:119]
	v_mfma_f32_16x16x32_bf16 v[112:115], v[180:183], v[188:191], v[112:115]
	v_mfma_f32_16x16x32_bf16 v[100:103], v[172:175], v[196:199], v[100:103]
	v_mfma_f32_16x16x32_bf16 v[96:99], v[180:183], v[196:199], v[96:99]
	v_mfma_f32_16x16x32_bf16 v[84:87], v[172:175], v[204:207], v[84:87]
	v_mfma_f32_16x16x32_bf16 v[80:83], v[180:183], v[204:207], v[80:83]
	v_mfma_f32_16x16x32_bf16 v[68:71], v[172:175], v[212:215], v[68:71]
	v_mfma_f32_16x16x32_bf16 v[64:67], v[180:183], v[212:215], v[64:67]
	v_mfma_f32_16x16x32_bf16 v[116:119], v[176:179], v[192:195], v[116:119]
	v_mfma_f32_16x16x32_bf16 v[112:115], v[184:187], v[192:195], v[112:115]
	v_mfma_f32_16x16x32_bf16 v[100:103], v[176:179], v[200:203], v[100:103]
	v_mfma_f32_16x16x32_bf16 v[96:99], v[184:187], v[200:203], v[96:99]
	v_mfma_f32_16x16x32_bf16 v[84:87], v[176:179], v[208:211], v[84:87]
	v_mfma_f32_16x16x32_bf16 v[80:83], v[184:187], v[208:211], v[80:83]
	v_mfma_f32_16x16x32_bf16 v[68:71], v[176:179], v[216:219], v[68:71]
	v_mfma_f32_16x16x32_bf16 v[64:67], v[184:187], v[216:219], v[64:67]
	s_setprio 0
	s_barrier
	s_add_i32 s34, s79, s48
	v_lshl_add_u64 v[220:221], v[220:221], 0, s[6:7]
	s_mov_b32 m0, s34
	ds_read_b128 v[188:191], v158 offset:49152
	ds_read_b128 v[192:195], v158 offset:50176
	ds_read_b128 v[196:199], v158 offset:51200
	ds_read_b128 v[200:203], v158 offset:52224
	ds_read_b128 v[204:207], v158 offset:53248
	ds_read_b128 v[208:211], v158 offset:54272
	ds_read_b128 v[212:215], v158 offset:55296
	ds_read_b128 v[216:219], v158 offset:56320
	global_load_lds_dwordx4 v[220:221], off
	s_add_i32 m0, s34, 0x2000
	s_add_u32 s34, s38, 0x40080
	v_lshl_add_u64 v[220:221], v[222:223], 0, s[6:7]
	s_addc_u32 s35, s39, 0
	s_add_i32 s38, s81, s48
	global_load_lds_dwordx4 v[220:221], off
	v_lshl_add_u64 v[220:221], s[34:35], 0, v[136:137]
	s_mov_b32 m0, s38
	s_nop 0
	global_load_lds_dwordx4 v[220:221], off
	v_lshl_add_u64 v[220:221], s[34:35], 0, v[132:133]
	s_add_i32 m0, s38, 0x2000
	s_nop 0
	global_load_lds_dwordx4 v[220:221], off
	v_lshl_add_u64 v[220:221], v[224:225], 0, s[6:7]
	s_mov_b32 m0, s12
	s_nop 0
	global_load_lds_dwordx4 v[220:221], off
	v_lshl_add_u64 v[220:221], v[226:227], 0, s[6:7]
	s_mov_b32 m0, s13
	s_nop 0
	global_load_lds_dwordx4 v[220:221], off
	s_waitcnt vmcnt(8)
	s_waitcnt lgkmcnt(0)
	s_barrier
	s_setprio 1
	s_waitcnt lgkmcnt(0)
	v_mfma_f32_16x16x32_bf16 v[60:63], v[148:151], v[188:191], v[60:63]
	v_mfma_f32_16x16x32_bf16 v[56:59], v[164:167], v[188:191], v[56:59]
	v_mfma_f32_16x16x32_bf16 v[44:47], v[148:151], v[196:199], v[44:47]
	v_mfma_f32_16x16x32_bf16 v[40:43], v[164:167], v[196:199], v[40:43]
	v_mfma_f32_16x16x32_bf16 v[28:31], v[148:151], v[204:207], v[28:31]
	v_mfma_f32_16x16x32_bf16 v[24:27], v[164:167], v[204:207], v[24:27]
	v_mfma_f32_16x16x32_bf16 v[12:15], v[148:151], v[212:215], v[12:15]
	v_mfma_f32_16x16x32_bf16 v[8:11], v[164:167], v[212:215], v[8:11]
	v_mfma_f32_16x16x32_bf16 v[60:63], v[160:163], v[192:195], v[60:63]
	v_mfma_f32_16x16x32_bf16 v[56:59], v[168:171], v[192:195], v[56:59]
	v_mfma_f32_16x16x32_bf16 v[44:47], v[160:163], v[200:203], v[44:47]
	v_mfma_f32_16x16x32_bf16 v[40:43], v[168:171], v[200:203], v[40:43]
	v_mfma_f32_16x16x32_bf16 v[28:31], v[160:163], v[208:211], v[28:31]
	v_mfma_f32_16x16x32_bf16 v[24:27], v[168:171], v[208:211], v[24:27]
	v_mfma_f32_16x16x32_bf16 v[12:15], v[160:163], v[216:219], v[12:15]
	v_mfma_f32_16x16x32_bf16 v[8:11], v[168:171], v[216:219], v[8:11]
	s_setprio 0
	s_setprio 1
	v_mfma_f32_16x16x32_bf16 v[52:55], v[172:175], v[188:191], v[52:55]
	v_mfma_f32_16x16x32_bf16 v[48:51], v[180:183], v[188:191], v[48:51]
	v_mfma_f32_16x16x32_bf16 v[36:39], v[172:175], v[196:199], v[36:39]
	v_mfma_f32_16x16x32_bf16 v[32:35], v[180:183], v[196:199], v[32:35]
	v_mfma_f32_16x16x32_bf16 v[20:23], v[172:175], v[204:207], v[20:23]
	v_mfma_f32_16x16x32_bf16 v[16:19], v[180:183], v[204:207], v[16:19]
	v_mfma_f32_16x16x32_bf16 v[4:7], v[172:175], v[212:215], v[4:7]
	v_mfma_f32_16x16x32_bf16 v[0:3], v[180:183], v[212:215], v[0:3]
	v_mfma_f32_16x16x32_bf16 v[52:55], v[176:179], v[192:195], v[52:55]
	v_mfma_f32_16x16x32_bf16 v[48:51], v[184:187], v[192:195], v[48:51]
	v_mfma_f32_16x16x32_bf16 v[36:39], v[176:179], v[200:203], v[36:39]
	v_mfma_f32_16x16x32_bf16 v[32:35], v[184:187], v[200:203], v[32:35]
	v_mfma_f32_16x16x32_bf16 v[20:23], v[176:179], v[208:211], v[20:23]
	v_mfma_f32_16x16x32_bf16 v[16:19], v[184:187], v[208:211], v[16:19]
	v_mfma_f32_16x16x32_bf16 v[4:7], v[176:179], v[216:219], v[4:7]
	v_mfma_f32_16x16x32_bf16 v[0:3], v[184:187], v[216:219], v[0:3]
	s_setprio 0
	s_barrier
	s_add_i32 s77, s77, 2
	s_add_u32 s36, s36, 0x100
	s_addc_u32 s37, s37, 0
	s_add_u32 s66, s66, 0x100
	s_addc_u32 s67, s67, 0

.Lmy_nobar2_16:
	ds_read_b128 v[146:149], v153
	ds_read_b128 v[158:161], v153 offset:1024
	ds_read_b128 v[162:165], v153 offset:2048
	ds_read_b128 v[166:169], v153 offset:3072
	ds_read_b128 v[170:173], v154
	ds_read_b128 v[174:177], v154 offset:1024
	ds_read_b128 v[178:181], v154 offset:2048
	ds_read_b128 v[182:185], v154 offset:3072
	s_add_u32 s34, s40, 0xfffc0080
	s_addc_u32 s35, s41, -1
	s_cmp_eq_u32 s62, 12
	s_cselect_b32 s45, s12, s35
	s_cselect_b32 s44, s13, s34
	s_cselect_b32 s43, s27, s61
	s_cselect_b32 s42, s29, s39
	v_lshl_add_u64 v[218:219], s[40:41], 0, v[138:139]
	s_add_i32 m0, s48, 0xc000
	ds_read_b128 v[186:189], v155
	ds_read_b128 v[190:193], v155 offset:1024
	ds_read_b128 v[194:197], v155 offset:2048
	ds_read_b128 v[198:201], v155 offset:3072
	ds_read_b128 v[202:205], v155 offset:4096
	ds_read_b128 v[206:209], v155 offset:5120
	ds_read_b128 v[210:213], v155 offset:6144
	ds_read_b128 v[214:217], v155 offset:7168
	global_load_lds_dwordx4 v[218:219], off
	v_lshl_add_u64 v[218:219], s[40:41], 0, v[140:141]
	s_add_i32 m0, s48, 0xe000
	s_nop 0
	global_load_lds_dwordx4 v[218:219], off
	s_cmp_eq_u32 s60, 1
	s_cbranch_scc1 .Lmy_sw_16_0a
	s_waitcnt vmcnt(40)
	s_branch .Lmy_sw_16_0b

.Lmy_sw_16_0b:
	s_waitcnt lgkmcnt(0)
	s_barrier
	s_setprio 1
	s_waitcnt lgkmcnt(0)
	v_mfma_f32_16x16x32_bf16 v[124:127], v[146:149], v[186:189], 0
	v_mfma_f32_16x16x32_bf16 v[120:123], v[162:165], v[186:189], 0
	v_mfma_f32_16x16x32_bf16 v[108:111], v[146:149], v[194:197], 0
	v_mfma_f32_16x16x32_bf16 v[104:107], v[162:165], v[194:197], 0
	v_mfma_f32_16x16x32_bf16 v[92:95], v[146:149], v[202:205], 0
	v_mfma_f32_16x16x32_bf16 v[88:91], v[162:165], v[202:205], 0
	v_mfma_f32_16x16x32_bf16 v[76:79], v[146:149], v[210:213], 0
	v_mfma_f32_16x16x32_bf16 v[72:75], v[162:165], v[210:213], 0
	v_mfma_f32_16x16x32_bf16 v[124:127], v[158:161], v[190:193], v[124:127]
	v_mfma_f32_16x16x32_bf16 v[120:123], v[166:169], v[190:193], v[120:123]
	v_mfma_f32_16x16x32_bf16 v[108:111], v[158:161], v[198:201], v[108:111]
	v_mfma_f32_16x16x32_bf16 v[104:107], v[166:169], v[198:201], v[104:107]
	v_mfma_f32_16x16x32_bf16 v[92:95], v[158:161], v[206:209], v[92:95]
	v_mfma_f32_16x16x32_bf16 v[88:91], v[166:169], v[206:209], v[88:91]
	v_mfma_f32_16x16x32_bf16 v[76:79], v[158:161], v[214:217], v[76:79]
	v_mfma_f32_16x16x32_bf16 v[72:75], v[166:169], v[214:217], v[72:75]
	s_setprio 0
	s_setprio 1
	v_mfma_f32_16x16x32_bf16 v[116:119], v[170:173], v[186:189], 0
	v_mfma_f32_16x16x32_bf16 v[112:115], v[178:181], v[186:189], 0
	v_mfma_f32_16x16x32_bf16 v[100:103], v[170:173], v[194:197], 0
	v_mfma_f32_16x16x32_bf16 v[96:99], v[178:181], v[194:197], 0
	v_mfma_f32_16x16x32_bf16 v[84:87], v[170:173], v[202:205], 0
	v_mfma_f32_16x16x32_bf16 v[80:83], v[178:181], v[202:205], 0
	v_mfma_f32_16x16x32_bf16 v[68:71], v[170:173], v[210:213], 0
	v_mfma_f32_16x16x32_bf16 v[64:67], v[178:181], v[210:213], 0
	v_mfma_f32_16x16x32_bf16 v[116:119], v[174:177], v[190:193], v[116:119]
	v_mfma_f32_16x16x32_bf16 v[112:115], v[182:185], v[190:193], v[112:115]
	v_mfma_f32_16x16x32_bf16 v[100:103], v[174:177], v[198:201], v[100:103]
	v_mfma_f32_16x16x32_bf16 v[96:99], v[182:185], v[198:201], v[96:99]
	v_mfma_f32_16x16x32_bf16 v[84:87], v[174:177], v[206:209], v[84:87]
	v_mfma_f32_16x16x32_bf16 v[80:83], v[182:185], v[206:209], v[80:83]
	v_mfma_f32_16x16x32_bf16 v[68:71], v[174:177], v[214:217], v[68:71]
	v_mfma_f32_16x16x32_bf16 v[64:67], v[182:185], v[214:217], v[64:67]
	s_setprio 0
	s_barrier
	s_add_i32 s34, s58, s47
	v_lshl_add_u64 v[218:219], s[42:43], 0, v[132:133]
	s_mov_b32 m0, s34
	ds_read_b128 v[186:189], v155 offset:16384
	ds_read_b128 v[190:193], v155 offset:17408
	ds_read_b128 v[194:197], v155 offset:18432
	ds_read_b128 v[198:201], v155 offset:19456
	ds_read_b128 v[202:205], v155 offset:20480
	ds_read_b128 v[206:209], v155 offset:21504
	ds_read_b128 v[210:213], v155 offset:22528
	ds_read_b128 v[214:217], v155 offset:23552
	global_load_lds_dwordx4 v[218:219], off
	s_add_i32 m0, s34, 0x2000
	s_add_u32 s34, s42, 0x40000
	v_lshl_add_u64 v[220:221], s[42:43], 0, v[136:137]
	s_addc_u32 s35, s43, 0
	s_add_i32 s63, s59, s47
	global_load_lds_dwordx4 v[220:221], off
	v_lshl_add_u64 v[222:223], s[34:35], 0, v[132:133]
	s_mov_b32 m0, s63
	v_lshl_add_u64 v[224:225], s[44:45], 0, v[134:135]
	global_load_lds_dwordx4 v[222:223], off
	v_lshl_add_u64 v[222:223], s[34:35], 0, v[136:137]
	s_add_i32 m0, s63, 0x2000
	s_nop 0
	global_load_lds_dwordx4 v[222:223], off
	v_lshl_add_u64 v[222:223], s[44:45], 0, v[130:131]
	s_mov_b32 m0, s48
	s_nop 0
	global_load_lds_dwordx4 v[222:223], off
	s_mov_b32 m0, s49
	s_nop 0
	global_load_lds_dwordx4 v[224:225], off
	s_cmp_eq_u32 s60, 1
	s_cbranch_scc1 .Lmy_sw_16_1a
	s_waitcnt vmcnt(40)
	s_branch .Lmy_sw_16_1b

.Lmy_sw_16_1b:
	s_waitcnt lgkmcnt(0)
	s_barrier
	s_setprio 1
	s_waitcnt lgkmcnt(0)
	v_mfma_f32_16x16x32_bf16 v[60:63], v[146:149], v[186:189], 0
	v_mfma_f32_16x16x32_bf16 v[56:59], v[162:165], v[186:189], 0
	v_mfma_f32_16x16x32_bf16 v[44:47], v[146:149], v[194:197], 0
	v_mfma_f32_16x16x32_bf16 v[40:43], v[162:165], v[194:197], 0
	v_mfma_f32_16x16x32_bf16 v[28:31], v[146:149], v[202:205], 0
	v_mfma_f32_16x16x32_bf16 v[24:27], v[162:165], v[202:205], 0
	v_mfma_f32_16x16x32_bf16 v[12:15], v[146:149], v[210:213], 0
	v_mfma_f32_16x16x32_bf16 v[8:11], v[162:165], v[210:213], 0
	v_mfma_f32_16x16x32_bf16 v[60:63], v[158:161], v[190:193], v[60:63]
	v_mfma_f32_16x16x32_bf16 v[56:59], v[166:169], v[190:193], v[56:59]
	v_mfma_f32_16x16x32_bf16 v[44:47], v[158:161], v[198:201], v[44:47]
	v_mfma_f32_16x16x32_bf16 v[40:43], v[166:169], v[198:201], v[40:43]
	v_mfma_f32_16x16x32_bf16 v[28:31], v[158:161], v[206:209], v[28:31]
	v_mfma_f32_16x16x32_bf16 v[24:27], v[166:169], v[206:209], v[24:27]
	v_mfma_f32_16x16x32_bf16 v[12:15], v[158:161], v[214:217], v[12:15]
	v_mfma_f32_16x16x32_bf16 v[8:11], v[166:169], v[214:217], v[8:11]
	s_setprio 0
	s_setprio 1
	v_mfma_f32_16x16x32_bf16 v[52:55], v[170:173], v[186:189], 0
	v_mfma_f32_16x16x32_bf16 v[48:51], v[178:181], v[186:189], 0
	v_mfma_f32_16x16x32_bf16 v[36:39], v[170:173], v[194:197], 0
	v_mfma_f32_16x16x32_bf16 v[32:35], v[178:181], v[194:197], 0
	v_mfma_f32_16x16x32_bf16 v[20:23], v[170:173], v[202:205], 0
	v_mfma_f32_16x16x32_bf16 v[16:19], v[178:181], v[202:205], 0
	v_mfma_f32_16x16x32_bf16 v[4:7], v[170:173], v[210:213], 0
	v_mfma_f32_16x16x32_bf16 v[0:3], v[178:181], v[210:213], 0
	v_mfma_f32_16x16x32_bf16 v[52:55], v[174:177], v[190:193], v[52:55]
	v_mfma_f32_16x16x32_bf16 v[48:51], v[182:185], v[190:193], v[48:51]
	v_mfma_f32_16x16x32_bf16 v[36:39], v[174:177], v[198:201], v[36:39]
	v_mfma_f32_16x16x32_bf16 v[32:35], v[182:185], v[198:201], v[32:35]
	v_mfma_f32_16x16x32_bf16 v[20:23], v[174:177], v[206:209], v[20:23]
	v_mfma_f32_16x16x32_bf16 v[16:19], v[182:185], v[206:209], v[16:19]
	v_mfma_f32_16x16x32_bf16 v[4:7], v[174:177], v[214:217], v[4:7]
	v_mfma_f32_16x16x32_bf16 v[0:3], v[182:185], v[214:217], v[0:3]
	s_setprio 0
	s_barrier
	s_add_i32 s63, 0, 0x18000
	s_add_i32 s64, 0, 0x1c000
	v_add_u32_e32 v166, s63, v151
	v_add_u32_e32 v182, s64, v151
	ds_read_b128 v[146:149], v166
	ds_read_b128 v[158:161], v166 offset:1024
	ds_read_b128 v[162:165], v166 offset:2048
	ds_read_b128 v[166:169], v166 offset:3072
	ds_read_b128 v[170:173], v182
	ds_read_b128 v[174:177], v182 offset:1024
	ds_read_b128 v[178:181], v182 offset:2048
	ds_read_b128 v[182:185], v182 offset:3072
	s_add_u32 s34, s44, 0x40000
	s_addc_u32 s35, s45, 0
	s_mov_b32 m0, s50
	v_lshl_add_u64 v[226:227], s[34:35], 0, v[130:131]
	ds_read_b128 v[186:189], v155 offset:32768
	ds_read_b128 v[190:193], v155 offset:33792
	ds_read_b128 v[194:197], v155 offset:34816
	ds_read_b128 v[198:201], v155 offset:35840
	ds_read_b128 v[202:205], v155 offset:36864
	ds_read_b128 v[206:209], v155 offset:37888
	ds_read_b128 v[210:213], v155 offset:38912
	ds_read_b128 v[214:217], v155 offset:39936
	global_load_lds_dwordx4 v[226:227], off
	v_lshl_add_u64 v[226:227], s[34:35], 0, v[134:135]
	s_mov_b32 m0, s51
	s_nop 0
	global_load_lds_dwordx4 v[226:227], off
	s_waitcnt vmcnt(8)
	s_waitcnt lgkmcnt(0)
	s_barrier
	s_setprio 1
	s_waitcnt lgkmcnt(0)
	v_mfma_f32_16x16x32_bf16 v[124:127], v[146:149], v[186:189], v[124:127]
	v_mfma_f32_16x16x32_bf16 v[120:123], v[162:165], v[186:189], v[120:123]
	v_mfma_f32_16x16x32_bf16 v[108:111], v[146:149], v[194:197], v[108:111]
	v_mfma_f32_16x16x32_bf16 v[104:107], v[162:165], v[194:197], v[104:107]
	v_mfma_f32_16x16x32_bf16 v[92:95], v[146:149], v[202:205], v[92:95]
	v_mfma_f32_16x16x32_bf16 v[88:91], v[162:165], v[202:205], v[88:91]
	v_mfma_f32_16x16x32_bf16 v[76:79], v[146:149], v[210:213], v[76:79]
	v_mfma_f32_16x16x32_bf16 v[72:75], v[162:165], v[210:213], v[72:75]
	v_mfma_f32_16x16x32_bf16 v[124:127], v[158:161], v[190:193], v[124:127]
	v_mfma_f32_16x16x32_bf16 v[120:123], v[166:169], v[190:193], v[120:123]
	v_mfma_f32_16x16x32_bf16 v[108:111], v[158:161], v[198:201], v[108:111]
	v_mfma_f32_16x16x32_bf16 v[104:107], v[166:169], v[198:201], v[104:107]
	v_mfma_f32_16x16x32_bf16 v[92:95], v[158:161], v[206:209], v[92:95]
	v_mfma_f32_16x16x32_bf16 v[88:91], v[166:169], v[206:209], v[88:91]
	v_mfma_f32_16x16x32_bf16 v[76:79], v[158:161], v[214:217], v[76:79]
	v_mfma_f32_16x16x32_bf16 v[72:75], v[166:169], v[214:217], v[72:75]
	s_setprio 0
	s_setprio 1
	v_mfma_f32_16x16x32_bf16 v[116:119], v[170:173], v[186:189], v[116:119]
	v_mfma_f32_16x16x32_bf16 v[112:115], v[178:181], v[186:189], v[112:115]
	v_mfma_f32_16x16x32_bf16 v[100:103], v[170:173], v[194:197], v[100:103]
	v_mfma_f32_16x16x32_bf16 v[96:99], v[178:181], v[194:197], v[96:99]
	v_mfma_f32_16x16x32_bf16 v[84:87], v[170:173], v[202:205], v[84:87]
	v_mfma_f32_16x16x32_bf16 v[80:83], v[178:181], v[202:205], v[80:83]
	v_mfma_f32_16x16x32_bf16 v[68:71], v[170:173], v[210:213], v[68:71]
	v_mfma_f32_16x16x32_bf16 v[64:67], v[178:181], v[210:213], v[64:67]
	v_mfma_f32_16x16x32_bf16 v[116:119], v[174:177], v[190:193], v[116:119]
	v_mfma_f32_16x16x32_bf16 v[112:115], v[182:185], v[190:193], v[112:115]
	v_mfma_f32_16x16x32_bf16 v[100:103], v[174:177], v[198:201], v[100:103]
	v_mfma_f32_16x16x32_bf16 v[96:99], v[182:185], v[198:201], v[96:99]
	v_mfma_f32_16x16x32_bf16 v[84:87], v[174:177], v[206:209], v[84:87]
	v_mfma_f32_16x16x32_bf16 v[80:83], v[182:185], v[206:209], v[80:83]
	v_mfma_f32_16x16x32_bf16 v[68:71], v[174:177], v[214:217], v[68:71]
	v_mfma_f32_16x16x32_bf16 v[64:67], v[182:185], v[214:217], v[64:67]
	s_setprio 0
	s_barrier
	s_add_i32 s34, s63, s47
	v_lshl_add_u64 v[218:219], v[218:219], 0, s[10:11]
	s_mov_b32 m0, s34
	ds_read_b128 v[186:189], v155 offset:49152
	ds_read_b128 v[190:193], v155 offset:50176
	ds_read_b128 v[194:197], v155 offset:51200
	ds_read_b128 v[198:201], v155 offset:52224
	ds_read_b128 v[202:205], v155 offset:53248
	ds_read_b128 v[206:209], v155 offset:54272
	ds_read_b128 v[210:213], v155 offset:55296
	ds_read_b128 v[214:217], v155 offset:56320
	global_load_lds_dwordx4 v[218:219], off
	s_add_i32 m0, s34, 0x2000
	s_add_u32 s34, s42, 0x40080
	v_lshl_add_u64 v[218:219], v[220:221], 0, s[10:11]
	s_addc_u32 s35, s43, 0
	s_add_i32 s42, s64, s47
	global_load_lds_dwordx4 v[218:219], off
	v_lshl_add_u64 v[218:219], s[34:35], 0, v[132:133]
	s_mov_b32 m0, s42
	s_nop 0
	global_load_lds_dwordx4 v[218:219], off
	v_lshl_add_u64 v[218:219], s[34:35], 0, v[136:137]
	s_add_i32 m0, s42, 0x2000
	s_nop 0
	global_load_lds_dwordx4 v[218:219], off
	v_lshl_add_u64 v[218:219], v[222:223], 0, s[10:11]
	s_mov_b32 m0, s53
	s_nop 0
	global_load_lds_dwordx4 v[218:219], off
	v_lshl_add_u64 v[218:219], v[224:225], 0, s[10:11]
	s_mov_b32 m0, s54
	s_nop 0
	global_load_lds_dwordx4 v[218:219], off
	s_waitcnt vmcnt(8)
	s_waitcnt lgkmcnt(0)
	s_barrier
	s_setprio 1
	s_waitcnt lgkmcnt(0)
	v_mfma_f32_16x16x32_bf16 v[60:63], v[146:149], v[186:189], v[60:63]
	v_mfma_f32_16x16x32_bf16 v[56:59], v[162:165], v[186:189], v[56:59]
	v_mfma_f32_16x16x32_bf16 v[44:47], v[146:149], v[194:197], v[44:47]
	v_mfma_f32_16x16x32_bf16 v[40:43], v[162:165], v[194:197], v[40:43]
	v_mfma_f32_16x16x32_bf16 v[28:31], v[146:149], v[202:205], v[28:31]
	v_mfma_f32_16x16x32_bf16 v[24:27], v[162:165], v[202:205], v[24:27]
	v_mfma_f32_16x16x32_bf16 v[12:15], v[146:149], v[210:213], v[12:15]
	v_mfma_f32_16x16x32_bf16 v[8:11], v[162:165], v[210:213], v[8:11]
	v_mfma_f32_16x16x32_bf16 v[60:63], v[158:161], v[190:193], v[60:63]
	v_mfma_f32_16x16x32_bf16 v[56:59], v[166:169], v[190:193], v[56:59]
	v_mfma_f32_16x16x32_bf16 v[44:47], v[158:161], v[198:201], v[44:47]
	v_mfma_f32_16x16x32_bf16 v[40:43], v[166:169], v[198:201], v[40:43]
	v_mfma_f32_16x16x32_bf16 v[28:31], v[158:161], v[206:209], v[28:31]
	v_mfma_f32_16x16x32_bf16 v[24:27], v[166:169], v[206:209], v[24:27]
	v_mfma_f32_16x16x32_bf16 v[12:15], v[158:161], v[214:217], v[12:15]
	v_mfma_f32_16x16x32_bf16 v[8:11], v[166:169], v[214:217], v[8:11]
	s_setprio 0
	s_setprio 1
	v_mfma_f32_16x16x32_bf16 v[52:55], v[170:173], v[186:189], v[52:55]
	v_mfma_f32_16x16x32_bf16 v[48:51], v[178:181], v[186:189], v[48:51]
	v_mfma_f32_16x16x32_bf16 v[36:39], v[170:173], v[194:197], v[36:39]
	v_mfma_f32_16x16x32_bf16 v[32:35], v[178:181], v[194:197], v[32:35]
	v_mfma_f32_16x16x32_bf16 v[20:23], v[170:173], v[202:205], v[20:23]
	v_mfma_f32_16x16x32_bf16 v[16:19], v[178:181], v[202:205], v[16:19]
	v_mfma_f32_16x16x32_bf16 v[4:7], v[170:173], v[210:213], v[4:7]
	v_mfma_f32_16x16x32_bf16 v[0:3], v[178:181], v[210:213], v[0:3]
	v_mfma_f32_16x16x32_bf16 v[52:55], v[174:177], v[190:193], v[52:55]
	v_mfma_f32_16x16x32_bf16 v[48:51], v[182:185], v[190:193], v[48:51]
	v_mfma_f32_16x16x32_bf16 v[36:39], v[174:177], v[198:201], v[36:39]
	v_mfma_f32_16x16x32_bf16 v[32:35], v[182:185], v[198:201], v[32:35]
	v_mfma_f32_16x16x32_bf16 v[20:23], v[174:177], v[206:209], v[20:23]
	v_mfma_f32_16x16x32_bf16 v[16:19], v[182:185], v[206:209], v[16:19]
	v_mfma_f32_16x16x32_bf16 v[4:7], v[174:177], v[214:217], v[4:7]
	v_mfma_f32_16x16x32_bf16 v[0:3], v[182:185], v[214:217], v[0:3]
	s_setprio 0
	s_barrier
	s_add_i32 s62, s62, 2
	s_add_u32 s40, s40, 0x100
	s_addc_u32 s41, s41, 0
	s_add_u32 s39, s39, 0x100
	s_addc_u32 s61, s61, 0

.Lmy_nobar2_17:
	ds_read_b128 v[146:149], v154
	ds_read_b128 v[158:161], v154 offset:1024
	ds_read_b128 v[162:165], v154 offset:2048
	ds_read_b128 v[166:169], v154 offset:3072
	ds_read_b128 v[170:173], v155
	ds_read_b128 v[174:177], v155 offset:1024
	ds_read_b128 v[178:181], v155 offset:2048
	ds_read_b128 v[182:185], v155 offset:3072
	s_add_u32 s34, s36, 0xfffc0080
	s_addc_u32 s35, s37, -1
	s_cmp_eq_u32 s62, 12
	s_cselect_b32 s41, s23, s35
	s_cselect_b32 s40, s58, s34
	s_cselect_b32 s39, s11, s61
	s_cselect_b32 s38, s59, s60
	v_lshl_add_u64 v[218:219], s[36:37], 0, v[138:139]
	s_add_i32 m0, s31, 0xc000
	ds_read_b128 v[186:189], v157
	ds_read_b128 v[190:193], v157 offset:1024
	ds_read_b128 v[194:197], v157 offset:2048
	ds_read_b128 v[198:201], v157 offset:3072
	ds_read_b128 v[202:205], v157 offset:4096
	ds_read_b128 v[206:209], v157 offset:5120
	ds_read_b128 v[210:213], v157 offset:6144
	ds_read_b128 v[214:217], v157 offset:7168
	global_load_lds_dwordx4 v[218:219], off
	v_lshl_add_u64 v[218:219], s[36:37], 0, v[140:141]
	s_add_i32 m0, s31, 0xe000
	s_nop 0
	global_load_lds_dwordx4 v[218:219], off
	s_cmp_eq_u32 s56, 1
	s_cbranch_scc1 .Lmy_sw_17_0a
	s_waitcnt vmcnt(16)
	s_branch .Lmy_sw_17_0b

.Lmy_sw_17_0b:
	s_waitcnt lgkmcnt(0)
	s_barrier
	s_setprio 1
	s_waitcnt lgkmcnt(0)
	v_mfma_f32_16x16x32_bf16 v[124:127], v[146:149], v[186:189], 0
	v_mfma_f32_16x16x32_bf16 v[120:123], v[162:165], v[186:189], 0
	v_mfma_f32_16x16x32_bf16 v[108:111], v[146:149], v[194:197], 0
	v_mfma_f32_16x16x32_bf16 v[104:107], v[162:165], v[194:197], 0
	v_mfma_f32_16x16x32_bf16 v[92:95], v[146:149], v[202:205], 0
	v_mfma_f32_16x16x32_bf16 v[88:91], v[162:165], v[202:205], 0
	v_mfma_f32_16x16x32_bf16 v[76:79], v[146:149], v[210:213], 0
	v_mfma_f32_16x16x32_bf16 v[72:75], v[162:165], v[210:213], 0
	v_mfma_f32_16x16x32_bf16 v[124:127], v[158:161], v[190:193], v[124:127]
	v_mfma_f32_16x16x32_bf16 v[120:123], v[166:169], v[190:193], v[120:123]
	v_mfma_f32_16x16x32_bf16 v[108:111], v[158:161], v[198:201], v[108:111]
	v_mfma_f32_16x16x32_bf16 v[104:107], v[166:169], v[198:201], v[104:107]
	v_mfma_f32_16x16x32_bf16 v[92:95], v[158:161], v[206:209], v[92:95]
	v_mfma_f32_16x16x32_bf16 v[88:91], v[166:169], v[206:209], v[88:91]
	v_mfma_f32_16x16x32_bf16 v[76:79], v[158:161], v[214:217], v[76:79]
	v_mfma_f32_16x16x32_bf16 v[72:75], v[166:169], v[214:217], v[72:75]
	s_setprio 0
	s_setprio 1
	v_mfma_f32_16x16x32_bf16 v[116:119], v[170:173], v[186:189], 0
	v_mfma_f32_16x16x32_bf16 v[112:115], v[178:181], v[186:189], 0
	v_mfma_f32_16x16x32_bf16 v[100:103], v[170:173], v[194:197], 0
	v_mfma_f32_16x16x32_bf16 v[96:99], v[178:181], v[194:197], 0
	v_mfma_f32_16x16x32_bf16 v[84:87], v[170:173], v[202:205], 0
	v_mfma_f32_16x16x32_bf16 v[80:83], v[178:181], v[202:205], 0
	v_mfma_f32_16x16x32_bf16 v[68:71], v[170:173], v[210:213], 0
	v_mfma_f32_16x16x32_bf16 v[64:67], v[178:181], v[210:213], 0
	v_mfma_f32_16x16x32_bf16 v[116:119], v[174:177], v[190:193], v[116:119]
	v_mfma_f32_16x16x32_bf16 v[112:115], v[182:185], v[190:193], v[112:115]
	v_mfma_f32_16x16x32_bf16 v[100:103], v[174:177], v[198:201], v[100:103]
	v_mfma_f32_16x16x32_bf16 v[96:99], v[182:185], v[198:201], v[96:99]
	v_mfma_f32_16x16x32_bf16 v[84:87], v[174:177], v[206:209], v[84:87]
	v_mfma_f32_16x16x32_bf16 v[80:83], v[182:185], v[206:209], v[80:83]
	v_mfma_f32_16x16x32_bf16 v[68:71], v[174:177], v[214:217], v[68:71]
	v_mfma_f32_16x16x32_bf16 v[64:67], v[182:185], v[214:217], v[64:67]
	s_setprio 0
	s_barrier
	s_add_i32 s34, s53, s44
	v_lshl_add_u64 v[218:219], s[38:39], 0, v[134:135]
	s_mov_b32 m0, s34
	ds_read_b128 v[186:189], v157 offset:16384
	ds_read_b128 v[190:193], v157 offset:17408
	ds_read_b128 v[194:197], v157 offset:18432
	ds_read_b128 v[198:201], v157 offset:19456
	ds_read_b128 v[202:205], v157 offset:20480
	ds_read_b128 v[206:209], v157 offset:21504
	ds_read_b128 v[210:213], v157 offset:22528
	ds_read_b128 v[214:217], v157 offset:23552
	global_load_lds_dwordx4 v[218:219], off
	s_add_i32 m0, s34, 0x2000
	s_add_u32 s34, s38, 0x40000
	v_lshl_add_u64 v[220:221], s[38:39], 0, v[130:131]
	s_addc_u32 s35, s39, 0
	s_add_i32 s63, s54, s44
	global_load_lds_dwordx4 v[220:221], off
	v_lshl_add_u64 v[222:223], s[34:35], 0, v[134:135]
	s_mov_b32 m0, s63
	v_lshl_add_u64 v[224:225], s[40:41], 0, v[132:133]
	global_load_lds_dwordx4 v[222:223], off
	v_lshl_add_u64 v[222:223], s[34:35], 0, v[130:131]
	s_add_i32 m0, s63, 0x2000
	s_nop 0
	global_load_lds_dwordx4 v[222:223], off
	v_lshl_add_u64 v[222:223], s[40:41], 0, v[136:137]
	s_mov_b32 m0, s31
	s_nop 0
	global_load_lds_dwordx4 v[222:223], off
	s_mov_b32 m0, s48
	s_nop 0
	global_load_lds_dwordx4 v[224:225], off
	s_cmp_eq_u32 s56, 1
	s_cbranch_scc1 .Lmy_sw_17_1a
	s_waitcnt vmcnt(16)
	s_branch .Lmy_sw_17_1b

.Lmy_sw_17_1b:
	s_waitcnt lgkmcnt(0)
	s_barrier
	s_setprio 1
	s_waitcnt lgkmcnt(0)
	v_mfma_f32_16x16x32_bf16 v[60:63], v[146:149], v[186:189], 0
	v_mfma_f32_16x16x32_bf16 v[56:59], v[162:165], v[186:189], 0
	v_mfma_f32_16x16x32_bf16 v[44:47], v[146:149], v[194:197], 0
	v_mfma_f32_16x16x32_bf16 v[40:43], v[162:165], v[194:197], 0
	v_mfma_f32_16x16x32_bf16 v[28:31], v[146:149], v[202:205], 0
	v_mfma_f32_16x16x32_bf16 v[24:27], v[162:165], v[202:205], 0
	v_mfma_f32_16x16x32_bf16 v[12:15], v[146:149], v[210:213], 0
	v_mfma_f32_16x16x32_bf16 v[8:11], v[162:165], v[210:213], 0
	v_mfma_f32_16x16x32_bf16 v[60:63], v[158:161], v[190:193], v[60:63]
	v_mfma_f32_16x16x32_bf16 v[56:59], v[166:169], v[190:193], v[56:59]
	v_mfma_f32_16x16x32_bf16 v[44:47], v[158:161], v[198:201], v[44:47]
	v_mfma_f32_16x16x32_bf16 v[40:43], v[166:169], v[198:201], v[40:43]
	v_mfma_f32_16x16x32_bf16 v[28:31], v[158:161], v[206:209], v[28:31]
	v_mfma_f32_16x16x32_bf16 v[24:27], v[166:169], v[206:209], v[24:27]
	v_mfma_f32_16x16x32_bf16 v[12:15], v[158:161], v[214:217], v[12:15]
	v_mfma_f32_16x16x32_bf16 v[8:11], v[166:169], v[214:217], v[8:11]
	s_setprio 0
	s_setprio 1
	v_mfma_f32_16x16x32_bf16 v[52:55], v[170:173], v[186:189], 0
	v_mfma_f32_16x16x32_bf16 v[48:51], v[178:181], v[186:189], 0
	v_mfma_f32_16x16x32_bf16 v[36:39], v[170:173], v[194:197], 0
	v_mfma_f32_16x16x32_bf16 v[32:35], v[178:181], v[194:197], 0
	v_mfma_f32_16x16x32_bf16 v[20:23], v[170:173], v[202:205], 0
	v_mfma_f32_16x16x32_bf16 v[16:19], v[178:181], v[202:205], 0
	v_mfma_f32_16x16x32_bf16 v[4:7], v[170:173], v[210:213], 0
	v_mfma_f32_16x16x32_bf16 v[0:3], v[178:181], v[210:213], 0
	v_mfma_f32_16x16x32_bf16 v[52:55], v[174:177], v[190:193], v[52:55]
	v_mfma_f32_16x16x32_bf16 v[48:51], v[182:185], v[190:193], v[48:51]
	v_mfma_f32_16x16x32_bf16 v[36:39], v[174:177], v[198:201], v[36:39]
	v_mfma_f32_16x16x32_bf16 v[32:35], v[182:185], v[198:201], v[32:35]
	v_mfma_f32_16x16x32_bf16 v[20:23], v[174:177], v[206:209], v[20:23]
	v_mfma_f32_16x16x32_bf16 v[16:19], v[182:185], v[206:209], v[16:19]
	v_mfma_f32_16x16x32_bf16 v[4:7], v[174:177], v[214:217], v[4:7]
	v_mfma_f32_16x16x32_bf16 v[0:3], v[182:185], v[214:217], v[0:3]
	s_setprio 0
	s_barrier
	s_add_i32 s63, 0, 0x18000
	s_add_i32 s64, 0, 0x1c000
	v_add_u32_e32 v166, s63, v151
	v_add_u32_e32 v182, s64, v151
	ds_read_b128 v[146:149], v166
	ds_read_b128 v[158:161], v166 offset:1024
	ds_read_b128 v[162:165], v166 offset:2048
	ds_read_b128 v[166:169], v166 offset:3072
	ds_read_b128 v[170:173], v182
	ds_read_b128 v[174:177], v182 offset:1024
	ds_read_b128 v[178:181], v182 offset:2048
	ds_read_b128 v[182:185], v182 offset:3072
	s_add_u32 s34, s40, 0x40000
	s_addc_u32 s35, s41, 0
	s_mov_b32 m0, s49
	v_lshl_add_u64 v[226:227], s[34:35], 0, v[136:137]
	ds_read_b128 v[186:189], v157 offset:32768
	ds_read_b128 v[190:193], v157 offset:33792
	ds_read_b128 v[194:197], v157 offset:34816
	ds_read_b128 v[198:201], v157 offset:35840
	ds_read_b128 v[202:205], v157 offset:36864
	ds_read_b128 v[206:209], v157 offset:37888
	ds_read_b128 v[210:213], v157 offset:38912
	ds_read_b128 v[214:217], v157 offset:39936
	global_load_lds_dwordx4 v[226:227], off
	v_lshl_add_u64 v[226:227], s[34:35], 0, v[132:133]
	s_mov_b32 m0, s50
	s_nop 0
	global_load_lds_dwordx4 v[226:227], off
	s_waitcnt vmcnt(8)
	s_waitcnt lgkmcnt(0)
	s_barrier
	s_setprio 1
	s_waitcnt lgkmcnt(0)
	v_mfma_f32_16x16x32_bf16 v[124:127], v[146:149], v[186:189], v[124:127]
	v_mfma_f32_16x16x32_bf16 v[120:123], v[162:165], v[186:189], v[120:123]
	v_mfma_f32_16x16x32_bf16 v[108:111], v[146:149], v[194:197], v[108:111]
	v_mfma_f32_16x16x32_bf16 v[104:107], v[162:165], v[194:197], v[104:107]
	v_mfma_f32_16x16x32_bf16 v[92:95], v[146:149], v[202:205], v[92:95]
	v_mfma_f32_16x16x32_bf16 v[88:91], v[162:165], v[202:205], v[88:91]
	v_mfma_f32_16x16x32_bf16 v[76:79], v[146:149], v[210:213], v[76:79]
	v_mfma_f32_16x16x32_bf16 v[72:75], v[162:165], v[210:213], v[72:75]
	v_mfma_f32_16x16x32_bf16 v[124:127], v[158:161], v[190:193], v[124:127]
	v_mfma_f32_16x16x32_bf16 v[120:123], v[166:169], v[190:193], v[120:123]
	v_mfma_f32_16x16x32_bf16 v[108:111], v[158:161], v[198:201], v[108:111]
	v_mfma_f32_16x16x32_bf16 v[104:107], v[166:169], v[198:201], v[104:107]
	v_mfma_f32_16x16x32_bf16 v[92:95], v[158:161], v[206:209], v[92:95]
	v_mfma_f32_16x16x32_bf16 v[88:91], v[166:169], v[206:209], v[88:91]
	v_mfma_f32_16x16x32_bf16 v[76:79], v[158:161], v[214:217], v[76:79]
	v_mfma_f32_16x16x32_bf16 v[72:75], v[166:169], v[214:217], v[72:75]
	s_setprio 0
	s_setprio 1
	v_mfma_f32_16x16x32_bf16 v[116:119], v[170:173], v[186:189], v[116:119]
	v_mfma_f32_16x16x32_bf16 v[112:115], v[178:181], v[186:189], v[112:115]
	v_mfma_f32_16x16x32_bf16 v[100:103], v[170:173], v[194:197], v[100:103]
	v_mfma_f32_16x16x32_bf16 v[96:99], v[178:181], v[194:197], v[96:99]
	v_mfma_f32_16x16x32_bf16 v[84:87], v[170:173], v[202:205], v[84:87]
	v_mfma_f32_16x16x32_bf16 v[80:83], v[178:181], v[202:205], v[80:83]
	v_mfma_f32_16x16x32_bf16 v[68:71], v[170:173], v[210:213], v[68:71]
	v_mfma_f32_16x16x32_bf16 v[64:67], v[178:181], v[210:213], v[64:67]
	v_mfma_f32_16x16x32_bf16 v[116:119], v[174:177], v[190:193], v[116:119]
	v_mfma_f32_16x16x32_bf16 v[112:115], v[182:185], v[190:193], v[112:115]
	v_mfma_f32_16x16x32_bf16 v[100:103], v[174:177], v[198:201], v[100:103]
	v_mfma_f32_16x16x32_bf16 v[96:99], v[182:185], v[198:201], v[96:99]
	v_mfma_f32_16x16x32_bf16 v[84:87], v[174:177], v[206:209], v[84:87]
	v_mfma_f32_16x16x32_bf16 v[80:83], v[182:185], v[206:209], v[80:83]
	v_mfma_f32_16x16x32_bf16 v[68:71], v[174:177], v[214:217], v[68:71]
	v_mfma_f32_16x16x32_bf16 v[64:67], v[182:185], v[214:217], v[64:67]
	s_setprio 0
	s_barrier
	s_add_i32 s34, s63, s44
	v_lshl_add_u64 v[218:219], v[218:219], 0, s[6:7]
	s_mov_b32 m0, s34
	ds_read_b128 v[186:189], v157 offset:49152
	ds_read_b128 v[190:193], v157 offset:50176
	ds_read_b128 v[194:197], v157 offset:51200
	ds_read_b128 v[198:201], v157 offset:52224
	ds_read_b128 v[202:205], v157 offset:53248
	ds_read_b128 v[206:209], v157 offset:54272
	ds_read_b128 v[210:213], v157 offset:55296
	ds_read_b128 v[214:217], v157 offset:56320
	global_load_lds_dwordx4 v[218:219], off
	s_add_i32 m0, s34, 0x2000
	s_add_u32 s34, s38, 0x40080
	v_lshl_add_u64 v[218:219], v[220:221], 0, s[6:7]
	s_addc_u32 s35, s39, 0
	s_add_i32 s38, s64, s44
	global_load_lds_dwordx4 v[218:219], off
	v_lshl_add_u64 v[218:219], s[34:35], 0, v[134:135]
	s_mov_b32 m0, s38
	s_nop 0
	global_load_lds_dwordx4 v[218:219], off
	v_lshl_add_u64 v[218:219], s[34:35], 0, v[130:131]
	s_add_i32 m0, s38, 0x2000
	s_nop 0
	global_load_lds_dwordx4 v[218:219], off
	v_lshl_add_u64 v[218:219], v[222:223], 0, s[6:7]
	s_mov_b32 m0, s51
	s_nop 0
	global_load_lds_dwordx4 v[218:219], off
	v_lshl_add_u64 v[218:219], v[224:225], 0, s[6:7]
	s_mov_b32 m0, s52
	s_nop 0
	global_load_lds_dwordx4 v[218:219], off
	s_waitcnt vmcnt(8)
	s_waitcnt lgkmcnt(0)
	s_barrier
	s_setprio 1
	s_waitcnt lgkmcnt(0)
	v_mfma_f32_16x16x32_bf16 v[60:63], v[146:149], v[186:189], v[60:63]
	v_mfma_f32_16x16x32_bf16 v[56:59], v[162:165], v[186:189], v[56:59]
	v_mfma_f32_16x16x32_bf16 v[44:47], v[146:149], v[194:197], v[44:47]
	v_mfma_f32_16x16x32_bf16 v[40:43], v[162:165], v[194:197], v[40:43]
	v_mfma_f32_16x16x32_bf16 v[28:31], v[146:149], v[202:205], v[28:31]
	v_mfma_f32_16x16x32_bf16 v[24:27], v[162:165], v[202:205], v[24:27]
	v_mfma_f32_16x16x32_bf16 v[12:15], v[146:149], v[210:213], v[12:15]
	v_mfma_f32_16x16x32_bf16 v[8:11], v[162:165], v[210:213], v[8:11]
	v_mfma_f32_16x16x32_bf16 v[60:63], v[158:161], v[190:193], v[60:63]
	v_mfma_f32_16x16x32_bf16 v[56:59], v[166:169], v[190:193], v[56:59]
	v_mfma_f32_16x16x32_bf16 v[44:47], v[158:161], v[198:201], v[44:47]
	v_mfma_f32_16x16x32_bf16 v[40:43], v[166:169], v[198:201], v[40:43]
	v_mfma_f32_16x16x32_bf16 v[28:31], v[158:161], v[206:209], v[28:31]
	v_mfma_f32_16x16x32_bf16 v[24:27], v[166:169], v[206:209], v[24:27]
	v_mfma_f32_16x16x32_bf16 v[12:15], v[158:161], v[214:217], v[12:15]
	v_mfma_f32_16x16x32_bf16 v[8:11], v[166:169], v[214:217], v[8:11]
	s_setprio 0
	s_setprio 1
	v_mfma_f32_16x16x32_bf16 v[52:55], v[170:173], v[186:189], v[52:55]
	v_mfma_f32_16x16x32_bf16 v[48:51], v[178:181], v[186:189], v[48:51]
	v_mfma_f32_16x16x32_bf16 v[36:39], v[170:173], v[194:197], v[36:39]
	v_mfma_f32_16x16x32_bf16 v[32:35], v[178:181], v[194:197], v[32:35]
	v_mfma_f32_16x16x32_bf16 v[20:23], v[170:173], v[202:205], v[20:23]
	v_mfma_f32_16x16x32_bf16 v[16:19], v[178:181], v[202:205], v[16:19]
	v_mfma_f32_16x16x32_bf16 v[4:7], v[170:173], v[210:213], v[4:7]
	v_mfma_f32_16x16x32_bf16 v[0:3], v[178:181], v[210:213], v[0:3]
	v_mfma_f32_16x16x32_bf16 v[52:55], v[174:177], v[190:193], v[52:55]
	v_mfma_f32_16x16x32_bf16 v[48:51], v[182:185], v[190:193], v[48:51]
	v_mfma_f32_16x16x32_bf16 v[36:39], v[174:177], v[198:201], v[36:39]
	v_mfma_f32_16x16x32_bf16 v[32:35], v[182:185], v[198:201], v[32:35]
	v_mfma_f32_16x16x32_bf16 v[20:23], v[174:177], v[206:209], v[20:23]
	v_mfma_f32_16x16x32_bf16 v[16:19], v[182:185], v[206:209], v[16:19]
	v_mfma_f32_16x16x32_bf16 v[4:7], v[174:177], v[214:217], v[4:7]
	v_mfma_f32_16x16x32_bf16 v[0:3], v[182:185], v[214:217], v[0:3]
	s_setprio 0
	s_barrier
	s_add_i32 s62, s62, 2
	s_add_u32 s36, s36, 0x100
	s_addc_u32 s37, s37, 0
	s_add_u32 s60, s60, 0x100
	s_addc_u32 s61, s61, 0

.Lmy_nobar2_18:
	ds_read_b128 v[146:149], v153
	ds_read_b128 v[158:161], v153 offset:1024
	ds_read_b128 v[162:165], v153 offset:2048
	ds_read_b128 v[166:169], v153 offset:3072
	ds_read_b128 v[170:173], v154
	ds_read_b128 v[174:177], v154 offset:1024
	ds_read_b128 v[178:181], v154 offset:2048
	ds_read_b128 v[182:185], v154 offset:3072
	s_add_u32 s34, s30, 0xfff50080
	s_addc_u32 s35, s31, -1
	s_cmp_eq_u32 s58, 40
	s_cselect_b32 s39, s1, s35
	s_cselect_b32 s38, s0, s34
	s_cselect_b32 s37, s29, s57
	s_cselect_b32 s36, s28, s13
	v_lshl_add_u64 v[218:219], s[30:31], 0, v[138:139]
	s_add_i32 m0, s42, 0xc000
	ds_read_b128 v[186:189], v155
	ds_read_b128 v[190:193], v155 offset:1024
	ds_read_b128 v[194:197], v155 offset:2048
	ds_read_b128 v[198:201], v155 offset:3072
	ds_read_b128 v[202:205], v155 offset:4096
	ds_read_b128 v[206:209], v155 offset:5120
	ds_read_b128 v[210:213], v155 offset:6144
	ds_read_b128 v[214:217], v155 offset:7168
	global_load_lds_dwordx4 v[218:219], off
	v_lshl_add_u64 v[218:219], s[30:31], 0, v[140:141]
	s_add_i32 m0, s42, 0xe000
	s_nop 0
	global_load_lds_dwordx4 v[218:219], off
	s_cmp_eq_u32 s54, 1
	s_cbranch_scc1 .Lmy_sw_18_0a
	s_waitcnt vmcnt(40)
	s_branch .Lmy_sw_18_0b

.Lmy_sw_18_0b:
	s_waitcnt lgkmcnt(0)
	s_barrier
	s_setprio 1
	s_waitcnt lgkmcnt(0)
	v_mfma_f32_16x16x32_bf16 v[124:127], v[146:149], v[186:189], 0
	v_mfma_f32_16x16x32_bf16 v[120:123], v[162:165], v[186:189], 0
	v_mfma_f32_16x16x32_bf16 v[108:111], v[146:149], v[194:197], 0
	v_mfma_f32_16x16x32_bf16 v[104:107], v[162:165], v[194:197], 0
	v_mfma_f32_16x16x32_bf16 v[92:95], v[146:149], v[202:205], 0
	v_mfma_f32_16x16x32_bf16 v[88:91], v[162:165], v[202:205], 0
	v_mfma_f32_16x16x32_bf16 v[76:79], v[146:149], v[210:213], 0
	v_mfma_f32_16x16x32_bf16 v[72:75], v[162:165], v[210:213], 0
	v_mfma_f32_16x16x32_bf16 v[124:127], v[158:161], v[190:193], v[124:127]
	v_mfma_f32_16x16x32_bf16 v[120:123], v[166:169], v[190:193], v[120:123]
	v_mfma_f32_16x16x32_bf16 v[108:111], v[158:161], v[198:201], v[108:111]
	v_mfma_f32_16x16x32_bf16 v[104:107], v[166:169], v[198:201], v[104:107]
	v_mfma_f32_16x16x32_bf16 v[92:95], v[158:161], v[206:209], v[92:95]
	v_mfma_f32_16x16x32_bf16 v[88:91], v[166:169], v[206:209], v[88:91]
	v_mfma_f32_16x16x32_bf16 v[76:79], v[158:161], v[214:217], v[76:79]
	v_mfma_f32_16x16x32_bf16 v[72:75], v[166:169], v[214:217], v[72:75]
	s_setprio 0
	s_setprio 1
	v_mfma_f32_16x16x32_bf16 v[116:119], v[170:173], v[186:189], 0
	v_mfma_f32_16x16x32_bf16 v[112:115], v[178:181], v[186:189], 0
	v_mfma_f32_16x16x32_bf16 v[100:103], v[170:173], v[194:197], 0
	v_mfma_f32_16x16x32_bf16 v[96:99], v[178:181], v[194:197], 0
	v_mfma_f32_16x16x32_bf16 v[84:87], v[170:173], v[202:205], 0
	v_mfma_f32_16x16x32_bf16 v[80:83], v[178:181], v[202:205], 0
	v_mfma_f32_16x16x32_bf16 v[68:71], v[170:173], v[210:213], 0
	v_mfma_f32_16x16x32_bf16 v[64:67], v[178:181], v[210:213], 0
	v_mfma_f32_16x16x32_bf16 v[116:119], v[174:177], v[190:193], v[116:119]
	v_mfma_f32_16x16x32_bf16 v[112:115], v[182:185], v[190:193], v[112:115]
	v_mfma_f32_16x16x32_bf16 v[100:103], v[174:177], v[198:201], v[100:103]
	v_mfma_f32_16x16x32_bf16 v[96:99], v[182:185], v[198:201], v[96:99]
	v_mfma_f32_16x16x32_bf16 v[84:87], v[174:177], v[206:209], v[84:87]
	v_mfma_f32_16x16x32_bf16 v[80:83], v[182:185], v[206:209], v[80:83]
	v_mfma_f32_16x16x32_bf16 v[68:71], v[174:177], v[214:217], v[68:71]
	v_mfma_f32_16x16x32_bf16 v[64:67], v[182:185], v[214:217], v[64:67]
	s_setprio 0
	s_barrier
	s_add_i32 s34, s52, s41
	v_lshl_add_u64 v[218:219], s[36:37], 0, v[132:133]
	s_mov_b32 m0, s34
	ds_read_b128 v[186:189], v155 offset:16384
	ds_read_b128 v[190:193], v155 offset:17408
	ds_read_b128 v[194:197], v155 offset:18432
	ds_read_b128 v[198:201], v155 offset:19456
	ds_read_b128 v[202:205], v155 offset:20480
	ds_read_b128 v[206:209], v155 offset:21504
	ds_read_b128 v[210:213], v155 offset:22528
	ds_read_b128 v[214:217], v155 offset:23552
	global_load_lds_dwordx4 v[218:219], off
	s_add_i32 m0, s34, 0x2000
	s_add_u32 s34, s36, 0xb0000
	v_lshl_add_u64 v[220:221], s[36:37], 0, v[136:137]
	s_addc_u32 s35, s37, 0
	s_add_i32 s59, s53, s41
	global_load_lds_dwordx4 v[220:221], off
	v_lshl_add_u64 v[222:223], s[34:35], 0, v[132:133]
	s_mov_b32 m0, s59
	v_lshl_add_u64 v[224:225], s[38:39], 0, v[134:135]
	global_load_lds_dwordx4 v[222:223], off
	v_lshl_add_u64 v[222:223], s[34:35], 0, v[136:137]
	s_add_i32 m0, s59, 0x2000
	s_nop 0
	global_load_lds_dwordx4 v[222:223], off
	v_lshl_add_u64 v[222:223], s[38:39], 0, v[130:131]
	s_mov_b32 m0, s42
	s_nop 0
	global_load_lds_dwordx4 v[222:223], off
	s_mov_b32 m0, s43
	s_nop 0
	global_load_lds_dwordx4 v[224:225], off
	s_cmp_eq_u32 s54, 1
	s_cbranch_scc1 .Lmy_sw_18_1a
	s_waitcnt vmcnt(40)
	s_branch .Lmy_sw_18_1b

.Lmy_sw_18_1b:
	s_waitcnt lgkmcnt(0)
	s_barrier
	s_setprio 1
	s_waitcnt lgkmcnt(0)
	v_mfma_f32_16x16x32_bf16 v[60:63], v[146:149], v[186:189], 0
	v_mfma_f32_16x16x32_bf16 v[56:59], v[162:165], v[186:189], 0
	v_mfma_f32_16x16x32_bf16 v[44:47], v[146:149], v[194:197], 0
	v_mfma_f32_16x16x32_bf16 v[40:43], v[162:165], v[194:197], 0
	v_mfma_f32_16x16x32_bf16 v[28:31], v[146:149], v[202:205], 0
	v_mfma_f32_16x16x32_bf16 v[24:27], v[162:165], v[202:205], 0
	v_mfma_f32_16x16x32_bf16 v[12:15], v[146:149], v[210:213], 0
	v_mfma_f32_16x16x32_bf16 v[8:11], v[162:165], v[210:213], 0
	v_mfma_f32_16x16x32_bf16 v[60:63], v[158:161], v[190:193], v[60:63]
	v_mfma_f32_16x16x32_bf16 v[56:59], v[166:169], v[190:193], v[56:59]
	v_mfma_f32_16x16x32_bf16 v[44:47], v[158:161], v[198:201], v[44:47]
	v_mfma_f32_16x16x32_bf16 v[40:43], v[166:169], v[198:201], v[40:43]
	v_mfma_f32_16x16x32_bf16 v[28:31], v[158:161], v[206:209], v[28:31]
	v_mfma_f32_16x16x32_bf16 v[24:27], v[166:169], v[206:209], v[24:27]
	v_mfma_f32_16x16x32_bf16 v[12:15], v[158:161], v[214:217], v[12:15]
	v_mfma_f32_16x16x32_bf16 v[8:11], v[166:169], v[214:217], v[8:11]
	s_setprio 0
	s_setprio 1
	v_mfma_f32_16x16x32_bf16 v[52:55], v[170:173], v[186:189], 0
	v_mfma_f32_16x16x32_bf16 v[48:51], v[178:181], v[186:189], 0
	v_mfma_f32_16x16x32_bf16 v[36:39], v[170:173], v[194:197], 0
	v_mfma_f32_16x16x32_bf16 v[32:35], v[178:181], v[194:197], 0
	v_mfma_f32_16x16x32_bf16 v[20:23], v[170:173], v[202:205], 0
	v_mfma_f32_16x16x32_bf16 v[16:19], v[178:181], v[202:205], 0
	v_mfma_f32_16x16x32_bf16 v[4:7], v[170:173], v[210:213], 0
	v_mfma_f32_16x16x32_bf16 v[0:3], v[178:181], v[210:213], 0
	v_mfma_f32_16x16x32_bf16 v[52:55], v[174:177], v[190:193], v[52:55]
	v_mfma_f32_16x16x32_bf16 v[48:51], v[182:185], v[190:193], v[48:51]
	v_mfma_f32_16x16x32_bf16 v[36:39], v[174:177], v[198:201], v[36:39]
	v_mfma_f32_16x16x32_bf16 v[32:35], v[182:185], v[198:201], v[32:35]
	v_mfma_f32_16x16x32_bf16 v[20:23], v[174:177], v[206:209], v[20:23]
	v_mfma_f32_16x16x32_bf16 v[16:19], v[182:185], v[206:209], v[16:19]
	v_mfma_f32_16x16x32_bf16 v[4:7], v[174:177], v[214:217], v[4:7]
	v_mfma_f32_16x16x32_bf16 v[0:3], v[182:185], v[214:217], v[0:3]
	s_setprio 0
	s_barrier
	s_add_i32 s59, 0, 0x18000
	s_add_i32 s60, 0, 0x1c000
	v_add_u32_e32 v166, s59, v151
	v_add_u32_e32 v182, s60, v151
	ds_read_b128 v[146:149], v166
	ds_read_b128 v[158:161], v166 offset:1024
	ds_read_b128 v[162:165], v166 offset:2048
	ds_read_b128 v[166:169], v166 offset:3072
	ds_read_b128 v[170:173], v182
	ds_read_b128 v[174:177], v182 offset:1024
	ds_read_b128 v[178:181], v182 offset:2048
	ds_read_b128 v[182:185], v182 offset:3072
	s_add_u32 s34, s38, 0xb0000
	s_addc_u32 s35, s39, 0
	s_mov_b32 m0, s44
	v_lshl_add_u64 v[226:227], s[34:35], 0, v[130:131]
	ds_read_b128 v[186:189], v155 offset:32768
	ds_read_b128 v[190:193], v155 offset:33792
	ds_read_b128 v[194:197], v155 offset:34816
	ds_read_b128 v[198:201], v155 offset:35840
	ds_read_b128 v[202:205], v155 offset:36864
	ds_read_b128 v[206:209], v155 offset:37888
	ds_read_b128 v[210:213], v155 offset:38912
	ds_read_b128 v[214:217], v155 offset:39936
	global_load_lds_dwordx4 v[226:227], off
	v_lshl_add_u64 v[226:227], s[34:35], 0, v[134:135]
	s_mov_b32 m0, s45
	s_nop 0
	global_load_lds_dwordx4 v[226:227], off
	s_waitcnt vmcnt(8)
	s_waitcnt lgkmcnt(0)
	s_barrier
	s_setprio 1
	s_waitcnt lgkmcnt(0)
	v_mfma_f32_16x16x32_bf16 v[124:127], v[146:149], v[186:189], v[124:127]
	v_mfma_f32_16x16x32_bf16 v[120:123], v[162:165], v[186:189], v[120:123]
	v_mfma_f32_16x16x32_bf16 v[108:111], v[146:149], v[194:197], v[108:111]
	v_mfma_f32_16x16x32_bf16 v[104:107], v[162:165], v[194:197], v[104:107]
	v_mfma_f32_16x16x32_bf16 v[92:95], v[146:149], v[202:205], v[92:95]
	v_mfma_f32_16x16x32_bf16 v[88:91], v[162:165], v[202:205], v[88:91]
	v_mfma_f32_16x16x32_bf16 v[76:79], v[146:149], v[210:213], v[76:79]
	v_mfma_f32_16x16x32_bf16 v[72:75], v[162:165], v[210:213], v[72:75]
	v_mfma_f32_16x16x32_bf16 v[124:127], v[158:161], v[190:193], v[124:127]
	v_mfma_f32_16x16x32_bf16 v[120:123], v[166:169], v[190:193], v[120:123]
	v_mfma_f32_16x16x32_bf16 v[108:111], v[158:161], v[198:201], v[108:111]
	v_mfma_f32_16x16x32_bf16 v[104:107], v[166:169], v[198:201], v[104:107]
	v_mfma_f32_16x16x32_bf16 v[92:95], v[158:161], v[206:209], v[92:95]
	v_mfma_f32_16x16x32_bf16 v[88:91], v[166:169], v[206:209], v[88:91]
	v_mfma_f32_16x16x32_bf16 v[76:79], v[158:161], v[214:217], v[76:79]
	v_mfma_f32_16x16x32_bf16 v[72:75], v[166:169], v[214:217], v[72:75]
	s_setprio 0
	s_setprio 1
	v_mfma_f32_16x16x32_bf16 v[116:119], v[170:173], v[186:189], v[116:119]
	v_mfma_f32_16x16x32_bf16 v[112:115], v[178:181], v[186:189], v[112:115]
	v_mfma_f32_16x16x32_bf16 v[100:103], v[170:173], v[194:197], v[100:103]
	v_mfma_f32_16x16x32_bf16 v[96:99], v[178:181], v[194:197], v[96:99]
	v_mfma_f32_16x16x32_bf16 v[84:87], v[170:173], v[202:205], v[84:87]
	v_mfma_f32_16x16x32_bf16 v[80:83], v[178:181], v[202:205], v[80:83]
	v_mfma_f32_16x16x32_bf16 v[68:71], v[170:173], v[210:213], v[68:71]
	v_mfma_f32_16x16x32_bf16 v[64:67], v[178:181], v[210:213], v[64:67]
	v_mfma_f32_16x16x32_bf16 v[116:119], v[174:177], v[190:193], v[116:119]
	v_mfma_f32_16x16x32_bf16 v[112:115], v[182:185], v[190:193], v[112:115]
	v_mfma_f32_16x16x32_bf16 v[100:103], v[174:177], v[198:201], v[100:103]
	v_mfma_f32_16x16x32_bf16 v[96:99], v[182:185], v[198:201], v[96:99]
	v_mfma_f32_16x16x32_bf16 v[84:87], v[174:177], v[206:209], v[84:87]
	v_mfma_f32_16x16x32_bf16 v[80:83], v[182:185], v[206:209], v[80:83]
	v_mfma_f32_16x16x32_bf16 v[68:71], v[174:177], v[214:217], v[68:71]
	v_mfma_f32_16x16x32_bf16 v[64:67], v[182:185], v[214:217], v[64:67]
	s_setprio 0
	s_barrier
	s_add_i32 s34, s59, s41
	v_lshl_add_u64 v[218:219], v[218:219], 0, s[22:23]
	s_mov_b32 m0, s34
	ds_read_b128 v[186:189], v155 offset:49152
	ds_read_b128 v[190:193], v155 offset:50176
	ds_read_b128 v[194:197], v155 offset:51200
	ds_read_b128 v[198:201], v155 offset:52224
	ds_read_b128 v[202:205], v155 offset:53248
	ds_read_b128 v[206:209], v155 offset:54272
	ds_read_b128 v[210:213], v155 offset:55296
	ds_read_b128 v[214:217], v155 offset:56320
	global_load_lds_dwordx4 v[218:219], off
	s_add_i32 m0, s34, 0x2000
	s_add_u32 s34, s36, 0xb0080
	v_lshl_add_u64 v[218:219], v[220:221], 0, s[22:23]
	s_addc_u32 s35, s37, 0
	s_add_i32 s36, s60, s41
	global_load_lds_dwordx4 v[218:219], off
	v_lshl_add_u64 v[218:219], s[34:35], 0, v[132:133]
	s_mov_b32 m0, s36
	s_nop 0
	global_load_lds_dwordx4 v[218:219], off
	v_lshl_add_u64 v[218:219], s[34:35], 0, v[136:137]
	s_add_i32 m0, s36, 0x2000
	s_nop 0
	global_load_lds_dwordx4 v[218:219], off
	v_lshl_add_u64 v[218:219], v[222:223], 0, s[22:23]
	s_mov_b32 m0, s47
	s_nop 0
	global_load_lds_dwordx4 v[218:219], off
	v_lshl_add_u64 v[218:219], v[224:225], 0, s[22:23]
	s_mov_b32 m0, s48
	s_nop 0
	global_load_lds_dwordx4 v[218:219], off
	s_waitcnt vmcnt(8)
	s_waitcnt lgkmcnt(0)
	s_barrier
	s_setprio 1
	s_waitcnt lgkmcnt(0)
	v_mfma_f32_16x16x32_bf16 v[60:63], v[146:149], v[186:189], v[60:63]
	v_mfma_f32_16x16x32_bf16 v[56:59], v[162:165], v[186:189], v[56:59]
	v_mfma_f32_16x16x32_bf16 v[44:47], v[146:149], v[194:197], v[44:47]
	v_mfma_f32_16x16x32_bf16 v[40:43], v[162:165], v[194:197], v[40:43]
	v_mfma_f32_16x16x32_bf16 v[28:31], v[146:149], v[202:205], v[28:31]
	v_mfma_f32_16x16x32_bf16 v[24:27], v[162:165], v[202:205], v[24:27]
	v_mfma_f32_16x16x32_bf16 v[12:15], v[146:149], v[210:213], v[12:15]
	v_mfma_f32_16x16x32_bf16 v[8:11], v[162:165], v[210:213], v[8:11]
	v_mfma_f32_16x16x32_bf16 v[60:63], v[158:161], v[190:193], v[60:63]
	v_mfma_f32_16x16x32_bf16 v[56:59], v[166:169], v[190:193], v[56:59]
	v_mfma_f32_16x16x32_bf16 v[44:47], v[158:161], v[198:201], v[44:47]
	v_mfma_f32_16x16x32_bf16 v[40:43], v[166:169], v[198:201], v[40:43]
	v_mfma_f32_16x16x32_bf16 v[28:31], v[158:161], v[206:209], v[28:31]
	v_mfma_f32_16x16x32_bf16 v[24:27], v[166:169], v[206:209], v[24:27]
	v_mfma_f32_16x16x32_bf16 v[12:15], v[158:161], v[214:217], v[12:15]
	v_mfma_f32_16x16x32_bf16 v[8:11], v[166:169], v[214:217], v[8:11]
	s_setprio 0
	s_setprio 1
	v_mfma_f32_16x16x32_bf16 v[52:55], v[170:173], v[186:189], v[52:55]
	v_mfma_f32_16x16x32_bf16 v[48:51], v[178:181], v[186:189], v[48:51]
	v_mfma_f32_16x16x32_bf16 v[36:39], v[170:173], v[194:197], v[36:39]
	v_mfma_f32_16x16x32_bf16 v[32:35], v[178:181], v[194:197], v[32:35]
	v_mfma_f32_16x16x32_bf16 v[20:23], v[170:173], v[202:205], v[20:23]
	v_mfma_f32_16x16x32_bf16 v[16:19], v[178:181], v[202:205], v[16:19]
	v_mfma_f32_16x16x32_bf16 v[4:7], v[170:173], v[210:213], v[4:7]
	v_mfma_f32_16x16x32_bf16 v[0:3], v[178:181], v[210:213], v[0:3]
	v_mfma_f32_16x16x32_bf16 v[52:55], v[174:177], v[190:193], v[52:55]
	v_mfma_f32_16x16x32_bf16 v[48:51], v[182:185], v[190:193], v[48:51]
	v_mfma_f32_16x16x32_bf16 v[36:39], v[174:177], v[198:201], v[36:39]
	v_mfma_f32_16x16x32_bf16 v[32:35], v[182:185], v[198:201], v[32:35]
	v_mfma_f32_16x16x32_bf16 v[20:23], v[174:177], v[206:209], v[20:23]
	v_mfma_f32_16x16x32_bf16 v[16:19], v[182:185], v[206:209], v[16:19]
	v_mfma_f32_16x16x32_bf16 v[4:7], v[174:177], v[214:217], v[4:7]
	v_mfma_f32_16x16x32_bf16 v[0:3], v[182:185], v[214:217], v[0:3]
	s_setprio 0
	s_barrier
	s_add_i32 s58, s58, 2
	s_add_u32 s30, s30, 0x100
	s_addc_u32 s31, s31, 0
	s_add_u32 s13, s13, 0x100
	s_addc_u32 s57, s57, 0

.Lmy_nobar2_19:
	ds_read_b128 v[150:153], v157
	ds_read_b128 v[160:163], v157 offset:1024
	ds_read_b128 v[164:167], v157 offset:2048
	ds_read_b128 v[168:171], v157 offset:3072
	ds_read_b128 v[172:175], v158
	ds_read_b128 v[176:179], v158 offset:1024
	ds_read_b128 v[180:183], v158 offset:2048
	ds_read_b128 v[184:187], v158 offset:3072
	s_add_u32 s34, s42, 0xfffc0080
	s_addc_u32 s35, s43, -1
	s_cmp_eq_u32 s65, 12
	s_cselect_b32 s47, s7, s35
	s_cselect_b32 s46, s8, s34
	s_cselect_b32 s45, s12, s37
	s_cselect_b32 s44, s13, s31
	v_lshl_add_u64 v[220:221], s[42:43], 0, v[142:143]
	s_add_i32 m0, s53, 0xc000
	ds_read_b128 v[188:191], v159
	ds_read_b128 v[192:195], v159 offset:1024
	ds_read_b128 v[196:199], v159 offset:2048
	ds_read_b128 v[200:203], v159 offset:3072
	ds_read_b128 v[204:207], v159 offset:4096
	ds_read_b128 v[208:211], v159 offset:5120
	ds_read_b128 v[212:215], v159 offset:6144
	ds_read_b128 v[216:219], v159 offset:7168
	global_load_lds_dwordx4 v[220:221], off
	v_lshl_add_u64 v[220:221], s[42:43], 0, v[144:145]
	s_add_i32 m0, s53, 0xe000
	s_nop 0
	global_load_lds_dwordx4 v[220:221], off
	s_cmp_eq_u32 s63, 1
	s_cbranch_scc1 .Lmy_sw_19_0a
	s_waitcnt vmcnt(16)
	s_branch .Lmy_sw_19_0b

.Lmy_sw_19_0b:
	s_waitcnt lgkmcnt(0)
	s_barrier
	s_setprio 1
	s_waitcnt lgkmcnt(0)
	v_mfma_f32_16x16x32_bf16 v[124:127], v[150:153], v[188:191], 0
	v_mfma_f32_16x16x32_bf16 v[120:123], v[164:167], v[188:191], 0
	v_mfma_f32_16x16x32_bf16 v[108:111], v[150:153], v[196:199], 0
	v_mfma_f32_16x16x32_bf16 v[104:107], v[164:167], v[196:199], 0
	v_mfma_f32_16x16x32_bf16 v[92:95], v[150:153], v[204:207], 0
	v_mfma_f32_16x16x32_bf16 v[88:91], v[164:167], v[204:207], 0
	v_mfma_f32_16x16x32_bf16 v[76:79], v[150:153], v[212:215], 0
	v_mfma_f32_16x16x32_bf16 v[72:75], v[164:167], v[212:215], 0
	v_mfma_f32_16x16x32_bf16 v[124:127], v[160:163], v[192:195], v[124:127]
	v_mfma_f32_16x16x32_bf16 v[120:123], v[168:171], v[192:195], v[120:123]
	v_mfma_f32_16x16x32_bf16 v[108:111], v[160:163], v[200:203], v[108:111]
	v_mfma_f32_16x16x32_bf16 v[104:107], v[168:171], v[200:203], v[104:107]
	v_mfma_f32_16x16x32_bf16 v[92:95], v[160:163], v[208:211], v[92:95]
	v_mfma_f32_16x16x32_bf16 v[88:91], v[168:171], v[208:211], v[88:91]
	v_mfma_f32_16x16x32_bf16 v[76:79], v[160:163], v[216:219], v[76:79]
	v_mfma_f32_16x16x32_bf16 v[72:75], v[168:171], v[216:219], v[72:75]
	s_setprio 0
	s_setprio 1
	v_mfma_f32_16x16x32_bf16 v[116:119], v[172:175], v[188:191], 0
	v_mfma_f32_16x16x32_bf16 v[112:115], v[180:183], v[188:191], 0
	v_mfma_f32_16x16x32_bf16 v[100:103], v[172:175], v[196:199], 0
	v_mfma_f32_16x16x32_bf16 v[96:99], v[180:183], v[196:199], 0
	v_mfma_f32_16x16x32_bf16 v[84:87], v[172:175], v[204:207], 0
	v_mfma_f32_16x16x32_bf16 v[80:83], v[180:183], v[204:207], 0
	v_mfma_f32_16x16x32_bf16 v[68:71], v[172:175], v[212:215], 0
	v_mfma_f32_16x16x32_bf16 v[64:67], v[180:183], v[212:215], 0
	v_mfma_f32_16x16x32_bf16 v[116:119], v[176:179], v[192:195], v[116:119]
	v_mfma_f32_16x16x32_bf16 v[112:115], v[184:187], v[192:195], v[112:115]
	v_mfma_f32_16x16x32_bf16 v[100:103], v[176:179], v[200:203], v[100:103]
	v_mfma_f32_16x16x32_bf16 v[96:99], v[184:187], v[200:203], v[96:99]
	v_mfma_f32_16x16x32_bf16 v[84:87], v[176:179], v[208:211], v[84:87]
	v_mfma_f32_16x16x32_bf16 v[80:83], v[184:187], v[208:211], v[80:83]
	v_mfma_f32_16x16x32_bf16 v[68:71], v[176:179], v[216:219], v[68:71]
	v_mfma_f32_16x16x32_bf16 v[64:67], v[184:187], v[216:219], v[64:67]
	s_setprio 0
	s_barrier
	s_add_i32 s34, s61, s50
	v_lshl_add_u64 v[220:221], s[44:45], 0, v[134:135]
	s_mov_b32 m0, s34
	ds_read_b128 v[188:191], v159 offset:16384
	ds_read_b128 v[192:195], v159 offset:17408
	ds_read_b128 v[196:199], v159 offset:18432
	ds_read_b128 v[200:203], v159 offset:19456
	ds_read_b128 v[204:207], v159 offset:20480
	ds_read_b128 v[208:211], v159 offset:21504
	ds_read_b128 v[212:215], v159 offset:22528
	ds_read_b128 v[216:219], v159 offset:23552
	global_load_lds_dwordx4 v[220:221], off
	s_add_i32 m0, s34, 0x2000
	s_add_u32 s34, s44, 0x40000
	v_lshl_add_u64 v[222:223], s[44:45], 0, v[138:139]
	s_addc_u32 s35, s45, 0
	s_add_i32 s66, s62, s50
	global_load_lds_dwordx4 v[222:223], off
	v_lshl_add_u64 v[224:225], s[34:35], 0, v[134:135]
	s_mov_b32 m0, s66
	v_lshl_add_u64 v[226:227], s[46:47], 0, v[136:137]
	global_load_lds_dwordx4 v[224:225], off
	v_lshl_add_u64 v[224:225], s[34:35], 0, v[138:139]
	s_add_i32 m0, s66, 0x2000
	s_nop 0
	global_load_lds_dwordx4 v[224:225], off
	v_lshl_add_u64 v[224:225], s[46:47], 0, v[132:133]
	s_mov_b32 m0, s53
	s_nop 0
	global_load_lds_dwordx4 v[224:225], off
	s_mov_b32 m0, s54
	s_nop 0
	global_load_lds_dwordx4 v[226:227], off
	s_cmp_eq_u32 s63, 1
	s_cbranch_scc1 .Lmy_sw_19_1a
	s_waitcnt vmcnt(16)
	s_branch .Lmy_sw_19_1b

.Lmy_sw_19_1b:
	s_waitcnt lgkmcnt(0)
	s_barrier
	s_setprio 1
	s_waitcnt lgkmcnt(0)
	v_mfma_f32_16x16x32_bf16 v[60:63], v[150:153], v[188:191], 0
	v_mfma_f32_16x16x32_bf16 v[56:59], v[164:167], v[188:191], 0
	v_mfma_f32_16x16x32_bf16 v[44:47], v[150:153], v[196:199], 0
	v_mfma_f32_16x16x32_bf16 v[40:43], v[164:167], v[196:199], 0
	v_mfma_f32_16x16x32_bf16 v[28:31], v[150:153], v[204:207], 0
	v_mfma_f32_16x16x32_bf16 v[24:27], v[164:167], v[204:207], 0
	v_mfma_f32_16x16x32_bf16 v[12:15], v[150:153], v[212:215], 0
	v_mfma_f32_16x16x32_bf16 v[8:11], v[164:167], v[212:215], 0
	v_mfma_f32_16x16x32_bf16 v[60:63], v[160:163], v[192:195], v[60:63]
	v_mfma_f32_16x16x32_bf16 v[56:59], v[168:171], v[192:195], v[56:59]
	v_mfma_f32_16x16x32_bf16 v[44:47], v[160:163], v[200:203], v[44:47]
	v_mfma_f32_16x16x32_bf16 v[40:43], v[168:171], v[200:203], v[40:43]
	v_mfma_f32_16x16x32_bf16 v[28:31], v[160:163], v[208:211], v[28:31]
	v_mfma_f32_16x16x32_bf16 v[24:27], v[168:171], v[208:211], v[24:27]
	v_mfma_f32_16x16x32_bf16 v[12:15], v[160:163], v[216:219], v[12:15]
	v_mfma_f32_16x16x32_bf16 v[8:11], v[168:171], v[216:219], v[8:11]
	s_setprio 0
	s_setprio 1
	v_mfma_f32_16x16x32_bf16 v[52:55], v[172:175], v[188:191], 0
	v_mfma_f32_16x16x32_bf16 v[48:51], v[180:183], v[188:191], 0
	v_mfma_f32_16x16x32_bf16 v[36:39], v[172:175], v[196:199], 0
	v_mfma_f32_16x16x32_bf16 v[32:35], v[180:183], v[196:199], 0
	v_mfma_f32_16x16x32_bf16 v[20:23], v[172:175], v[204:207], 0
	v_mfma_f32_16x16x32_bf16 v[16:19], v[180:183], v[204:207], 0
	v_mfma_f32_16x16x32_bf16 v[4:7], v[172:175], v[212:215], 0
	v_mfma_f32_16x16x32_bf16 v[0:3], v[180:183], v[212:215], 0
	v_mfma_f32_16x16x32_bf16 v[52:55], v[176:179], v[192:195], v[52:55]
	v_mfma_f32_16x16x32_bf16 v[48:51], v[184:187], v[192:195], v[48:51]
	v_mfma_f32_16x16x32_bf16 v[36:39], v[176:179], v[200:203], v[36:39]
	v_mfma_f32_16x16x32_bf16 v[32:35], v[184:187], v[200:203], v[32:35]
	v_mfma_f32_16x16x32_bf16 v[20:23], v[176:179], v[208:211], v[20:23]
	v_mfma_f32_16x16x32_bf16 v[16:19], v[184:187], v[208:211], v[16:19]
	v_mfma_f32_16x16x32_bf16 v[4:7], v[176:179], v[216:219], v[4:7]
	v_mfma_f32_16x16x32_bf16 v[0:3], v[184:187], v[216:219], v[0:3]
	s_setprio 0
	s_barrier
	s_add_i32 s66, 0, 0x18000
	v_add_u32_e32 v140, s66, v154
	s_add_i32 s67, 0, 0x1c000
	ds_read_b128 v[150:153], v140
	ds_read_b128 v[160:163], v140 offset:1024
	ds_read_b128 v[164:167], v140 offset:2048
	ds_read_b128 v[168:171], v140 offset:3072
	v_add_u32_e32 v140, s67, v154
	ds_read_b128 v[172:175], v140
	ds_read_b128 v[176:179], v140 offset:1024
	ds_read_b128 v[180:183], v140 offset:2048
	ds_read_b128 v[184:187], v140 offset:3072
	s_add_u32 s34, s46, 0x40000
	s_addc_u32 s35, s47, 0
	s_mov_b32 m0, s55
	v_lshl_add_u64 v[228:229], s[34:35], 0, v[132:133]
	ds_read_b128 v[188:191], v159 offset:32768
	ds_read_b128 v[192:195], v159 offset:33792
	ds_read_b128 v[196:199], v159 offset:34816
	ds_read_b128 v[200:203], v159 offset:35840
	ds_read_b128 v[204:207], v159 offset:36864
	ds_read_b128 v[208:211], v159 offset:37888
	ds_read_b128 v[212:215], v159 offset:38912
	ds_read_b128 v[216:219], v159 offset:39936
	global_load_lds_dwordx4 v[228:229], off
	v_lshl_add_u64 v[228:229], s[34:35], 0, v[136:137]
	s_mov_b32 m0, s56
	s_nop 0
	global_load_lds_dwordx4 v[228:229], off
	s_waitcnt vmcnt(8)
	s_waitcnt lgkmcnt(0)
	s_barrier
	s_setprio 1
	s_waitcnt lgkmcnt(0)
	v_mfma_f32_16x16x32_bf16 v[124:127], v[150:153], v[188:191], v[124:127]
	v_mfma_f32_16x16x32_bf16 v[120:123], v[164:167], v[188:191], v[120:123]
	v_mfma_f32_16x16x32_bf16 v[108:111], v[150:153], v[196:199], v[108:111]
	v_mfma_f32_16x16x32_bf16 v[104:107], v[164:167], v[196:199], v[104:107]
	v_mfma_f32_16x16x32_bf16 v[92:95], v[150:153], v[204:207], v[92:95]
	v_mfma_f32_16x16x32_bf16 v[88:91], v[164:167], v[204:207], v[88:91]
	v_mfma_f32_16x16x32_bf16 v[76:79], v[150:153], v[212:215], v[76:79]
	v_mfma_f32_16x16x32_bf16 v[72:75], v[164:167], v[212:215], v[72:75]
	v_mfma_f32_16x16x32_bf16 v[124:127], v[160:163], v[192:195], v[124:127]
	v_mfma_f32_16x16x32_bf16 v[120:123], v[168:171], v[192:195], v[120:123]
	v_mfma_f32_16x16x32_bf16 v[108:111], v[160:163], v[200:203], v[108:111]
	v_mfma_f32_16x16x32_bf16 v[104:107], v[168:171], v[200:203], v[104:107]
	v_mfma_f32_16x16x32_bf16 v[92:95], v[160:163], v[208:211], v[92:95]
	v_mfma_f32_16x16x32_bf16 v[88:91], v[168:171], v[208:211], v[88:91]
	v_mfma_f32_16x16x32_bf16 v[76:79], v[160:163], v[216:219], v[76:79]
	v_mfma_f32_16x16x32_bf16 v[72:75], v[168:171], v[216:219], v[72:75]
	s_setprio 0
	s_setprio 1
	v_mfma_f32_16x16x32_bf16 v[116:119], v[172:175], v[188:191], v[116:119]
	v_mfma_f32_16x16x32_bf16 v[112:115], v[180:183], v[188:191], v[112:115]
	v_mfma_f32_16x16x32_bf16 v[100:103], v[172:175], v[196:199], v[100:103]
	v_mfma_f32_16x16x32_bf16 v[96:99], v[180:183], v[196:199], v[96:99]
	v_mfma_f32_16x16x32_bf16 v[84:87], v[172:175], v[204:207], v[84:87]
	v_mfma_f32_16x16x32_bf16 v[80:83], v[180:183], v[204:207], v[80:83]
	v_mfma_f32_16x16x32_bf16 v[68:71], v[172:175], v[212:215], v[68:71]
	v_mfma_f32_16x16x32_bf16 v[64:67], v[180:183], v[212:215], v[64:67]
	v_mfma_f32_16x16x32_bf16 v[116:119], v[176:179], v[192:195], v[116:119]
	v_mfma_f32_16x16x32_bf16 v[112:115], v[184:187], v[192:195], v[112:115]
	v_mfma_f32_16x16x32_bf16 v[100:103], v[176:179], v[200:203], v[100:103]
	v_mfma_f32_16x16x32_bf16 v[96:99], v[184:187], v[200:203], v[96:99]
	v_mfma_f32_16x16x32_bf16 v[84:87], v[176:179], v[208:211], v[84:87]
	v_mfma_f32_16x16x32_bf16 v[80:83], v[184:187], v[208:211], v[80:83]
	v_mfma_f32_16x16x32_bf16 v[68:71], v[176:179], v[216:219], v[68:71]
	v_mfma_f32_16x16x32_bf16 v[64:67], v[184:187], v[216:219], v[64:67]
	s_setprio 0
	s_barrier
	s_add_i32 s34, s66, s50
	v_lshl_add_u64 v[220:221], v[220:221], 0, s[26:27]
	s_mov_b32 m0, s34
	ds_read_b128 v[188:191], v159 offset:49152
	ds_read_b128 v[192:195], v159 offset:50176
	ds_read_b128 v[196:199], v159 offset:51200
	ds_read_b128 v[200:203], v159 offset:52224
	ds_read_b128 v[204:207], v159 offset:53248
	ds_read_b128 v[208:211], v159 offset:54272
	ds_read_b128 v[212:215], v159 offset:55296
	ds_read_b128 v[216:219], v159 offset:56320
	global_load_lds_dwordx4 v[220:221], off
	s_add_i32 m0, s34, 0x2000
	s_add_u32 s34, s44, 0x40080
	v_lshl_add_u64 v[220:221], v[222:223], 0, s[26:27]
	s_addc_u32 s35, s45, 0
	s_add_i32 s44, s67, s50
	global_load_lds_dwordx4 v[220:221], off
	v_lshl_add_u64 v[220:221], s[34:35], 0, v[134:135]
	s_mov_b32 m0, s44
	s_nop 0
	global_load_lds_dwordx4 v[220:221], off
	v_lshl_add_u64 v[220:221], s[34:35], 0, v[138:139]
	s_add_i32 m0, s44, 0x2000
	s_nop 0
	global_load_lds_dwordx4 v[220:221], off
	v_lshl_add_u64 v[220:221], v[224:225], 0, s[26:27]
	s_mov_b32 m0, s58
	s_nop 0
	global_load_lds_dwordx4 v[220:221], off
	v_lshl_add_u64 v[220:221], v[226:227], 0, s[26:27]
	s_mov_b32 m0, s59
	s_nop 0
	global_load_lds_dwordx4 v[220:221], off
	s_waitcnt vmcnt(8)
	s_waitcnt lgkmcnt(0)
	s_barrier
	s_setprio 1
	s_waitcnt lgkmcnt(0)
	v_mfma_f32_16x16x32_bf16 v[60:63], v[150:153], v[188:191], v[60:63]
	v_mfma_f32_16x16x32_bf16 v[56:59], v[164:167], v[188:191], v[56:59]
	v_mfma_f32_16x16x32_bf16 v[44:47], v[150:153], v[196:199], v[44:47]
	v_mfma_f32_16x16x32_bf16 v[40:43], v[164:167], v[196:199], v[40:43]
	v_mfma_f32_16x16x32_bf16 v[28:31], v[150:153], v[204:207], v[28:31]
	v_mfma_f32_16x16x32_bf16 v[24:27], v[164:167], v[204:207], v[24:27]
	v_mfma_f32_16x16x32_bf16 v[12:15], v[150:153], v[212:215], v[12:15]
	v_mfma_f32_16x16x32_bf16 v[8:11], v[164:167], v[212:215], v[8:11]
	v_mfma_f32_16x16x32_bf16 v[60:63], v[160:163], v[192:195], v[60:63]
	v_mfma_f32_16x16x32_bf16 v[56:59], v[168:171], v[192:195], v[56:59]
	v_mfma_f32_16x16x32_bf16 v[44:47], v[160:163], v[200:203], v[44:47]
	v_mfma_f32_16x16x32_bf16 v[40:43], v[168:171], v[200:203], v[40:43]
	v_mfma_f32_16x16x32_bf16 v[28:31], v[160:163], v[208:211], v[28:31]
	v_mfma_f32_16x16x32_bf16 v[24:27], v[168:171], v[208:211], v[24:27]
	v_mfma_f32_16x16x32_bf16 v[12:15], v[160:163], v[216:219], v[12:15]
	v_mfma_f32_16x16x32_bf16 v[8:11], v[168:171], v[216:219], v[8:11]
	s_setprio 0
	s_setprio 1
	v_mfma_f32_16x16x32_bf16 v[52:55], v[172:175], v[188:191], v[52:55]
	v_mfma_f32_16x16x32_bf16 v[48:51], v[180:183], v[188:191], v[48:51]
	v_mfma_f32_16x16x32_bf16 v[36:39], v[172:175], v[196:199], v[36:39]
	v_mfma_f32_16x16x32_bf16 v[32:35], v[180:183], v[196:199], v[32:35]
	v_mfma_f32_16x16x32_bf16 v[20:23], v[172:175], v[204:207], v[20:23]
	v_mfma_f32_16x16x32_bf16 v[16:19], v[180:183], v[204:207], v[16:19]
	v_mfma_f32_16x16x32_bf16 v[4:7], v[172:175], v[212:215], v[4:7]
	v_mfma_f32_16x16x32_bf16 v[0:3], v[180:183], v[212:215], v[0:3]
	v_mfma_f32_16x16x32_bf16 v[52:55], v[176:179], v[192:195], v[52:55]
	v_mfma_f32_16x16x32_bf16 v[48:51], v[184:187], v[192:195], v[48:51]
	v_mfma_f32_16x16x32_bf16 v[36:39], v[176:179], v[200:203], v[36:39]
	v_mfma_f32_16x16x32_bf16 v[32:35], v[184:187], v[200:203], v[32:35]
	v_mfma_f32_16x16x32_bf16 v[20:23], v[176:179], v[208:211], v[20:23]
	v_mfma_f32_16x16x32_bf16 v[16:19], v[184:187], v[208:211], v[16:19]
	v_mfma_f32_16x16x32_bf16 v[4:7], v[176:179], v[216:219], v[4:7]
	v_mfma_f32_16x16x32_bf16 v[0:3], v[184:187], v[216:219], v[0:3]
	s_setprio 0
	s_barrier
	s_add_i32 s65, s65, 2
	s_add_u32 s42, s42, 0x100
	s_addc_u32 s43, s43, 0
	s_add_u32 s31, s31, 0x100
	s_addc_u32 s37, s37, 0

.Lmy_nobar2_21:
	ds_read_b128 v[146:149], v153
	ds_read_b128 v[158:161], v153 offset:1024
	ds_read_b128 v[162:165], v153 offset:2048
	ds_read_b128 v[166:169], v153 offset:3072
	ds_read_b128 v[170:173], v154
	ds_read_b128 v[174:177], v154 offset:1024
	ds_read_b128 v[178:181], v154 offset:2048
	ds_read_b128 v[182:185], v154 offset:3072
	s_add_u32 s34, s38, 0xfffc0080
	s_addc_u32 s35, s39, -1
	s_cmp_eq_u32 s60, 12
	s_cselect_b32 s43, s12, s35
	s_cselect_b32 s42, s13, s34
	s_cselect_b32 s41, s25, s59
	s_cselect_b32 s40, s27, s37
	v_lshl_add_u64 v[218:219], s[38:39], 0, v[138:139]
	s_add_i32 m0, s46, 0xc000
	ds_read_b128 v[186:189], v155
	ds_read_b128 v[190:193], v155 offset:1024
	ds_read_b128 v[194:197], v155 offset:2048
	ds_read_b128 v[198:201], v155 offset:3072
	ds_read_b128 v[202:205], v155 offset:4096
	ds_read_b128 v[206:209], v155 offset:5120
	ds_read_b128 v[210:213], v155 offset:6144
	ds_read_b128 v[214:217], v155 offset:7168
	global_load_lds_dwordx4 v[218:219], off
	v_lshl_add_u64 v[218:219], s[38:39], 0, v[140:141]
	s_add_i32 m0, s46, 0xe000
	s_nop 0
	global_load_lds_dwordx4 v[218:219], off
	s_cmp_eq_u32 s58, 1
	s_cbranch_scc1 .Lmy_sw_21_0a
	s_waitcnt vmcnt(40)
	s_branch .Lmy_sw_21_0b

.Lmy_sw_21_0b:
	s_waitcnt lgkmcnt(0)
	s_barrier
	s_setprio 1
	s_waitcnt lgkmcnt(0)
	v_mfma_f32_16x16x32_bf16 v[124:127], v[146:149], v[186:189], 0
	v_mfma_f32_16x16x32_bf16 v[120:123], v[162:165], v[186:189], 0
	v_mfma_f32_16x16x32_bf16 v[108:111], v[146:149], v[194:197], 0
	v_mfma_f32_16x16x32_bf16 v[104:107], v[162:165], v[194:197], 0
	v_mfma_f32_16x16x32_bf16 v[92:95], v[146:149], v[202:205], 0
	v_mfma_f32_16x16x32_bf16 v[88:91], v[162:165], v[202:205], 0
	v_mfma_f32_16x16x32_bf16 v[76:79], v[146:149], v[210:213], 0
	v_mfma_f32_16x16x32_bf16 v[72:75], v[162:165], v[210:213], 0
	v_mfma_f32_16x16x32_bf16 v[124:127], v[158:161], v[190:193], v[124:127]
	v_mfma_f32_16x16x32_bf16 v[120:123], v[166:169], v[190:193], v[120:123]
	v_mfma_f32_16x16x32_bf16 v[108:111], v[158:161], v[198:201], v[108:111]
	v_mfma_f32_16x16x32_bf16 v[104:107], v[166:169], v[198:201], v[104:107]
	v_mfma_f32_16x16x32_bf16 v[92:95], v[158:161], v[206:209], v[92:95]
	v_mfma_f32_16x16x32_bf16 v[88:91], v[166:169], v[206:209], v[88:91]
	v_mfma_f32_16x16x32_bf16 v[76:79], v[158:161], v[214:217], v[76:79]
	v_mfma_f32_16x16x32_bf16 v[72:75], v[166:169], v[214:217], v[72:75]
	s_setprio 0
	s_setprio 1
	v_mfma_f32_16x16x32_bf16 v[116:119], v[170:173], v[186:189], 0
	v_mfma_f32_16x16x32_bf16 v[112:115], v[178:181], v[186:189], 0
	v_mfma_f32_16x16x32_bf16 v[100:103], v[170:173], v[194:197], 0
	v_mfma_f32_16x16x32_bf16 v[96:99], v[178:181], v[194:197], 0
	v_mfma_f32_16x16x32_bf16 v[84:87], v[170:173], v[202:205], 0
	v_mfma_f32_16x16x32_bf16 v[80:83], v[178:181], v[202:205], 0
	v_mfma_f32_16x16x32_bf16 v[68:71], v[170:173], v[210:213], 0
	v_mfma_f32_16x16x32_bf16 v[64:67], v[178:181], v[210:213], 0
	v_mfma_f32_16x16x32_bf16 v[116:119], v[174:177], v[190:193], v[116:119]
	v_mfma_f32_16x16x32_bf16 v[112:115], v[182:185], v[190:193], v[112:115]
	v_mfma_f32_16x16x32_bf16 v[100:103], v[174:177], v[198:201], v[100:103]
	v_mfma_f32_16x16x32_bf16 v[96:99], v[182:185], v[198:201], v[96:99]
	v_mfma_f32_16x16x32_bf16 v[84:87], v[174:177], v[206:209], v[84:87]
	v_mfma_f32_16x16x32_bf16 v[80:83], v[182:185], v[206:209], v[80:83]
	v_mfma_f32_16x16x32_bf16 v[68:71], v[174:177], v[214:217], v[68:71]
	v_mfma_f32_16x16x32_bf16 v[64:67], v[182:185], v[214:217], v[64:67]
	s_setprio 0
	s_barrier
	s_add_i32 s34, s56, s45
	v_lshl_add_u64 v[218:219], s[40:41], 0, v[132:133]
	s_mov_b32 m0, s34
	ds_read_b128 v[186:189], v155 offset:16384
	ds_read_b128 v[190:193], v155 offset:17408
	ds_read_b128 v[194:197], v155 offset:18432
	ds_read_b128 v[198:201], v155 offset:19456
	ds_read_b128 v[202:205], v155 offset:20480
	ds_read_b128 v[206:209], v155 offset:21504
	ds_read_b128 v[210:213], v155 offset:22528
	ds_read_b128 v[214:217], v155 offset:23552
	global_load_lds_dwordx4 v[218:219], off
	s_add_i32 m0, s34, 0x2000
	s_add_u32 s34, s40, 0x40000
	v_lshl_add_u64 v[220:221], s[40:41], 0, v[136:137]
	s_addc_u32 s35, s41, 0
	s_add_i32 s61, s57, s45
	global_load_lds_dwordx4 v[220:221], off
	v_lshl_add_u64 v[222:223], s[34:35], 0, v[132:133]
	s_mov_b32 m0, s61
	v_lshl_add_u64 v[224:225], s[42:43], 0, v[134:135]
	global_load_lds_dwordx4 v[222:223], off
	v_lshl_add_u64 v[222:223], s[34:35], 0, v[136:137]
	s_add_i32 m0, s61, 0x2000
	s_nop 0
	global_load_lds_dwordx4 v[222:223], off
	v_lshl_add_u64 v[222:223], s[42:43], 0, v[130:131]
	s_mov_b32 m0, s46
	s_nop 0
	global_load_lds_dwordx4 v[222:223], off
	s_mov_b32 m0, s47
	s_nop 0
	global_load_lds_dwordx4 v[224:225], off
	s_cmp_eq_u32 s58, 1
	s_cbranch_scc1 .Lmy_sw_21_1a
	s_waitcnt vmcnt(40)
	s_branch .Lmy_sw_21_1b

.Lmy_sw_21_1b:
	s_waitcnt lgkmcnt(0)
	s_barrier
	s_setprio 1
	s_waitcnt lgkmcnt(0)
	v_mfma_f32_16x16x32_bf16 v[60:63], v[146:149], v[186:189], 0
	v_mfma_f32_16x16x32_bf16 v[56:59], v[162:165], v[186:189], 0
	v_mfma_f32_16x16x32_bf16 v[44:47], v[146:149], v[194:197], 0
	v_mfma_f32_16x16x32_bf16 v[40:43], v[162:165], v[194:197], 0
	v_mfma_f32_16x16x32_bf16 v[28:31], v[146:149], v[202:205], 0
	v_mfma_f32_16x16x32_bf16 v[24:27], v[162:165], v[202:205], 0
	v_mfma_f32_16x16x32_bf16 v[12:15], v[146:149], v[210:213], 0
	v_mfma_f32_16x16x32_bf16 v[8:11], v[162:165], v[210:213], 0
	v_mfma_f32_16x16x32_bf16 v[60:63], v[158:161], v[190:193], v[60:63]
	v_mfma_f32_16x16x32_bf16 v[56:59], v[166:169], v[190:193], v[56:59]
	v_mfma_f32_16x16x32_bf16 v[44:47], v[158:161], v[198:201], v[44:47]
	v_mfma_f32_16x16x32_bf16 v[40:43], v[166:169], v[198:201], v[40:43]
	v_mfma_f32_16x16x32_bf16 v[28:31], v[158:161], v[206:209], v[28:31]
	v_mfma_f32_16x16x32_bf16 v[24:27], v[166:169], v[206:209], v[24:27]
	v_mfma_f32_16x16x32_bf16 v[12:15], v[158:161], v[214:217], v[12:15]
	v_mfma_f32_16x16x32_bf16 v[8:11], v[166:169], v[214:217], v[8:11]
	s_setprio 0
	s_setprio 1
	v_mfma_f32_16x16x32_bf16 v[52:55], v[170:173], v[186:189], 0
	v_mfma_f32_16x16x32_bf16 v[48:51], v[178:181], v[186:189], 0
	v_mfma_f32_16x16x32_bf16 v[36:39], v[170:173], v[194:197], 0
	v_mfma_f32_16x16x32_bf16 v[32:35], v[178:181], v[194:197], 0
	v_mfma_f32_16x16x32_bf16 v[20:23], v[170:173], v[202:205], 0
	v_mfma_f32_16x16x32_bf16 v[16:19], v[178:181], v[202:205], 0
	v_mfma_f32_16x16x32_bf16 v[4:7], v[170:173], v[210:213], 0
	v_mfma_f32_16x16x32_bf16 v[0:3], v[178:181], v[210:213], 0
	v_mfma_f32_16x16x32_bf16 v[52:55], v[174:177], v[190:193], v[52:55]
	v_mfma_f32_16x16x32_bf16 v[48:51], v[182:185], v[190:193], v[48:51]
	v_mfma_f32_16x16x32_bf16 v[36:39], v[174:177], v[198:201], v[36:39]
	v_mfma_f32_16x16x32_bf16 v[32:35], v[182:185], v[198:201], v[32:35]
	v_mfma_f32_16x16x32_bf16 v[20:23], v[174:177], v[206:209], v[20:23]
	v_mfma_f32_16x16x32_bf16 v[16:19], v[182:185], v[206:209], v[16:19]
	v_mfma_f32_16x16x32_bf16 v[4:7], v[174:177], v[214:217], v[4:7]
	v_mfma_f32_16x16x32_bf16 v[0:3], v[182:185], v[214:217], v[0:3]
	s_setprio 0
	s_barrier
	s_add_i32 s61, 0, 0x18000
	v_add_u32_e32 v157, s61, v151
	s_add_i32 s62, 0, 0x1c000
	ds_read_b128 v[146:149], v157
	ds_read_b128 v[158:161], v157 offset:1024
	ds_read_b128 v[162:165], v157 offset:2048
	ds_read_b128 v[166:169], v157 offset:3072
	v_add_u32_e32 v157, s62, v151
	ds_read_b128 v[170:173], v157
	ds_read_b128 v[174:177], v157 offset:1024
	ds_read_b128 v[178:181], v157 offset:2048
	ds_read_b128 v[182:185], v157 offset:3072
	s_add_u32 s34, s42, 0x40000
	s_addc_u32 s35, s43, 0
	s_mov_b32 m0, s48
	v_lshl_add_u64 v[226:227], s[34:35], 0, v[130:131]
	ds_read_b128 v[186:189], v155 offset:32768
	ds_read_b128 v[190:193], v155 offset:33792
	ds_read_b128 v[194:197], v155 offset:34816
	ds_read_b128 v[198:201], v155 offset:35840
	ds_read_b128 v[202:205], v155 offset:36864
	ds_read_b128 v[206:209], v155 offset:37888
	ds_read_b128 v[210:213], v155 offset:38912
	ds_read_b128 v[214:217], v155 offset:39936
	global_load_lds_dwordx4 v[226:227], off
	v_lshl_add_u64 v[226:227], s[34:35], 0, v[134:135]
	s_mov_b32 m0, s49
	s_nop 0
	global_load_lds_dwordx4 v[226:227], off
	s_waitcnt vmcnt(8)
	s_waitcnt lgkmcnt(0)
	s_barrier
	s_setprio 1
	s_waitcnt lgkmcnt(0)
	v_mfma_f32_16x16x32_bf16 v[124:127], v[146:149], v[186:189], v[124:127]
	v_mfma_f32_16x16x32_bf16 v[120:123], v[162:165], v[186:189], v[120:123]
	v_mfma_f32_16x16x32_bf16 v[108:111], v[146:149], v[194:197], v[108:111]
	v_mfma_f32_16x16x32_bf16 v[104:107], v[162:165], v[194:197], v[104:107]
	v_mfma_f32_16x16x32_bf16 v[92:95], v[146:149], v[202:205], v[92:95]
	v_mfma_f32_16x16x32_bf16 v[88:91], v[162:165], v[202:205], v[88:91]
	v_mfma_f32_16x16x32_bf16 v[76:79], v[146:149], v[210:213], v[76:79]
	v_mfma_f32_16x16x32_bf16 v[72:75], v[162:165], v[210:213], v[72:75]
	v_mfma_f32_16x16x32_bf16 v[124:127], v[158:161], v[190:193], v[124:127]
	v_mfma_f32_16x16x32_bf16 v[120:123], v[166:169], v[190:193], v[120:123]
	v_mfma_f32_16x16x32_bf16 v[108:111], v[158:161], v[198:201], v[108:111]
	v_mfma_f32_16x16x32_bf16 v[104:107], v[166:169], v[198:201], v[104:107]
	v_mfma_f32_16x16x32_bf16 v[92:95], v[158:161], v[206:209], v[92:95]
	v_mfma_f32_16x16x32_bf16 v[88:91], v[166:169], v[206:209], v[88:91]
	v_mfma_f32_16x16x32_bf16 v[76:79], v[158:161], v[214:217], v[76:79]
	v_mfma_f32_16x16x32_bf16 v[72:75], v[166:169], v[214:217], v[72:75]
	s_setprio 0
	s_setprio 1
	v_mfma_f32_16x16x32_bf16 v[116:119], v[170:173], v[186:189], v[116:119]
	v_mfma_f32_16x16x32_bf16 v[112:115], v[178:181], v[186:189], v[112:115]
	v_mfma_f32_16x16x32_bf16 v[100:103], v[170:173], v[194:197], v[100:103]
	v_mfma_f32_16x16x32_bf16 v[96:99], v[178:181], v[194:197], v[96:99]
	v_mfma_f32_16x16x32_bf16 v[84:87], v[170:173], v[202:205], v[84:87]
	v_mfma_f32_16x16x32_bf16 v[80:83], v[178:181], v[202:205], v[80:83]
	v_mfma_f32_16x16x32_bf16 v[68:71], v[170:173], v[210:213], v[68:71]
	v_mfma_f32_16x16x32_bf16 v[64:67], v[178:181], v[210:213], v[64:67]
	v_mfma_f32_16x16x32_bf16 v[116:119], v[174:177], v[190:193], v[116:119]
	v_mfma_f32_16x16x32_bf16 v[112:115], v[182:185], v[190:193], v[112:115]
	v_mfma_f32_16x16x32_bf16 v[100:103], v[174:177], v[198:201], v[100:103]
	v_mfma_f32_16x16x32_bf16 v[96:99], v[182:185], v[198:201], v[96:99]
	v_mfma_f32_16x16x32_bf16 v[84:87], v[174:177], v[206:209], v[84:87]
	v_mfma_f32_16x16x32_bf16 v[80:83], v[182:185], v[206:209], v[80:83]
	v_mfma_f32_16x16x32_bf16 v[68:71], v[174:177], v[214:217], v[68:71]
	v_mfma_f32_16x16x32_bf16 v[64:67], v[182:185], v[214:217], v[64:67]
	s_setprio 0
	s_barrier
	s_add_i32 s34, s61, s45
	v_lshl_add_u64 v[218:219], v[218:219], 0, s[10:11]
	s_mov_b32 m0, s34
	ds_read_b128 v[186:189], v155 offset:49152
	ds_read_b128 v[190:193], v155 offset:50176
	ds_read_b128 v[194:197], v155 offset:51200
	ds_read_b128 v[198:201], v155 offset:52224
	ds_read_b128 v[202:205], v155 offset:53248
	ds_read_b128 v[206:209], v155 offset:54272
	ds_read_b128 v[210:213], v155 offset:55296
	ds_read_b128 v[214:217], v155 offset:56320
	global_load_lds_dwordx4 v[218:219], off
	s_add_i32 m0, s34, 0x2000
	s_add_u32 s34, s40, 0x40080
	v_lshl_add_u64 v[218:219], v[220:221], 0, s[10:11]
	s_addc_u32 s35, s41, 0
	s_add_i32 s40, s62, s45
	global_load_lds_dwordx4 v[218:219], off
	v_lshl_add_u64 v[218:219], s[34:35], 0, v[132:133]
	s_mov_b32 m0, s40
	s_nop 0
	global_load_lds_dwordx4 v[218:219], off
	v_lshl_add_u64 v[218:219], s[34:35], 0, v[136:137]
	s_add_i32 m0, s40, 0x2000
	s_nop 0
	global_load_lds_dwordx4 v[218:219], off
	v_lshl_add_u64 v[218:219], v[222:223], 0, s[10:11]
	s_mov_b32 m0, s51
	s_nop 0
	global_load_lds_dwordx4 v[218:219], off
	v_lshl_add_u64 v[218:219], v[224:225], 0, s[10:11]
	s_mov_b32 m0, s52
	s_nop 0
	global_load_lds_dwordx4 v[218:219], off
	s_waitcnt vmcnt(8)
	s_waitcnt lgkmcnt(0)
	s_barrier
	s_setprio 1
	s_waitcnt lgkmcnt(0)
	v_mfma_f32_16x16x32_bf16 v[60:63], v[146:149], v[186:189], v[60:63]
	v_mfma_f32_16x16x32_bf16 v[56:59], v[162:165], v[186:189], v[56:59]
	v_mfma_f32_16x16x32_bf16 v[44:47], v[146:149], v[194:197], v[44:47]
	v_mfma_f32_16x16x32_bf16 v[40:43], v[162:165], v[194:197], v[40:43]
	v_mfma_f32_16x16x32_bf16 v[28:31], v[146:149], v[202:205], v[28:31]
	v_mfma_f32_16x16x32_bf16 v[24:27], v[162:165], v[202:205], v[24:27]
	v_mfma_f32_16x16x32_bf16 v[12:15], v[146:149], v[210:213], v[12:15]
	v_mfma_f32_16x16x32_bf16 v[8:11], v[162:165], v[210:213], v[8:11]
	v_mfma_f32_16x16x32_bf16 v[60:63], v[158:161], v[190:193], v[60:63]
	v_mfma_f32_16x16x32_bf16 v[56:59], v[166:169], v[190:193], v[56:59]
	v_mfma_f32_16x16x32_bf16 v[44:47], v[158:161], v[198:201], v[44:47]
	v_mfma_f32_16x16x32_bf16 v[40:43], v[166:169], v[198:201], v[40:43]
	v_mfma_f32_16x16x32_bf16 v[28:31], v[158:161], v[206:209], v[28:31]
	v_mfma_f32_16x16x32_bf16 v[24:27], v[166:169], v[206:209], v[24:27]
	v_mfma_f32_16x16x32_bf16 v[12:15], v[158:161], v[214:217], v[12:15]
	v_mfma_f32_16x16x32_bf16 v[8:11], v[166:169], v[214:217], v[8:11]
	s_setprio 0
	s_setprio 1
	v_mfma_f32_16x16x32_bf16 v[52:55], v[170:173], v[186:189], v[52:55]
	v_mfma_f32_16x16x32_bf16 v[48:51], v[178:181], v[186:189], v[48:51]
	v_mfma_f32_16x16x32_bf16 v[36:39], v[170:173], v[194:197], v[36:39]
	v_mfma_f32_16x16x32_bf16 v[32:35], v[178:181], v[194:197], v[32:35]
	v_mfma_f32_16x16x32_bf16 v[20:23], v[170:173], v[202:205], v[20:23]
	v_mfma_f32_16x16x32_bf16 v[16:19], v[178:181], v[202:205], v[16:19]
	v_mfma_f32_16x16x32_bf16 v[4:7], v[170:173], v[210:213], v[4:7]
	v_mfma_f32_16x16x32_bf16 v[0:3], v[178:181], v[210:213], v[0:3]
	v_mfma_f32_16x16x32_bf16 v[52:55], v[174:177], v[190:193], v[52:55]
	v_mfma_f32_16x16x32_bf16 v[48:51], v[182:185], v[190:193], v[48:51]
	v_mfma_f32_16x16x32_bf16 v[36:39], v[174:177], v[198:201], v[36:39]
	v_mfma_f32_16x16x32_bf16 v[32:35], v[182:185], v[198:201], v[32:35]
	v_mfma_f32_16x16x32_bf16 v[20:23], v[174:177], v[206:209], v[20:23]
	v_mfma_f32_16x16x32_bf16 v[16:19], v[182:185], v[206:209], v[16:19]
	v_mfma_f32_16x16x32_bf16 v[4:7], v[174:177], v[214:217], v[4:7]
	v_mfma_f32_16x16x32_bf16 v[0:3], v[182:185], v[214:217], v[0:3]
	s_setprio 0
	s_barrier
	s_add_i32 s60, s60, 2
	s_add_u32 s38, s38, 0x100
	s_addc_u32 s39, s39, 0
	s_add_u32 s37, s37, 0x100
	s_addc_u32 s59, s59, 0

.Lmy_nobar2_22:
	ds_read_b128 v[146:149], v153
	ds_read_b128 v[156:159], v153 offset:1024
	ds_read_b128 v[160:163], v153 offset:2048
	ds_read_b128 v[164:167], v153 offset:3072
	ds_read_b128 v[168:171], v154
	ds_read_b128 v[172:175], v154 offset:1024
	ds_read_b128 v[176:179], v154 offset:2048
	ds_read_b128 v[180:183], v154 offset:3072
	s_add_u32 s28, s26, 0xfffc0080
	s_addc_u32 s29, s27, -1
	s_cmp_eq_u32 s56, 12
	s_cselect_b32 s31, s19, s29
	s_cselect_b32 s30, s52, s28
	s_cselect_b32 s29, s11, s55
	s_cselect_b32 s28, s53, s54
	v_lshl_add_u64 v[216:217], s[26:27], 0, v[138:139]
	s_add_i32 m0, s25, 0xc000
	ds_read_b128 v[184:187], v155
	ds_read_b128 v[188:191], v155 offset:1024
	ds_read_b128 v[192:195], v155 offset:2048
	ds_read_b128 v[196:199], v155 offset:3072
	ds_read_b128 v[200:203], v155 offset:4096
	ds_read_b128 v[204:207], v155 offset:5120
	ds_read_b128 v[208:211], v155 offset:6144
	ds_read_b128 v[212:215], v155 offset:7168
	global_load_lds_dwordx4 v[216:217], off
	v_lshl_add_u64 v[216:217], s[26:27], 0, v[140:141]
	s_add_i32 m0, s25, 0xe000
	s_nop 0
	global_load_lds_dwordx4 v[216:217], off
	s_cmp_eq_u32 s50, 1
	s_cbranch_scc1 .Lmy_sw_22_0a
	s_waitcnt vmcnt(16)
	s_branch .Lmy_sw_22_0b

.Lmy_sw_22_0b:
	s_waitcnt lgkmcnt(0)
	s_barrier
	s_setprio 1
	s_waitcnt lgkmcnt(0)
	v_mfma_f32_16x16x32_bf16 v[124:127], v[146:149], v[184:187], 0
	v_mfma_f32_16x16x32_bf16 v[120:123], v[160:163], v[184:187], 0
	v_mfma_f32_16x16x32_bf16 v[108:111], v[146:149], v[192:195], 0
	v_mfma_f32_16x16x32_bf16 v[104:107], v[160:163], v[192:195], 0
	v_mfma_f32_16x16x32_bf16 v[92:95], v[146:149], v[200:203], 0
	v_mfma_f32_16x16x32_bf16 v[88:91], v[160:163], v[200:203], 0
	v_mfma_f32_16x16x32_bf16 v[76:79], v[146:149], v[208:211], 0
	v_mfma_f32_16x16x32_bf16 v[72:75], v[160:163], v[208:211], 0
	v_mfma_f32_16x16x32_bf16 v[124:127], v[156:159], v[188:191], v[124:127]
	v_mfma_f32_16x16x32_bf16 v[120:123], v[164:167], v[188:191], v[120:123]
	v_mfma_f32_16x16x32_bf16 v[108:111], v[156:159], v[196:199], v[108:111]
	v_mfma_f32_16x16x32_bf16 v[104:107], v[164:167], v[196:199], v[104:107]
	v_mfma_f32_16x16x32_bf16 v[92:95], v[156:159], v[204:207], v[92:95]
	v_mfma_f32_16x16x32_bf16 v[88:91], v[164:167], v[204:207], v[88:91]
	v_mfma_f32_16x16x32_bf16 v[76:79], v[156:159], v[212:215], v[76:79]
	v_mfma_f32_16x16x32_bf16 v[72:75], v[164:167], v[212:215], v[72:75]
	s_setprio 0
	s_setprio 1
	v_mfma_f32_16x16x32_bf16 v[116:119], v[168:171], v[184:187], 0
	v_mfma_f32_16x16x32_bf16 v[112:115], v[176:179], v[184:187], 0
	v_mfma_f32_16x16x32_bf16 v[100:103], v[168:171], v[192:195], 0
	v_mfma_f32_16x16x32_bf16 v[96:99], v[176:179], v[192:195], 0
	v_mfma_f32_16x16x32_bf16 v[84:87], v[168:171], v[200:203], 0
	v_mfma_f32_16x16x32_bf16 v[80:83], v[176:179], v[200:203], 0
	v_mfma_f32_16x16x32_bf16 v[68:71], v[168:171], v[208:211], 0
	v_mfma_f32_16x16x32_bf16 v[64:67], v[176:179], v[208:211], 0
	v_mfma_f32_16x16x32_bf16 v[116:119], v[172:175], v[188:191], v[116:119]
	v_mfma_f32_16x16x32_bf16 v[112:115], v[180:183], v[188:191], v[112:115]
	v_mfma_f32_16x16x32_bf16 v[100:103], v[172:175], v[196:199], v[100:103]
	v_mfma_f32_16x16x32_bf16 v[96:99], v[180:183], v[196:199], v[96:99]
	v_mfma_f32_16x16x32_bf16 v[84:87], v[172:175], v[204:207], v[84:87]
	v_mfma_f32_16x16x32_bf16 v[80:83], v[180:183], v[204:207], v[80:83]
	v_mfma_f32_16x16x32_bf16 v[68:71], v[172:175], v[212:215], v[68:71]
	v_mfma_f32_16x16x32_bf16 v[64:67], v[180:183], v[212:215], v[64:67]
	s_setprio 0
	s_barrier
	s_add_i32 s34, s47, s38
	v_lshl_add_u64 v[216:217], s[28:29], 0, v[134:135]
	s_mov_b32 m0, s34
	ds_read_b128 v[184:187], v155 offset:16384
	ds_read_b128 v[188:191], v155 offset:17408
	ds_read_b128 v[192:195], v155 offset:18432
	ds_read_b128 v[196:199], v155 offset:19456
	ds_read_b128 v[200:203], v155 offset:20480
	ds_read_b128 v[204:207], v155 offset:21504
	ds_read_b128 v[208:211], v155 offset:22528
	ds_read_b128 v[212:215], v155 offset:23552
	global_load_lds_dwordx4 v[216:217], off
	s_add_i32 m0, s34, 0x2000
	s_add_u32 s34, s28, 0x40000
	v_lshl_add_u64 v[218:219], s[28:29], 0, v[130:131]
	s_addc_u32 s35, s29, 0
	s_add_i32 s57, s48, s38
	global_load_lds_dwordx4 v[218:219], off
	v_lshl_add_u64 v[220:221], s[34:35], 0, v[134:135]
	s_mov_b32 m0, s57
	v_lshl_add_u64 v[222:223], s[30:31], 0, v[132:133]
	global_load_lds_dwordx4 v[220:221], off
	v_lshl_add_u64 v[220:221], s[34:35], 0, v[130:131]
	s_add_i32 m0, s57, 0x2000
	s_nop 0
	global_load_lds_dwordx4 v[220:221], off
	v_lshl_add_u64 v[220:221], s[30:31], 0, v[136:137]
	s_mov_b32 m0, s25
	s_nop 0
	global_load_lds_dwordx4 v[220:221], off
	s_mov_b32 m0, s42
	s_nop 0
	global_load_lds_dwordx4 v[222:223], off
	s_cmp_eq_u32 s50, 1
	s_cbranch_scc1 .Lmy_sw_22_1a
	s_waitcnt vmcnt(16)
	s_branch .Lmy_sw_22_1b

.Lmy_sw_22_1b:
	s_waitcnt lgkmcnt(0)
	s_barrier
	s_setprio 1
	s_waitcnt lgkmcnt(0)
	v_mfma_f32_16x16x32_bf16 v[60:63], v[146:149], v[184:187], 0
	v_mfma_f32_16x16x32_bf16 v[56:59], v[160:163], v[184:187], 0
	v_mfma_f32_16x16x32_bf16 v[44:47], v[146:149], v[192:195], 0
	v_mfma_f32_16x16x32_bf16 v[40:43], v[160:163], v[192:195], 0
	v_mfma_f32_16x16x32_bf16 v[28:31], v[146:149], v[200:203], 0
	v_mfma_f32_16x16x32_bf16 v[24:27], v[160:163], v[200:203], 0
	v_mfma_f32_16x16x32_bf16 v[12:15], v[146:149], v[208:211], 0
	v_mfma_f32_16x16x32_bf16 v[8:11], v[160:163], v[208:211], 0
	v_mfma_f32_16x16x32_bf16 v[60:63], v[156:159], v[188:191], v[60:63]
	v_mfma_f32_16x16x32_bf16 v[56:59], v[164:167], v[188:191], v[56:59]
	v_mfma_f32_16x16x32_bf16 v[44:47], v[156:159], v[196:199], v[44:47]
	v_mfma_f32_16x16x32_bf16 v[40:43], v[164:167], v[196:199], v[40:43]
	v_mfma_f32_16x16x32_bf16 v[28:31], v[156:159], v[204:207], v[28:31]
	v_mfma_f32_16x16x32_bf16 v[24:27], v[164:167], v[204:207], v[24:27]
	v_mfma_f32_16x16x32_bf16 v[12:15], v[156:159], v[212:215], v[12:15]
	v_mfma_f32_16x16x32_bf16 v[8:11], v[164:167], v[212:215], v[8:11]
	s_setprio 0
	s_setprio 1
	v_mfma_f32_16x16x32_bf16 v[52:55], v[168:171], v[184:187], 0
	v_mfma_f32_16x16x32_bf16 v[48:51], v[176:179], v[184:187], 0
	v_mfma_f32_16x16x32_bf16 v[36:39], v[168:171], v[192:195], 0
	v_mfma_f32_16x16x32_bf16 v[32:35], v[176:179], v[192:195], 0
	v_mfma_f32_16x16x32_bf16 v[20:23], v[168:171], v[200:203], 0
	v_mfma_f32_16x16x32_bf16 v[16:19], v[176:179], v[200:203], 0
	v_mfma_f32_16x16x32_bf16 v[4:7], v[168:171], v[208:211], 0
	v_mfma_f32_16x16x32_bf16 v[0:3], v[176:179], v[208:211], 0
	v_mfma_f32_16x16x32_bf16 v[52:55], v[172:175], v[188:191], v[52:55]
	v_mfma_f32_16x16x32_bf16 v[48:51], v[180:183], v[188:191], v[48:51]
	v_mfma_f32_16x16x32_bf16 v[36:39], v[172:175], v[196:199], v[36:39]
	v_mfma_f32_16x16x32_bf16 v[32:35], v[180:183], v[196:199], v[32:35]
	v_mfma_f32_16x16x32_bf16 v[20:23], v[172:175], v[204:207], v[20:23]
	v_mfma_f32_16x16x32_bf16 v[16:19], v[180:183], v[204:207], v[16:19]
	v_mfma_f32_16x16x32_bf16 v[4:7], v[172:175], v[212:215], v[4:7]
	v_mfma_f32_16x16x32_bf16 v[0:3], v[180:183], v[212:215], v[0:3]
	s_setprio 0
	s_barrier
	s_add_i32 s34, 0, 0x18000
	s_add_i32 s35, 0, 0x1c000
	v_add_u32_e32 v164, s34, v150
	v_add_u32_e32 v180, s35, v150
	ds_read_b128 v[146:149], v164
	ds_read_b128 v[156:159], v164 offset:1024
	ds_read_b128 v[160:163], v164 offset:2048
	ds_read_b128 v[164:167], v164 offset:3072
	ds_read_b128 v[168:171], v180
	ds_read_b128 v[172:175], v180 offset:1024
	ds_read_b128 v[176:179], v180 offset:2048
	ds_read_b128 v[180:183], v180 offset:3072
	s_add_u32 s30, s30, 0x40000
	s_addc_u32 s31, s31, 0
	s_mov_b32 m0, s43
	v_lshl_add_u64 v[224:225], s[30:31], 0, v[136:137]
	ds_read_b128 v[184:187], v155 offset:32768
	ds_read_b128 v[188:191], v155 offset:33792
	ds_read_b128 v[192:195], v155 offset:34816
	ds_read_b128 v[196:199], v155 offset:35840
	ds_read_b128 v[200:203], v155 offset:36864
	ds_read_b128 v[204:207], v155 offset:37888
	ds_read_b128 v[208:211], v155 offset:38912
	ds_read_b128 v[212:215], v155 offset:39936
	global_load_lds_dwordx4 v[224:225], off
	v_lshl_add_u64 v[224:225], s[30:31], 0, v[132:133]
	s_mov_b32 m0, s44
	s_nop 0
	global_load_lds_dwordx4 v[224:225], off
	s_waitcnt vmcnt(8)
	s_waitcnt lgkmcnt(0)
	s_barrier
	s_setprio 1
	s_waitcnt lgkmcnt(0)
	v_mfma_f32_16x16x32_bf16 v[124:127], v[146:149], v[184:187], v[124:127]
	v_mfma_f32_16x16x32_bf16 v[120:123], v[160:163], v[184:187], v[120:123]
	v_mfma_f32_16x16x32_bf16 v[108:111], v[146:149], v[192:195], v[108:111]
	v_mfma_f32_16x16x32_bf16 v[104:107], v[160:163], v[192:195], v[104:107]
	v_mfma_f32_16x16x32_bf16 v[92:95], v[146:149], v[200:203], v[92:95]
	v_mfma_f32_16x16x32_bf16 v[88:91], v[160:163], v[200:203], v[88:91]
	v_mfma_f32_16x16x32_bf16 v[76:79], v[146:149], v[208:211], v[76:79]
	v_mfma_f32_16x16x32_bf16 v[72:75], v[160:163], v[208:211], v[72:75]
	v_mfma_f32_16x16x32_bf16 v[124:127], v[156:159], v[188:191], v[124:127]
	v_mfma_f32_16x16x32_bf16 v[120:123], v[164:167], v[188:191], v[120:123]
	v_mfma_f32_16x16x32_bf16 v[108:111], v[156:159], v[196:199], v[108:111]
	v_mfma_f32_16x16x32_bf16 v[104:107], v[164:167], v[196:199], v[104:107]
	v_mfma_f32_16x16x32_bf16 v[92:95], v[156:159], v[204:207], v[92:95]
	v_mfma_f32_16x16x32_bf16 v[88:91], v[164:167], v[204:207], v[88:91]
	v_mfma_f32_16x16x32_bf16 v[76:79], v[156:159], v[212:215], v[76:79]
	v_mfma_f32_16x16x32_bf16 v[72:75], v[164:167], v[212:215], v[72:75]
	s_setprio 0
	s_setprio 1
	v_mfma_f32_16x16x32_bf16 v[116:119], v[168:171], v[184:187], v[116:119]
	v_mfma_f32_16x16x32_bf16 v[112:115], v[176:179], v[184:187], v[112:115]
	v_mfma_f32_16x16x32_bf16 v[100:103], v[168:171], v[192:195], v[100:103]
	v_mfma_f32_16x16x32_bf16 v[96:99], v[176:179], v[192:195], v[96:99]
	v_mfma_f32_16x16x32_bf16 v[84:87], v[168:171], v[200:203], v[84:87]
	v_mfma_f32_16x16x32_bf16 v[80:83], v[176:179], v[200:203], v[80:83]
	v_mfma_f32_16x16x32_bf16 v[68:71], v[168:171], v[208:211], v[68:71]
	v_mfma_f32_16x16x32_bf16 v[64:67], v[176:179], v[208:211], v[64:67]
	v_mfma_f32_16x16x32_bf16 v[116:119], v[172:175], v[188:191], v[116:119]
	v_mfma_f32_16x16x32_bf16 v[112:115], v[180:183], v[188:191], v[112:115]
	v_mfma_f32_16x16x32_bf16 v[100:103], v[172:175], v[196:199], v[100:103]
	v_mfma_f32_16x16x32_bf16 v[96:99], v[180:183], v[196:199], v[96:99]
	v_mfma_f32_16x16x32_bf16 v[84:87], v[172:175], v[204:207], v[84:87]
	v_mfma_f32_16x16x32_bf16 v[80:83], v[180:183], v[204:207], v[80:83]
	v_mfma_f32_16x16x32_bf16 v[68:71], v[172:175], v[212:215], v[68:71]
	v_mfma_f32_16x16x32_bf16 v[64:67], v[180:183], v[212:215], v[64:67]
	s_setprio 0
	s_barrier
	s_add_i32 s30, s34, s38
	v_lshl_add_u64 v[216:217], v[216:217], 0, s[6:7]
	s_mov_b32 m0, s30
	ds_read_b128 v[184:187], v155 offset:49152
	ds_read_b128 v[188:191], v155 offset:50176
	ds_read_b128 v[192:195], v155 offset:51200
	ds_read_b128 v[196:199], v155 offset:52224
	ds_read_b128 v[200:203], v155 offset:53248
	ds_read_b128 v[204:207], v155 offset:54272
	ds_read_b128 v[208:211], v155 offset:55296
	ds_read_b128 v[212:215], v155 offset:56320
	global_load_lds_dwordx4 v[216:217], off
	s_add_i32 m0, s30, 0x2000
	s_add_u32 s28, s28, 0x40080
	v_lshl_add_u64 v[216:217], v[218:219], 0, s[6:7]
	s_addc_u32 s29, s29, 0
	s_add_i32 s30, s35, s38
	global_load_lds_dwordx4 v[216:217], off
	v_lshl_add_u64 v[216:217], s[28:29], 0, v[134:135]
	s_mov_b32 m0, s30
	s_nop 0
	global_load_lds_dwordx4 v[216:217], off
	v_lshl_add_u64 v[216:217], s[28:29], 0, v[130:131]
	s_add_i32 m0, s30, 0x2000
	s_nop 0
	global_load_lds_dwordx4 v[216:217], off
	v_lshl_add_u64 v[216:217], v[220:221], 0, s[6:7]
	s_mov_b32 m0, s45
	s_nop 0
	global_load_lds_dwordx4 v[216:217], off
	v_lshl_add_u64 v[216:217], v[222:223], 0, s[6:7]
	s_mov_b32 m0, s46
	s_nop 0
	global_load_lds_dwordx4 v[216:217], off
	s_waitcnt vmcnt(8)
	s_waitcnt lgkmcnt(0)
	s_barrier
	s_setprio 1
	s_waitcnt lgkmcnt(0)
	v_mfma_f32_16x16x32_bf16 v[60:63], v[146:149], v[184:187], v[60:63]
	v_mfma_f32_16x16x32_bf16 v[56:59], v[160:163], v[184:187], v[56:59]
	v_mfma_f32_16x16x32_bf16 v[44:47], v[146:149], v[192:195], v[44:47]
	v_mfma_f32_16x16x32_bf16 v[40:43], v[160:163], v[192:195], v[40:43]
	v_mfma_f32_16x16x32_bf16 v[28:31], v[146:149], v[200:203], v[28:31]
	v_mfma_f32_16x16x32_bf16 v[24:27], v[160:163], v[200:203], v[24:27]
	v_mfma_f32_16x16x32_bf16 v[12:15], v[146:149], v[208:211], v[12:15]
	v_mfma_f32_16x16x32_bf16 v[8:11], v[160:163], v[208:211], v[8:11]
	v_mfma_f32_16x16x32_bf16 v[60:63], v[156:159], v[188:191], v[60:63]
	v_mfma_f32_16x16x32_bf16 v[56:59], v[164:167], v[188:191], v[56:59]
	v_mfma_f32_16x16x32_bf16 v[44:47], v[156:159], v[196:199], v[44:47]
	v_mfma_f32_16x16x32_bf16 v[40:43], v[164:167], v[196:199], v[40:43]
	v_mfma_f32_16x16x32_bf16 v[28:31], v[156:159], v[204:207], v[28:31]
	v_mfma_f32_16x16x32_bf16 v[24:27], v[164:167], v[204:207], v[24:27]
	v_mfma_f32_16x16x32_bf16 v[12:15], v[156:159], v[212:215], v[12:15]
	v_mfma_f32_16x16x32_bf16 v[8:11], v[164:167], v[212:215], v[8:11]
	s_setprio 0
	s_setprio 1
	v_mfma_f32_16x16x32_bf16 v[52:55], v[168:171], v[184:187], v[52:55]
	v_mfma_f32_16x16x32_bf16 v[48:51], v[176:179], v[184:187], v[48:51]
	v_mfma_f32_16x16x32_bf16 v[36:39], v[168:171], v[192:195], v[36:39]
	v_mfma_f32_16x16x32_bf16 v[32:35], v[176:179], v[192:195], v[32:35]
	v_mfma_f32_16x16x32_bf16 v[20:23], v[168:171], v[200:203], v[20:23]
	v_mfma_f32_16x16x32_bf16 v[16:19], v[176:179], v[200:203], v[16:19]
	v_mfma_f32_16x16x32_bf16 v[4:7], v[168:171], v[208:211], v[4:7]
	v_mfma_f32_16x16x32_bf16 v[0:3], v[176:179], v[208:211], v[0:3]
	v_mfma_f32_16x16x32_bf16 v[52:55], v[172:175], v[188:191], v[52:55]
	v_mfma_f32_16x16x32_bf16 v[48:51], v[180:183], v[188:191], v[48:51]
	v_mfma_f32_16x16x32_bf16 v[36:39], v[172:175], v[196:199], v[36:39]
	v_mfma_f32_16x16x32_bf16 v[32:35], v[180:183], v[196:199], v[32:35]
	v_mfma_f32_16x16x32_bf16 v[20:23], v[172:175], v[204:207], v[20:23]
	v_mfma_f32_16x16x32_bf16 v[16:19], v[180:183], v[204:207], v[16:19]
	v_mfma_f32_16x16x32_bf16 v[4:7], v[172:175], v[212:215], v[4:7]
	v_mfma_f32_16x16x32_bf16 v[0:3], v[180:183], v[212:215], v[0:3]
	s_setprio 0
	s_barrier
	s_add_i32 s56, s56, 2
	s_add_u32 s26, s26, 0x100
	s_addc_u32 s27, s27, 0
	s_add_u32 s54, s54, 0x100
	s_addc_u32 s55, s55, 0

.Lmy_nobar2_23:
	ds_read_b128 v[144:147], v153
	ds_read_b128 v[156:159], v153 offset:1024
	ds_read_b128 v[160:163], v153 offset:2048
	ds_read_b128 v[164:167], v153 offset:3072
	ds_read_b128 v[168:171], v154
	ds_read_b128 v[172:175], v154 offset:1024
	ds_read_b128 v[176:179], v154 offset:2048
	ds_read_b128 v[180:183], v154 offset:3072
	s_add_u32 s30, s28, 0xfff50080
	s_addc_u32 s31, s29, -1
	s_cmp_eq_u32 s56, 40
	s_cselect_b32 s37, s1, s31
	s_cselect_b32 s36, s0, s30
	s_cselect_b32 s31, s27, s55
	s_cselect_b32 s30, s26, s54
	v_lshl_add_u64 v[148:149], s[28:29], 0, v[128:129]
	s_add_i32 m0, s41, 0xc000
	ds_read_b128 v[184:187], v155
	ds_read_b128 v[188:191], v155 offset:1024
	ds_read_b128 v[192:195], v155 offset:2048
	ds_read_b128 v[196:199], v155 offset:3072
	ds_read_b128 v[200:203], v155 offset:4096
	ds_read_b128 v[204:207], v155 offset:5120
	ds_read_b128 v[208:211], v155 offset:6144
	ds_read_b128 v[212:215], v155 offset:7168
	global_load_lds_dwordx4 v[148:149], off
	v_lshl_add_u64 v[148:149], s[28:29], 0, v[138:139]
	s_add_i32 m0, s41, 0xe000
	s_nop 0
	global_load_lds_dwordx4 v[148:149], off
	s_cmp_eq_u32 s45, 1
	s_cbranch_scc1 .Lmy_sw_23_0a
	s_waitcnt vmcnt(48)
	s_branch .Lmy_sw_23_0b

.Lmy_sw_23_0b:
	s_waitcnt lgkmcnt(0)
	s_barrier
	s_setprio 1
	s_waitcnt lgkmcnt(0)
	v_mfma_f32_16x16x32_bf16 v[124:127], v[144:147], v[184:187], 0
	v_mfma_f32_16x16x32_bf16 v[120:123], v[160:163], v[184:187], 0
	v_mfma_f32_16x16x32_bf16 v[108:111], v[144:147], v[192:195], 0
	v_mfma_f32_16x16x32_bf16 v[104:107], v[160:163], v[192:195], 0
	v_mfma_f32_16x16x32_bf16 v[92:95], v[144:147], v[200:203], 0
	v_mfma_f32_16x16x32_bf16 v[88:91], v[160:163], v[200:203], 0
	v_mfma_f32_16x16x32_bf16 v[76:79], v[144:147], v[208:211], 0
	v_mfma_f32_16x16x32_bf16 v[72:75], v[160:163], v[208:211], 0
	v_mfma_f32_16x16x32_bf16 v[124:127], v[156:159], v[188:191], v[124:127]
	v_mfma_f32_16x16x32_bf16 v[120:123], v[164:167], v[188:191], v[120:123]
	v_mfma_f32_16x16x32_bf16 v[108:111], v[156:159], v[196:199], v[108:111]
	v_mfma_f32_16x16x32_bf16 v[104:107], v[164:167], v[196:199], v[104:107]
	v_mfma_f32_16x16x32_bf16 v[92:95], v[156:159], v[204:207], v[92:95]
	v_mfma_f32_16x16x32_bf16 v[88:91], v[164:167], v[204:207], v[88:91]
	v_mfma_f32_16x16x32_bf16 v[76:79], v[156:159], v[212:215], v[76:79]
	v_mfma_f32_16x16x32_bf16 v[72:75], v[164:167], v[212:215], v[72:75]
	s_setprio 0
	s_setprio 1
	v_mfma_f32_16x16x32_bf16 v[116:119], v[168:171], v[184:187], 0
	v_mfma_f32_16x16x32_bf16 v[112:115], v[176:179], v[184:187], 0
	v_mfma_f32_16x16x32_bf16 v[100:103], v[168:171], v[192:195], 0
	v_mfma_f32_16x16x32_bf16 v[96:99], v[176:179], v[192:195], 0
	v_mfma_f32_16x16x32_bf16 v[84:87], v[168:171], v[200:203], 0
	v_mfma_f32_16x16x32_bf16 v[80:83], v[176:179], v[200:203], 0
	v_mfma_f32_16x16x32_bf16 v[68:71], v[168:171], v[208:211], 0
	v_mfma_f32_16x16x32_bf16 v[64:67], v[176:179], v[208:211], 0
	v_mfma_f32_16x16x32_bf16 v[116:119], v[172:175], v[188:191], v[116:119]
	v_mfma_f32_16x16x32_bf16 v[112:115], v[180:183], v[188:191], v[112:115]
	v_mfma_f32_16x16x32_bf16 v[100:103], v[172:175], v[196:199], v[100:103]
	v_mfma_f32_16x16x32_bf16 v[96:99], v[180:183], v[196:199], v[96:99]
	v_mfma_f32_16x16x32_bf16 v[84:87], v[172:175], v[204:207], v[84:87]
	v_mfma_f32_16x16x32_bf16 v[80:83], v[180:183], v[204:207], v[80:83]
	v_mfma_f32_16x16x32_bf16 v[68:71], v[172:175], v[212:215], v[68:71]
	v_mfma_f32_16x16x32_bf16 v[64:67], v[180:183], v[212:215], v[64:67]
	s_setprio 0
	s_barrier
	s_add_i32 s34, s50, s40
	v_lshl_add_u64 v[148:149], s[30:31], 0, v[132:133]
	s_mov_b32 m0, s34
	ds_read_b128 v[184:187], v155 offset:16384
	ds_read_b128 v[188:191], v155 offset:17408
	ds_read_b128 v[192:195], v155 offset:18432
	ds_read_b128 v[196:199], v155 offset:19456
	ds_read_b128 v[200:203], v155 offset:20480
	ds_read_b128 v[204:207], v155 offset:21504
	ds_read_b128 v[208:211], v155 offset:22528
	ds_read_b128 v[212:215], v155 offset:23552
	global_load_lds_dwordx4 v[148:149], off
	s_add_i32 m0, s34, 0x2000
	s_add_u32 s34, s30, 0xb0000
	v_lshl_add_u64 v[216:217], s[30:31], 0, v[136:137]
	s_addc_u32 s35, s31, 0
	s_add_i32 s57, s51, s40
	global_load_lds_dwordx4 v[216:217], off
	v_lshl_add_u64 v[218:219], s[34:35], 0, v[132:133]
	s_mov_b32 m0, s57
	v_lshl_add_u64 v[220:221], s[36:37], 0, v[134:135]
	global_load_lds_dwordx4 v[218:219], off
	v_lshl_add_u64 v[218:219], s[34:35], 0, v[136:137]
	s_add_i32 m0, s57, 0x2000
	s_nop 0
	global_load_lds_dwordx4 v[218:219], off
	v_lshl_add_u64 v[218:219], s[36:37], 0, v[130:131]
	s_mov_b32 m0, s41
	s_nop 0
	global_load_lds_dwordx4 v[218:219], off
	s_mov_b32 m0, s42
	s_nop 0
	global_load_lds_dwordx4 v[220:221], off
	s_cmp_eq_u32 s45, 1
	s_cbranch_scc1 .Lmy_sw_23_1a
	s_waitcnt vmcnt(48)
	s_branch .Lmy_sw_23_1b

.Lmy_sw_23_1b:
	s_waitcnt lgkmcnt(0)
	s_barrier
	s_setprio 1
	s_waitcnt lgkmcnt(0)
	v_mfma_f32_16x16x32_bf16 v[60:63], v[144:147], v[184:187], 0
	v_mfma_f32_16x16x32_bf16 v[56:59], v[160:163], v[184:187], 0
	v_mfma_f32_16x16x32_bf16 v[44:47], v[144:147], v[192:195], 0
	v_mfma_f32_16x16x32_bf16 v[40:43], v[160:163], v[192:195], 0
	v_mfma_f32_16x16x32_bf16 v[28:31], v[144:147], v[200:203], 0
	v_mfma_f32_16x16x32_bf16 v[24:27], v[160:163], v[200:203], 0
	v_mfma_f32_16x16x32_bf16 v[12:15], v[144:147], v[208:211], 0
	v_mfma_f32_16x16x32_bf16 v[8:11], v[160:163], v[208:211], 0
	v_mfma_f32_16x16x32_bf16 v[60:63], v[156:159], v[188:191], v[60:63]
	v_mfma_f32_16x16x32_bf16 v[56:59], v[164:167], v[188:191], v[56:59]
	v_mfma_f32_16x16x32_bf16 v[44:47], v[156:159], v[196:199], v[44:47]
	v_mfma_f32_16x16x32_bf16 v[40:43], v[164:167], v[196:199], v[40:43]
	v_mfma_f32_16x16x32_bf16 v[28:31], v[156:159], v[204:207], v[28:31]
	v_mfma_f32_16x16x32_bf16 v[24:27], v[164:167], v[204:207], v[24:27]
	v_mfma_f32_16x16x32_bf16 v[12:15], v[156:159], v[212:215], v[12:15]
	v_mfma_f32_16x16x32_bf16 v[8:11], v[164:167], v[212:215], v[8:11]
	s_setprio 0
	s_setprio 1
	v_mfma_f32_16x16x32_bf16 v[52:55], v[168:171], v[184:187], 0
	v_mfma_f32_16x16x32_bf16 v[48:51], v[176:179], v[184:187], 0
	v_mfma_f32_16x16x32_bf16 v[36:39], v[168:171], v[192:195], 0
	v_mfma_f32_16x16x32_bf16 v[32:35], v[176:179], v[192:195], 0
	v_mfma_f32_16x16x32_bf16 v[20:23], v[168:171], v[200:203], 0
	v_mfma_f32_16x16x32_bf16 v[16:19], v[176:179], v[200:203], 0
	v_mfma_f32_16x16x32_bf16 v[4:7], v[168:171], v[208:211], 0
	v_mfma_f32_16x16x32_bf16 v[0:3], v[176:179], v[208:211], 0
	v_mfma_f32_16x16x32_bf16 v[52:55], v[172:175], v[188:191], v[52:55]
	v_mfma_f32_16x16x32_bf16 v[48:51], v[180:183], v[188:191], v[48:51]
	v_mfma_f32_16x16x32_bf16 v[36:39], v[172:175], v[196:199], v[36:39]
	v_mfma_f32_16x16x32_bf16 v[32:35], v[180:183], v[196:199], v[32:35]
	v_mfma_f32_16x16x32_bf16 v[20:23], v[172:175], v[204:207], v[20:23]
	v_mfma_f32_16x16x32_bf16 v[16:19], v[180:183], v[204:207], v[16:19]
	v_mfma_f32_16x16x32_bf16 v[4:7], v[172:175], v[212:215], v[4:7]
	v_mfma_f32_16x16x32_bf16 v[0:3], v[180:183], v[212:215], v[0:3]
	s_setprio 0
	s_barrier
	s_add_i32 s57, 0, 0x18000
	s_add_i32 s58, 0, 0x1c000
	v_add_u32_e32 v164, s57, v151
	v_add_u32_e32 v180, s58, v151
	ds_read_b128 v[144:147], v164
	ds_read_b128 v[156:159], v164 offset:1024
	ds_read_b128 v[160:163], v164 offset:2048
	ds_read_b128 v[164:167], v164 offset:3072
	ds_read_b128 v[168:171], v180
	ds_read_b128 v[172:175], v180 offset:1024
	ds_read_b128 v[176:179], v180 offset:2048
	ds_read_b128 v[180:183], v180 offset:3072
	s_add_u32 s34, s36, 0xb0000
	s_addc_u32 s35, s37, 0
	s_mov_b32 m0, s43
	v_lshl_add_u64 v[222:223], s[34:35], 0, v[130:131]
	ds_read_b128 v[184:187], v155 offset:32768
	ds_read_b128 v[188:191], v155 offset:33792
	ds_read_b128 v[192:195], v155 offset:34816
	ds_read_b128 v[196:199], v155 offset:35840
	ds_read_b128 v[200:203], v155 offset:36864
	ds_read_b128 v[204:207], v155 offset:37888
	ds_read_b128 v[208:211], v155 offset:38912
	ds_read_b128 v[212:215], v155 offset:39936
	global_load_lds_dwordx4 v[222:223], off
	v_lshl_add_u64 v[222:223], s[34:35], 0, v[134:135]
	s_mov_b32 m0, s44
	s_nop 0
	global_load_lds_dwordx4 v[222:223], off
	s_waitcnt vmcnt(8)
	s_waitcnt lgkmcnt(0)
	s_barrier
	s_setprio 1
	s_waitcnt lgkmcnt(0)
	v_mfma_f32_16x16x32_bf16 v[124:127], v[144:147], v[184:187], v[124:127]
	v_mfma_f32_16x16x32_bf16 v[120:123], v[160:163], v[184:187], v[120:123]
	v_mfma_f32_16x16x32_bf16 v[108:111], v[144:147], v[192:195], v[108:111]
	v_mfma_f32_16x16x32_bf16 v[104:107], v[160:163], v[192:195], v[104:107]
	v_mfma_f32_16x16x32_bf16 v[92:95], v[144:147], v[200:203], v[92:95]
	v_mfma_f32_16x16x32_bf16 v[88:91], v[160:163], v[200:203], v[88:91]
	v_mfma_f32_16x16x32_bf16 v[76:79], v[144:147], v[208:211], v[76:79]
	v_mfma_f32_16x16x32_bf16 v[72:75], v[160:163], v[208:211], v[72:75]
	v_mfma_f32_16x16x32_bf16 v[124:127], v[156:159], v[188:191], v[124:127]
	v_mfma_f32_16x16x32_bf16 v[120:123], v[164:167], v[188:191], v[120:123]
	v_mfma_f32_16x16x32_bf16 v[108:111], v[156:159], v[196:199], v[108:111]
	v_mfma_f32_16x16x32_bf16 v[104:107], v[164:167], v[196:199], v[104:107]
	v_mfma_f32_16x16x32_bf16 v[92:95], v[156:159], v[204:207], v[92:95]
	v_mfma_f32_16x16x32_bf16 v[88:91], v[164:167], v[204:207], v[88:91]
	v_mfma_f32_16x16x32_bf16 v[76:79], v[156:159], v[212:215], v[76:79]
	v_mfma_f32_16x16x32_bf16 v[72:75], v[164:167], v[212:215], v[72:75]
	s_setprio 0
	s_setprio 1
	v_mfma_f32_16x16x32_bf16 v[116:119], v[168:171], v[184:187], v[116:119]
	v_mfma_f32_16x16x32_bf16 v[112:115], v[176:179], v[184:187], v[112:115]
	v_mfma_f32_16x16x32_bf16 v[100:103], v[168:171], v[192:195], v[100:103]
	v_mfma_f32_16x16x32_bf16 v[96:99], v[176:179], v[192:195], v[96:99]
	v_mfma_f32_16x16x32_bf16 v[84:87], v[168:171], v[200:203], v[84:87]
	v_mfma_f32_16x16x32_bf16 v[80:83], v[176:179], v[200:203], v[80:83]
	v_mfma_f32_16x16x32_bf16 v[68:71], v[168:171], v[208:211], v[68:71]
	v_mfma_f32_16x16x32_bf16 v[64:67], v[176:179], v[208:211], v[64:67]
	v_mfma_f32_16x16x32_bf16 v[116:119], v[172:175], v[188:191], v[116:119]
	v_mfma_f32_16x16x32_bf16 v[112:115], v[180:183], v[188:191], v[112:115]
	v_mfma_f32_16x16x32_bf16 v[100:103], v[172:175], v[196:199], v[100:103]
	v_mfma_f32_16x16x32_bf16 v[96:99], v[180:183], v[196:199], v[96:99]
	v_mfma_f32_16x16x32_bf16 v[84:87], v[172:175], v[204:207], v[84:87]
	v_mfma_f32_16x16x32_bf16 v[80:83], v[180:183], v[204:207], v[80:83]
	v_mfma_f32_16x16x32_bf16 v[68:71], v[172:175], v[212:215], v[68:71]
	v_mfma_f32_16x16x32_bf16 v[64:67], v[180:183], v[212:215], v[64:67]
	s_setprio 0
	s_barrier
	s_add_i32 s34, s57, s40
	v_lshl_add_u64 v[148:149], v[148:149], 0, s[8:9]
	s_mov_b32 m0, s34
	ds_read_b128 v[184:187], v155 offset:49152
	ds_read_b128 v[188:191], v155 offset:50176
	ds_read_b128 v[192:195], v155 offset:51200
	ds_read_b128 v[196:199], v155 offset:52224
	ds_read_b128 v[200:203], v155 offset:53248
	ds_read_b128 v[204:207], v155 offset:54272
	ds_read_b128 v[208:211], v155 offset:55296
	ds_read_b128 v[212:215], v155 offset:56320
	global_load_lds_dwordx4 v[148:149], off
	s_add_i32 m0, s34, 0x2000
	s_add_u32 s30, s30, 0xb0080
	v_lshl_add_u64 v[148:149], v[216:217], 0, s[8:9]
	s_addc_u32 s31, s31, 0
	s_add_i32 s34, s58, s40
	global_load_lds_dwordx4 v[148:149], off
	v_lshl_add_u64 v[148:149], s[30:31], 0, v[132:133]
	s_mov_b32 m0, s34
	s_nop 0
	global_load_lds_dwordx4 v[148:149], off
	v_lshl_add_u64 v[148:149], s[30:31], 0, v[136:137]
	s_add_i32 m0, s34, 0x2000
	s_nop 0
	global_load_lds_dwordx4 v[148:149], off
	v_lshl_add_u64 v[148:149], v[218:219], 0, s[8:9]
	s_mov_b32 m0, s46
	s_nop 0
	global_load_lds_dwordx4 v[148:149], off
	v_lshl_add_u64 v[148:149], v[220:221], 0, s[8:9]
	s_mov_b32 m0, s47
	s_nop 0
	global_load_lds_dwordx4 v[148:149], off
	s_waitcnt vmcnt(8)
	s_waitcnt lgkmcnt(0)
	s_barrier
	s_setprio 1
	s_waitcnt lgkmcnt(0)
	v_mfma_f32_16x16x32_bf16 v[60:63], v[144:147], v[184:187], v[60:63]
	v_mfma_f32_16x16x32_bf16 v[56:59], v[160:163], v[184:187], v[56:59]
	v_mfma_f32_16x16x32_bf16 v[44:47], v[144:147], v[192:195], v[44:47]
	v_mfma_f32_16x16x32_bf16 v[40:43], v[160:163], v[192:195], v[40:43]
	v_mfma_f32_16x16x32_bf16 v[28:31], v[144:147], v[200:203], v[28:31]
	v_mfma_f32_16x16x32_bf16 v[24:27], v[160:163], v[200:203], v[24:27]
	v_mfma_f32_16x16x32_bf16 v[12:15], v[144:147], v[208:211], v[12:15]
	v_mfma_f32_16x16x32_bf16 v[8:11], v[160:163], v[208:211], v[8:11]
	v_mfma_f32_16x16x32_bf16 v[60:63], v[156:159], v[188:191], v[60:63]
	v_mfma_f32_16x16x32_bf16 v[56:59], v[164:167], v[188:191], v[56:59]
	v_mfma_f32_16x16x32_bf16 v[44:47], v[156:159], v[196:199], v[44:47]
	v_mfma_f32_16x16x32_bf16 v[40:43], v[164:167], v[196:199], v[40:43]
	v_mfma_f32_16x16x32_bf16 v[28:31], v[156:159], v[204:207], v[28:31]
	v_mfma_f32_16x16x32_bf16 v[24:27], v[164:167], v[204:207], v[24:27]
	v_mfma_f32_16x16x32_bf16 v[12:15], v[156:159], v[212:215], v[12:15]
	v_mfma_f32_16x16x32_bf16 v[8:11], v[164:167], v[212:215], v[8:11]
	s_setprio 0
	s_setprio 1
	v_mfma_f32_16x16x32_bf16 v[52:55], v[168:171], v[184:187], v[52:55]
	v_mfma_f32_16x16x32_bf16 v[48:51], v[176:179], v[184:187], v[48:51]
	v_mfma_f32_16x16x32_bf16 v[36:39], v[168:171], v[192:195], v[36:39]
	v_mfma_f32_16x16x32_bf16 v[32:35], v[176:179], v[192:195], v[32:35]
	v_mfma_f32_16x16x32_bf16 v[20:23], v[168:171], v[200:203], v[20:23]
	v_mfma_f32_16x16x32_bf16 v[16:19], v[176:179], v[200:203], v[16:19]
	v_mfma_f32_16x16x32_bf16 v[4:7], v[168:171], v[208:211], v[4:7]
	v_mfma_f32_16x16x32_bf16 v[0:3], v[176:179], v[208:211], v[0:3]
	v_mfma_f32_16x16x32_bf16 v[52:55], v[172:175], v[188:191], v[52:55]
	v_mfma_f32_16x16x32_bf16 v[48:51], v[180:183], v[188:191], v[48:51]
	v_mfma_f32_16x16x32_bf16 v[36:39], v[172:175], v[196:199], v[36:39]
	v_mfma_f32_16x16x32_bf16 v[32:35], v[180:183], v[196:199], v[32:35]
	v_mfma_f32_16x16x32_bf16 v[20:23], v[172:175], v[204:207], v[20:23]
	v_mfma_f32_16x16x32_bf16 v[16:19], v[180:183], v[204:207], v[16:19]
	v_mfma_f32_16x16x32_bf16 v[4:7], v[172:175], v[212:215], v[4:7]
	v_mfma_f32_16x16x32_bf16 v[0:3], v[180:183], v[212:215], v[0:3]
	s_setprio 0
	s_barrier
	s_add_i32 s56, s56, 2
	s_add_u32 s28, s28, 0x100
	s_addc_u32 s29, s29, 0
	s_add_u32 s54, s54, 0x100
	s_addc_u32 s55, s55, 0
